# s_setprio flips deleted plus .p2align 6 in front of the 20 inner K-loop head labels
# speedup vs baseline: 1.0038x; 1.0025x over previous
.LBB0_391:
	s_ashr_i32 s9, s8, 31
	s_lshl_b64 s[20:21], s[8:9], 20
	s_add_u32 s44, s26, s20
	s_addc_u32 s45, s27, s21
	s_ashr_i32 s37, s36, 31
	s_lshl_b64 s[20:21], s[36:37], 20
	s_add_u32 s46, s17, s20
	s_addc_u32 s47, s24, s21
	s_add_u32 s52, s50, 0x180
	s_addc_u32 s53, s51, 0
	s_waitcnt lgkmcnt(0)
	s_and_b64 s[20:21], s[42:43], exec
	s_cselect_b32 s9, s47, s49
	s_cselect_b32 s12, s46, s48
	s_cselect_b32 s20, s45, s51
	s_cselect_b32 s21, s44, s50
	s_add_u32 s54, s48, 0x180
	s_addc_u32 s55, s49, 0
	s_barrier
	s_waitcnt lgkmcnt(0)
	v_mfma_f32_16x16x32_bf16 v[120:123], v[16:19], v[112:115], 0
	v_mfma_f32_16x16x32_bf16 v[148:151], v[20:23], v[116:119], v[120:123]
	v_mfma_f32_16x16x32_bf16 v[120:123], v[24:27], v[112:115], 0
	v_mfma_f32_16x16x32_bf16 v[152:155], v[28:31], v[116:119], v[120:123]
	v_mfma_f32_16x16x32_bf16 v[120:123], v[16:19], v[104:107], 0
	v_mfma_f32_16x16x32_bf16 v[156:159], v[20:23], v[108:111], v[120:123]
	v_mfma_f32_16x16x32_bf16 v[120:123], v[24:27], v[104:107], 0
	v_mfma_f32_16x16x32_bf16 v[160:163], v[28:31], v[108:111], v[120:123]
	v_mfma_f32_16x16x32_bf16 v[120:123], v[16:19], v[96:99], 0
	v_mfma_f32_16x16x32_bf16 v[16:19], v[16:19], v[64:67], 0
	v_mfma_f32_16x16x32_bf16 v[164:167], v[20:23], v[100:103], v[120:123]
	v_mfma_f32_16x16x32_bf16 v[120:123], v[24:27], v[96:99], 0
	v_mfma_f32_16x16x32_bf16 v[20:23], v[20:23], v[72:75], v[16:19]
	v_mfma_f32_16x16x32_bf16 v[16:19], v[24:27], v[64:67], 0
	v_mfma_f32_16x16x32_bf16 v[168:171], v[28:31], v[100:103], v[120:123]
	v_mfma_f32_16x16x32_bf16 v[28:31], v[28:31], v[72:75], v[16:19]
	v_mfma_f32_16x16x32_bf16 v[16:19], v[0:3], v[112:115], 0
	v_mfma_f32_16x16x32_bf16 v[172:175], v[4:7], v[116:119], v[16:19]
	v_mfma_f32_16x16x32_bf16 v[16:19], v[8:11], v[112:115], 0
	v_mfma_f32_16x16x32_bf16 v[176:179], v[12:15], v[116:119], v[16:19]
	v_mfma_f32_16x16x32_bf16 v[16:19], v[0:3], v[104:107], 0
	v_mfma_f32_16x16x32_bf16 v[180:183], v[4:7], v[108:111], v[16:19]
	v_mfma_f32_16x16x32_bf16 v[16:19], v[8:11], v[104:107], 0
	v_mfma_f32_16x16x32_bf16 v[184:187], v[12:15], v[108:111], v[16:19]
	v_mfma_f32_16x16x32_bf16 v[16:19], v[0:3], v[96:99], 0
	v_mfma_f32_16x16x32_bf16 v[0:3], v[0:3], v[64:67], 0
	v_mfma_f32_16x16x32_bf16 v[188:191], v[4:7], v[100:103], v[16:19]
	v_mfma_f32_16x16x32_bf16 v[16:19], v[8:11], v[96:99], 0
	v_mfma_f32_16x16x32_bf16 v[4:7], v[4:7], v[72:75], v[0:3]
	v_mfma_f32_16x16x32_bf16 v[0:3], v[8:11], v[64:67], 0
	v_mfma_f32_16x16x32_bf16 v[192:195], v[12:15], v[100:103], v[16:19]
	v_mfma_f32_16x16x32_bf16 v[196:199], v[12:15], v[72:75], v[0:3]
	s_barrier
	v_add_u32_e32 v146, s71, v142
	v_add_u32_e32 v147, s72, v142
	s_nop 1
	ds_read_b128 v[0:3], v146
	ds_read_b128 v[8:11], v146 offset:1024
	ds_read_b128 v[12:15], v146 offset:2048
	ds_read_b128 v[200:203], v146 offset:3072
	ds_read_b128 v[204:207], v147
	ds_read_b128 v[208:211], v147 offset:1024
	ds_read_b128 v[212:215], v147 offset:2048
	ds_read_b128 v[216:219], v147 offset:3072
	s_add_u32 s56, s50, 0x80100
	s_addc_u32 s57, s51, 0
	s_mov_b32 m0, s63
	ds_read_b128 v[16:19], v145 offset:32768
	ds_read_b128 v[24:27], v145 offset:33792
	ds_read_b128 v[100:103], v145 offset:34816
	ds_read_b128 v[220:223], v145 offset:35840
	ds_read_b128 v[224:227], v145 offset:36864
	ds_read_b128 v[228:231], v145 offset:37888
	ds_read_b128 v[232:235], v145 offset:38912
	ds_read_b128 v[236:239], v145 offset:39936
	s_nop 0
	global_load_lds_dwordx4 v138, s[56:57]
	s_mov_b32 m0, s64
	s_nop 0
	global_load_lds_dwordx4 v140, s[56:57]
	s_waitcnt vmcnt(8)
	s_waitcnt lgkmcnt(0)
	s_barrier
	s_waitcnt lgkmcnt(0)
	v_mfma_f32_16x16x32_bf16 v[32:35], v[0:3], v[16:19], v[32:35]
	v_mfma_f32_16x16x32_bf16 v[120:123], v[8:11], v[24:27], v[32:35]
	v_mfma_f32_16x16x32_bf16 v[32:35], v[12:15], v[16:19], v[36:39]
	v_mfma_f32_16x16x32_bf16 v[112:115], v[200:203], v[24:27], v[32:35]
	v_mfma_f32_16x16x32_bf16 v[32:35], v[0:3], v[100:103], v[40:43]
	v_mfma_f32_16x16x32_bf16 v[104:107], v[8:11], v[220:223], v[32:35]
	v_mfma_f32_16x16x32_bf16 v[32:35], v[12:15], v[100:103], v[44:47]
	v_mfma_f32_16x16x32_bf16 v[96:99], v[200:203], v[220:223], v[32:35]
	v_mfma_f32_16x16x32_bf16 v[32:35], v[0:3], v[224:227], v[48:51]
	v_mfma_f32_16x16x32_bf16 v[72:75], v[8:11], v[228:231], v[32:35]
	v_mfma_f32_16x16x32_bf16 v[32:35], v[12:15], v[224:227], v[52:55]
	v_mfma_f32_16x16x32_bf16 v[64:67], v[200:203], v[228:231], v[32:35]
	v_mfma_f32_16x16x32_bf16 v[32:35], v[0:3], v[232:235], v[56:59]
	v_mfma_f32_16x16x32_bf16 v[40:43], v[8:11], v[236:239], v[32:35]
	v_mfma_f32_16x16x32_bf16 v[32:35], v[12:15], v[232:235], v[60:63]
	v_mfma_f32_16x16x32_bf16 v[32:35], v[200:203], v[236:239], v[32:35]
	v_mfma_f32_16x16x32_bf16 v[36:39], v[204:207], v[16:19], v[68:71]
	v_mfma_f32_16x16x32_bf16 v[16:19], v[212:215], v[16:19], v[76:79]
	v_mfma_f32_16x16x32_bf16 v[116:119], v[216:219], v[24:27], v[16:19]
	v_mfma_f32_16x16x32_bf16 v[16:19], v[204:207], v[100:103], v[80:83]
	v_mfma_f32_16x16x32_bf16 v[108:111], v[208:211], v[220:223], v[16:19]
	v_mfma_f32_16x16x32_bf16 v[16:19], v[212:215], v[100:103], v[84:87]
	v_mfma_f32_16x16x32_bf16 v[100:103], v[216:219], v[220:223], v[16:19]
	v_mfma_f32_16x16x32_bf16 v[16:19], v[204:207], v[224:227], v[88:91]
	v_mfma_f32_16x16x32_bf16 v[76:79], v[208:211], v[228:231], v[16:19]
	v_mfma_f32_16x16x32_bf16 v[16:19], v[212:215], v[224:227], v[92:95]
	v_mfma_f32_16x16x32_bf16 v[68:71], v[216:219], v[228:231], v[16:19]
	v_mfma_f32_16x16x32_bf16 v[16:19], v[204:207], v[232:235], v[128:131]
	v_mfma_f32_16x16x32_bf16 v[44:47], v[208:211], v[236:239], v[16:19]
	v_mfma_f32_16x16x32_bf16 v[16:19], v[212:215], v[232:235], v[132:135]
	v_mfma_f32_16x16x32_bf16 v[124:127], v[208:211], v[24:27], v[36:39]
	v_mfma_f32_16x16x32_bf16 v[36:39], v[216:219], v[236:239], v[16:19]
	s_barrier
	s_add_i32 s37, s71, s25
	s_mov_b32 m0, s37
	s_add_i32 s39, s37, 0x2000
	ds_read_b128 v[52:55], v145 offset:49152
	ds_read_b128 v[60:63], v145 offset:50176
	ds_read_b128 v[128:131], v145 offset:51200
	ds_read_b128 v[132:135], v145 offset:52224
	ds_read_b128 v[220:223], v145 offset:53248
	ds_read_b128 v[224:227], v145 offset:54272
	ds_read_b128 v[228:231], v145 offset:55296
	ds_read_b128 v[232:235], v145 offset:56320
	s_nop 0
	global_load_lds_dwordx4 v139, s[54:55]
	s_mov_b32 m0, s39
	s_nop 0
	global_load_lds_dwordx4 v141, s[54:55]
	s_add_u32 s54, s48, 0x80180
	s_addc_u32 s55, s49, 0
	s_add_i32 s75, s72, s25
	s_mov_b32 m0, s75
	s_add_i32 s76, s75, 0x2000
	s_nop 0
	global_load_lds_dwordx4 v139, s[54:55]
	s_mov_b32 m0, s76
	s_nop 0
	global_load_lds_dwordx4 v141, s[54:55]
	s_mov_b32 m0, s65
	s_nop 0
	global_load_lds_dwordx4 v138, s[52:53]
	s_mov_b32 m0, s66
	s_nop 0
	global_load_lds_dwordx4 v140, s[52:53]
	s_waitcnt vmcnt(8)
	s_waitcnt lgkmcnt(0)
	s_barrier
	s_waitcnt lgkmcnt(0)
	v_mfma_f32_16x16x32_bf16 v[16:19], v[0:3], v[52:55], v[148:151]
	v_mfma_f32_16x16x32_bf16 v[92:95], v[8:11], v[60:63], v[16:19]
	v_mfma_f32_16x16x32_bf16 v[16:19], v[12:15], v[52:55], v[152:155]
	v_mfma_f32_16x16x32_bf16 v[84:87], v[200:203], v[60:63], v[16:19]
	v_mfma_f32_16x16x32_bf16 v[16:19], v[0:3], v[128:131], v[156:159]
	v_mfma_f32_16x16x32_bf16 v[56:59], v[8:11], v[132:135], v[16:19]
	v_mfma_f32_16x16x32_bf16 v[16:19], v[12:15], v[128:131], v[160:163]
	v_mfma_f32_16x16x32_bf16 v[48:51], v[200:203], v[132:135], v[16:19]
	v_mfma_f32_16x16x32_bf16 v[16:19], v[0:3], v[220:223], v[164:167]
	v_mfma_f32_16x16x32_bf16 v[0:3], v[0:3], v[228:231], v[20:23]
	v_mfma_f32_16x16x32_bf16 v[24:27], v[8:11], v[224:227], v[16:19]
	v_mfma_f32_16x16x32_bf16 v[16:19], v[12:15], v[220:223], v[168:171]
	v_mfma_f32_16x16x32_bf16 v[8:11], v[8:11], v[232:235], v[0:3]
	v_mfma_f32_16x16x32_bf16 v[0:3], v[12:15], v[228:231], v[28:31]
	v_mfma_f32_16x16x32_bf16 v[16:19], v[200:203], v[224:227], v[16:19]
	v_mfma_f32_16x16x32_bf16 v[0:3], v[200:203], v[232:235], v[0:3]
	v_mfma_f32_16x16x32_bf16 v[12:15], v[204:207], v[52:55], v[172:175]
	v_mfma_f32_16x16x32_bf16 v[88:91], v[208:211], v[60:63], v[12:15]
	v_mfma_f32_16x16x32_bf16 v[12:15], v[212:215], v[52:55], v[176:179]
	v_mfma_f32_16x16x32_bf16 v[80:83], v[216:219], v[60:63], v[12:15]
	v_mfma_f32_16x16x32_bf16 v[12:15], v[204:207], v[128:131], v[180:183]
	v_mfma_f32_16x16x32_bf16 v[60:63], v[208:211], v[132:135], v[12:15]
	v_mfma_f32_16x16x32_bf16 v[12:15], v[212:215], v[128:131], v[184:187]
	v_mfma_f32_16x16x32_bf16 v[52:55], v[216:219], v[132:135], v[12:15]
	v_mfma_f32_16x16x32_bf16 v[12:15], v[204:207], v[220:223], v[188:191]
	v_mfma_f32_16x16x32_bf16 v[28:31], v[208:211], v[224:227], v[12:15]
	v_mfma_f32_16x16x32_bf16 v[12:15], v[212:215], v[220:223], v[192:195]
	v_mfma_f32_16x16x32_bf16 v[4:7], v[204:207], v[228:231], v[4:7]
	v_mfma_f32_16x16x32_bf16 v[20:23], v[216:219], v[224:227], v[12:15]
	v_mfma_f32_16x16x32_bf16 v[12:15], v[208:211], v[232:235], v[4:7]
	v_mfma_f32_16x16x32_bf16 v[4:7], v[212:215], v[228:231], v[196:199]
	v_mfma_f32_16x16x32_bf16 v[4:7], v[216:219], v[232:235], v[4:7]
	s_barrier
	s_add_u32 s56, s50, 0x100
	s_addc_u32 s57, s51, 0
	s_add_u32 s77, s48, 0x200
	s_addc_u32 s78, s49, 0
	s_mov_b32 s79, 0
	.p2align	6

.LBB0_428:
	s_ashr_i32 s7, s6, 31
	s_lshl_b64 s[20:21], s[6:7], 20
	s_add_u32 s42, s14, s20
	s_addc_u32 s43, s15, s21
	s_ashr_i32 s9, s8, 31
	s_lshl_b64 s[20:21], s[8:9], 20
	s_add_u32 s44, s17, s20
	s_addc_u32 s45, s24, s21
	s_add_u32 s50, s48, 0x180
	s_addc_u32 s51, s49, 0
	s_waitcnt lgkmcnt(0)
	s_and_b64 s[20:21], s[40:41], exec
	s_cselect_b32 s9, s45, s47
	s_cselect_b32 s12, s44, s46
	s_cselect_b32 s20, s43, s49
	s_cselect_b32 s21, s42, s48
	s_add_u32 s52, s46, 0x180
	s_addc_u32 s53, s47, 0
	s_barrier
	s_waitcnt lgkmcnt(0)
	v_mfma_f32_16x16x32_bf16 v[116:119], v[16:19], v[108:111], 0
	v_mfma_f32_16x16x32_bf16 v[156:159], v[20:23], v[112:115], v[116:119]
	v_mfma_f32_16x16x32_bf16 v[116:119], v[24:27], v[108:111], 0
	v_mfma_f32_16x16x32_bf16 v[160:163], v[28:31], v[112:115], v[116:119]
	v_mfma_f32_16x16x32_bf16 v[116:119], v[16:19], v[100:103], 0
	v_mfma_f32_16x16x32_bf16 v[164:167], v[20:23], v[104:107], v[116:119]
	v_mfma_f32_16x16x32_bf16 v[116:119], v[24:27], v[100:103], 0
	v_mfma_f32_16x16x32_bf16 v[168:171], v[28:31], v[104:107], v[116:119]
	v_mfma_f32_16x16x32_bf16 v[116:119], v[16:19], v[92:95], 0
	v_mfma_f32_16x16x32_bf16 v[16:19], v[16:19], v[60:63], 0
	v_mfma_f32_16x16x32_bf16 v[172:175], v[20:23], v[96:99], v[116:119]
	v_mfma_f32_16x16x32_bf16 v[16:19], v[20:23], v[88:91], v[16:19]
	v_mfma_f32_16x16x32_bf16 v[20:23], v[24:27], v[60:63], 0
	v_mfma_f32_16x16x32_bf16 v[116:119], v[24:27], v[92:95], 0
	v_mfma_f32_16x16x32_bf16 v[20:23], v[28:31], v[88:91], v[20:23]
	v_mfma_f32_16x16x32_bf16 v[176:179], v[28:31], v[96:99], v[116:119]
	v_mfma_f32_16x16x32_bf16 v[24:27], v[0:3], v[108:111], 0
	v_mfma_f32_16x16x32_bf16 v[180:183], v[4:7], v[112:115], v[24:27]
	v_mfma_f32_16x16x32_bf16 v[24:27], v[8:11], v[108:111], 0
	v_mfma_f32_16x16x32_bf16 v[184:187], v[12:15], v[112:115], v[24:27]
	v_mfma_f32_16x16x32_bf16 v[24:27], v[0:3], v[100:103], 0
	v_mfma_f32_16x16x32_bf16 v[188:191], v[4:7], v[104:107], v[24:27]
	v_mfma_f32_16x16x32_bf16 v[24:27], v[8:11], v[100:103], 0
	v_mfma_f32_16x16x32_bf16 v[192:195], v[12:15], v[104:107], v[24:27]
	v_mfma_f32_16x16x32_bf16 v[24:27], v[0:3], v[92:95], 0
	v_mfma_f32_16x16x32_bf16 v[0:3], v[0:3], v[60:63], 0
	v_mfma_f32_16x16x32_bf16 v[196:199], v[4:7], v[96:99], v[24:27]
	v_mfma_f32_16x16x32_bf16 v[24:27], v[8:11], v[92:95], 0
	v_mfma_f32_16x16x32_bf16 v[0:3], v[4:7], v[88:91], v[0:3]
	v_mfma_f32_16x16x32_bf16 v[4:7], v[8:11], v[60:63], 0
	v_mfma_f32_16x16x32_bf16 v[200:203], v[12:15], v[96:99], v[24:27]
	v_mfma_f32_16x16x32_bf16 v[204:207], v[12:15], v[88:91], v[4:7]
	s_barrier
	v_add_u32_e32 v153, s69, v147
	v_add_u32_e32 v154, s70, v147
	s_nop 1
	ds_read_b128 v[4:7], v153
	ds_read_b128 v[8:11], v153 offset:1024
	ds_read_b128 v[208:211], v153 offset:2048
	ds_read_b128 v[212:215], v153 offset:3072
	ds_read_b128 v[216:219], v154
	ds_read_b128 v[220:223], v154 offset:1024
	ds_read_b128 v[224:227], v154 offset:2048
	ds_read_b128 v[228:231], v154 offset:3072
	s_add_u32 s54, s48, 0x80100
	s_addc_u32 s55, s49, 0
	s_mov_b32 m0, s60
	ds_read_b128 v[12:15], v150 offset:32768
	ds_read_b128 v[24:27], v150 offset:33792
	ds_read_b128 v[28:31], v150 offset:34816
	ds_read_b128 v[96:99], v150 offset:35840
	ds_read_b128 v[232:235], v150 offset:36864
	ds_read_b128 v[236:239], v150 offset:37888
	ds_read_b128 v[240:243], v150 offset:38912
	ds_read_b128 v[244:247], v150 offset:39936
	s_nop 0
	global_load_lds_dwordx4 v143, s[54:55]
	s_mov_b32 m0, s61
	s_nop 0
	global_load_lds_dwordx4 v145, s[54:55]
	s_waitcnt vmcnt(8)
	s_waitcnt lgkmcnt(0)
	s_barrier
	s_waitcnt lgkmcnt(0)
	v_mfma_f32_16x16x32_bf16 v[32:35], v[4:7], v[12:15], v[32:35]
	v_mfma_f32_16x16x32_bf16 v[124:127], v[8:11], v[24:27], v[32:35]
	v_mfma_f32_16x16x32_bf16 v[32:35], v[208:211], v[12:15], v[36:39]
	v_mfma_f32_16x16x32_bf16 v[120:123], v[212:215], v[24:27], v[32:35]
	v_mfma_f32_16x16x32_bf16 v[32:35], v[4:7], v[28:31], v[40:43]
	v_mfma_f32_16x16x32_bf16 v[108:111], v[8:11], v[96:99], v[32:35]
	v_mfma_f32_16x16x32_bf16 v[32:35], v[208:211], v[28:31], v[44:47]
	v_mfma_f32_16x16x32_bf16 v[104:107], v[212:215], v[96:99], v[32:35]
	v_mfma_f32_16x16x32_bf16 v[32:35], v[4:7], v[232:235], v[48:51]
	v_mfma_f32_16x16x32_bf16 v[92:95], v[8:11], v[236:239], v[32:35]
	v_mfma_f32_16x16x32_bf16 v[32:35], v[208:211], v[232:235], v[52:55]
	v_mfma_f32_16x16x32_bf16 v[88:91], v[212:215], v[236:239], v[32:35]
	v_mfma_f32_16x16x32_bf16 v[32:35], v[4:7], v[240:243], v[56:59]
	v_mfma_f32_16x16x32_bf16 v[60:63], v[8:11], v[244:247], v[32:35]
	v_mfma_f32_16x16x32_bf16 v[32:35], v[208:211], v[240:243], v[64:67]
	v_mfma_f32_16x16x32_bf16 v[56:59], v[212:215], v[244:247], v[32:35]
	v_mfma_f32_16x16x32_bf16 v[32:35], v[216:219], v[12:15], v[68:71]
	v_mfma_f32_16x16x32_bf16 v[12:15], v[224:227], v[12:15], v[72:75]
	v_mfma_f32_16x16x32_bf16 v[112:115], v[228:231], v[24:27], v[12:15]
	v_mfma_f32_16x16x32_bf16 v[12:15], v[216:219], v[28:31], v[76:79]
	v_mfma_f32_16x16x32_bf16 v[100:103], v[220:223], v[96:99], v[12:15]
	v_mfma_f32_16x16x32_bf16 v[12:15], v[224:227], v[28:31], v[80:83]
	v_mfma_f32_16x16x32_bf16 v[96:99], v[228:231], v[96:99], v[12:15]
	v_mfma_f32_16x16x32_bf16 v[12:15], v[216:219], v[232:235], v[84:87]
	v_mfma_f32_16x16x32_bf16 v[84:87], v[220:223], v[236:239], v[12:15]
	v_mfma_f32_16x16x32_bf16 v[12:15], v[224:227], v[232:235], v[128:131]
	v_mfma_f32_16x16x32_bf16 v[80:83], v[228:231], v[236:239], v[12:15]
	v_mfma_f32_16x16x32_bf16 v[12:15], v[216:219], v[240:243], v[132:135]
	v_mfma_f32_16x16x32_bf16 v[52:55], v[220:223], v[244:247], v[12:15]
	v_mfma_f32_16x16x32_bf16 v[12:15], v[224:227], v[240:243], v[136:139]
	v_mfma_f32_16x16x32_bf16 v[116:119], v[220:223], v[24:27], v[32:35]
	v_mfma_f32_16x16x32_bf16 v[48:51], v[228:231], v[244:247], v[12:15]
	s_barrier
	s_add_i32 s37, s69, s25
	s_mov_b32 m0, s37
	s_add_i32 s74, s37, 0x2000
	ds_read_b128 v[32:35], v150 offset:49152
	ds_read_b128 v[36:39], v150 offset:50176
	ds_read_b128 v[128:131], v150 offset:51200
	ds_read_b128 v[132:135], v150 offset:52224
	ds_read_b128 v[136:139], v150 offset:53248
	ds_read_b128 v[232:235], v150 offset:54272
	ds_read_b128 v[236:239], v150 offset:55296
	ds_read_b128 v[240:243], v150 offset:56320
	s_nop 0
	global_load_lds_dwordx4 v144, s[52:53]
	s_mov_b32 m0, s74
	s_nop 0
	global_load_lds_dwordx4 v146, s[52:53]
	s_add_u32 s52, s46, 0x80180
	s_addc_u32 s53, s47, 0
	s_add_i32 s75, s70, s25
	s_mov_b32 m0, s75
	s_add_i32 s76, s75, 0x2000
	s_nop 0
	global_load_lds_dwordx4 v144, s[52:53]
	s_mov_b32 m0, s76
	s_nop 0
	global_load_lds_dwordx4 v146, s[52:53]
	s_mov_b32 m0, s62
	s_nop 0
	global_load_lds_dwordx4 v143, s[50:51]
	s_mov_b32 m0, s63
	s_nop 0
	global_load_lds_dwordx4 v145, s[50:51]
	s_waitcnt vmcnt(8)
	s_waitcnt lgkmcnt(0)
	s_barrier
	s_waitcnt lgkmcnt(0)
	v_mfma_f32_16x16x32_bf16 v[12:15], v[4:7], v[32:35], v[156:159]
	v_mfma_f32_16x16x32_bf16 v[76:79], v[8:11], v[36:39], v[12:15]
	v_mfma_f32_16x16x32_bf16 v[12:15], v[208:211], v[32:35], v[160:163]
	v_mfma_f32_16x16x32_bf16 v[72:75], v[212:215], v[36:39], v[12:15]
	v_mfma_f32_16x16x32_bf16 v[12:15], v[4:7], v[128:131], v[164:167]
	v_mfma_f32_16x16x32_bf16 v[44:47], v[8:11], v[132:135], v[12:15]
	v_mfma_f32_16x16x32_bf16 v[12:15], v[208:211], v[128:131], v[168:171]
	v_mfma_f32_16x16x32_bf16 v[40:43], v[212:215], v[132:135], v[12:15]
	v_mfma_f32_16x16x32_bf16 v[12:15], v[4:7], v[136:139], v[172:175]
	v_mfma_f32_16x16x32_bf16 v[28:31], v[8:11], v[232:235], v[12:15]
	v_mfma_f32_16x16x32_bf16 v[12:15], v[208:211], v[136:139], v[176:179]
	v_mfma_f32_16x16x32_bf16 v[4:7], v[4:7], v[236:239], v[16:19]
	v_mfma_f32_16x16x32_bf16 v[24:27], v[212:215], v[232:235], v[12:15]
	v_mfma_f32_16x16x32_bf16 v[12:15], v[8:11], v[240:243], v[4:7]
	v_mfma_f32_16x16x32_bf16 v[4:7], v[208:211], v[236:239], v[20:23]
	v_mfma_f32_16x16x32_bf16 v[8:11], v[212:215], v[240:243], v[4:7]
	v_mfma_f32_16x16x32_bf16 v[4:7], v[216:219], v[32:35], v[180:183]
	v_mfma_f32_16x16x32_bf16 v[68:71], v[220:223], v[36:39], v[4:7]
	v_mfma_f32_16x16x32_bf16 v[4:7], v[224:227], v[32:35], v[184:187]
	v_mfma_f32_16x16x32_bf16 v[64:67], v[228:231], v[36:39], v[4:7]
	v_mfma_f32_16x16x32_bf16 v[4:7], v[216:219], v[128:131], v[188:191]
	v_mfma_f32_16x16x32_bf16 v[36:39], v[220:223], v[132:135], v[4:7]
	v_mfma_f32_16x16x32_bf16 v[4:7], v[224:227], v[128:131], v[192:195]
	v_mfma_f32_16x16x32_bf16 v[32:35], v[228:231], v[132:135], v[4:7]
	v_mfma_f32_16x16x32_bf16 v[4:7], v[216:219], v[136:139], v[196:199]
	v_mfma_f32_16x16x32_bf16 v[20:23], v[220:223], v[232:235], v[4:7]
	v_mfma_f32_16x16x32_bf16 v[4:7], v[224:227], v[136:139], v[200:203]
	v_mfma_f32_16x16x32_bf16 v[0:3], v[216:219], v[236:239], v[0:3]
	v_mfma_f32_16x16x32_bf16 v[16:19], v[228:231], v[232:235], v[4:7]
	v_mfma_f32_16x16x32_bf16 v[4:7], v[220:223], v[240:243], v[0:3]
	v_mfma_f32_16x16x32_bf16 v[0:3], v[224:227], v[236:239], v[204:207]
	v_mfma_f32_16x16x32_bf16 v[0:3], v[228:231], v[240:243], v[0:3]
	s_barrier
	s_add_u32 s54, s48, 0x100
	s_addc_u32 s55, s49, 0
	s_add_u32 s77, s46, 0x200
	s_addc_u32 s78, s47, 0
	s_mov_b32 s79, 0
	.p2align	6

.LBB0_691:
	s_ashr_i32 s41, s40, 31
	s_lshl_b64 s[20:21], s[40:41], 20
	s_add_u32 s46, s13, s20
	s_addc_u32 s47, s82, s21
	s_and_b64 s[20:21], s[44:45], exec
	s_cselect_b32 s3, s47, s53
	s_cselect_b32 s5, s46, s52
	s_ashr_i32 s43, s42, 31
	s_lshl_b64 s[20:21], s[42:43], 20
	s_add_u32 s48, s24, s20
	s_addc_u32 s49, s25, s21
	s_and_b64 s[20:21], s[44:45], exec
	s_cselect_b32 s12, s49, s51
	s_cselect_b32 s20, s48, s50
	s_add_u32 s54, s52, 0x180
	s_waitcnt lgkmcnt(0)
	s_addc_u32 s55, s53, 0
	s_add_u32 s56, s50, 0x180
	s_addc_u32 s57, s51, 0
	s_barrier
	s_waitcnt lgkmcnt(0)
	v_mfma_f32_16x16x32_bf16 v[128:131], v[16:19], v[116:119], 0
	v_mfma_f32_16x16x32_bf16 v[134:137], v[20:23], v[124:127], v[128:131]
	v_mfma_f32_16x16x32_bf16 v[128:131], v[24:27], v[116:119], 0
	v_mfma_f32_16x16x32_bf16 v[156:159], v[28:31], v[124:127], v[128:131]
	v_mfma_f32_16x16x32_bf16 v[128:131], v[16:19], v[104:107], 0
	v_mfma_f32_16x16x32_bf16 v[160:163], v[20:23], v[112:115], v[128:131]
	v_mfma_f32_16x16x32_bf16 v[128:131], v[24:27], v[104:107], 0
	v_mfma_f32_16x16x32_bf16 v[164:167], v[28:31], v[112:115], v[128:131]
	v_mfma_f32_16x16x32_bf16 v[128:131], v[16:19], v[96:99], 0
	v_mfma_f32_16x16x32_bf16 v[16:19], v[16:19], v[76:79], 0
	v_mfma_f32_16x16x32_bf16 v[168:171], v[20:23], v[100:103], v[128:131]
	v_mfma_f32_16x16x32_bf16 v[16:19], v[20:23], v[80:83], v[16:19]
	v_mfma_f32_16x16x32_bf16 v[20:23], v[24:27], v[76:79], 0
	v_mfma_f32_16x16x32_bf16 v[128:131], v[24:27], v[96:99], 0
	v_mfma_f32_16x16x32_bf16 v[20:23], v[28:31], v[80:83], v[20:23]
	v_mfma_f32_16x16x32_bf16 v[172:175], v[28:31], v[100:103], v[128:131]
	v_mfma_f32_16x16x32_bf16 v[24:27], v[0:3], v[116:119], 0
	v_mfma_f32_16x16x32_bf16 v[176:179], v[4:7], v[124:127], v[24:27]
	v_mfma_f32_16x16x32_bf16 v[24:27], v[8:11], v[116:119], 0
	v_mfma_f32_16x16x32_bf16 v[180:183], v[12:15], v[124:127], v[24:27]
	v_mfma_f32_16x16x32_bf16 v[24:27], v[0:3], v[104:107], 0
	v_mfma_f32_16x16x32_bf16 v[186:189], v[4:7], v[112:115], v[24:27]
	v_mfma_f32_16x16x32_bf16 v[24:27], v[8:11], v[104:107], 0
	v_mfma_f32_16x16x32_bf16 v[190:193], v[12:15], v[112:115], v[24:27]
	v_mfma_f32_16x16x32_bf16 v[24:27], v[0:3], v[96:99], 0
	v_mfma_f32_16x16x32_bf16 v[0:3], v[0:3], v[76:79], 0
	v_mfma_f32_16x16x32_bf16 v[194:197], v[4:7], v[100:103], v[24:27]
	v_mfma_f32_16x16x32_bf16 v[24:27], v[8:11], v[96:99], 0
	v_mfma_f32_16x16x32_bf16 v[0:3], v[4:7], v[80:83], v[0:3]
	v_mfma_f32_16x16x32_bf16 v[4:7], v[8:11], v[76:79], 0
	v_mfma_f32_16x16x32_bf16 v[198:201], v[12:15], v[100:103], v[24:27]
	v_mfma_f32_16x16x32_bf16 v[212:215], v[12:15], v[80:83], v[4:7]
	s_barrier
	v_add_u32_e32 v132, s72, v206
	v_add_u32_e32 v133, s73, v206
	s_nop 1
	ds_read_b128 v[4:7], v132
	ds_read_b128 v[8:11], v132 offset:1024
	ds_read_b128 v[216:219], v132 offset:2048
	ds_read_b128 v[220:223], v132 offset:3072
	ds_read_b128 v[224:227], v133
	ds_read_b128 v[228:231], v133 offset:1024
	ds_read_b128 v[232:235], v133 offset:2048
	ds_read_b128 v[236:239], v133 offset:3072
	s_add_u32 s76, s52, 0x80100
	s_addc_u32 s77, s53, 0
	s_mov_b32 m0, s63
	ds_read_b128 v[12:15], v209 offset:32768
	ds_read_b128 v[24:27], v209 offset:33792
	ds_read_b128 v[28:31], v209 offset:34816
	ds_read_b128 v[96:99], v209 offset:35840
	ds_read_b128 v[240:243], v209 offset:36864
	ds_read_b128 v[244:247], v209 offset:37888
	ds_read_b128 v[248:251], v209 offset:38912
	ds_read_b128 v[32:35], v209 offset:39936
	s_nop 0
	global_load_lds_dwordx4 v202, s[76:77]
	s_mov_b32 m0, s64
	s_nop 0
	global_load_lds_dwordx4 v204, s[76:77]
	s_waitcnt vmcnt(8)
	s_waitcnt lgkmcnt(0)
	s_barrier
	s_waitcnt lgkmcnt(0)
	v_mfma_f32_16x16x32_bf16 v[36:39], v[216:219], v[12:15], v[36:39]
	v_mfma_f32_16x16x32_bf16 v[148:151], v[220:223], v[24:27], v[36:39]
	v_mfma_f32_16x16x32_bf16 v[36:39], v[4:7], v[28:31], v[40:43]
	v_mfma_f32_16x16x32_bf16 v[128:131], v[8:11], v[96:99], v[36:39]
	v_mfma_f32_16x16x32_bf16 v[36:39], v[216:219], v[28:31], v[44:47]
	v_mfma_f32_16x16x32_bf16 v[124:127], v[220:223], v[96:99], v[36:39]
	v_mfma_f32_16x16x32_bf16 v[36:39], v[4:7], v[240:243], v[48:51]
	v_mfma_f32_16x16x32_bf16 v[104:107], v[8:11], v[244:247], v[36:39]
	v_mfma_f32_16x16x32_bf16 v[36:39], v[216:219], v[240:243], v[52:55]
	v_mfma_f32_16x16x32_bf16 v[100:103], v[220:223], v[244:247], v[36:39]
	v_mfma_f32_16x16x32_bf16 v[36:39], v[4:7], v[248:251], v[56:59]
	v_mfma_f32_16x16x32_bf16 v[76:79], v[4:7], v[12:15], v[138:141]
	v_mfma_f32_16x16x32_bf16 v[80:83], v[8:11], v[32:35], v[36:39]
	v_mfma_f32_16x16x32_bf16 v[36:39], v[216:219], v[248:251], v[60:63]
	v_mfma_f32_16x16x32_bf16 v[152:155], v[8:11], v[24:27], v[76:79]
	v_mfma_f32_16x16x32_bf16 v[76:79], v[220:223], v[32:35], v[36:39]
	v_mfma_f32_16x16x32_bf16 v[36:39], v[224:227], v[12:15], v[64:67]
	v_mfma_f32_16x16x32_bf16 v[12:15], v[232:235], v[12:15], v[68:71]
	v_mfma_f32_16x16x32_bf16 v[140:143], v[236:239], v[24:27], v[12:15]
	v_mfma_f32_16x16x32_bf16 v[12:15], v[224:227], v[28:31], v[72:75]
	v_mfma_f32_16x16x32_bf16 v[116:119], v[228:231], v[96:99], v[12:15]
	v_mfma_f32_16x16x32_bf16 v[12:15], v[232:235], v[28:31], v[84:87]
	v_mfma_f32_16x16x32_bf16 v[112:115], v[236:239], v[96:99], v[12:15]
	v_mfma_f32_16x16x32_bf16 v[12:15], v[224:227], v[240:243], v[88:91]
	v_mfma_f32_16x16x32_bf16 v[96:99], v[228:231], v[244:247], v[12:15]
	v_mfma_f32_16x16x32_bf16 v[12:15], v[232:235], v[240:243], v[92:95]
	v_mfma_f32_16x16x32_bf16 v[88:91], v[236:239], v[244:247], v[12:15]
	v_mfma_f32_16x16x32_bf16 v[12:15], v[224:227], v[248:251], v[108:111]
	v_mfma_f32_16x16x32_bf16 v[72:75], v[228:231], v[32:35], v[12:15]
	v_mfma_f32_16x16x32_bf16 v[12:15], v[232:235], v[248:251], v[120:123]
	v_mfma_f32_16x16x32_bf16 v[144:147], v[228:231], v[24:27], v[36:39]
	v_mfma_f32_16x16x32_bf16 v[64:67], v[236:239], v[32:35], v[12:15]
	s_barrier
	s_add_i32 s21, s72, s26
	s_mov_b32 m0, s21
	s_add_i32 s41, s21, 0x2000
	ds_read_b128 v[32:35], v209 offset:49152
	ds_read_b128 v[36:39], v209 offset:50176
	ds_read_b128 v[68:71], v209 offset:51200
	ds_read_b128 v[84:87], v209 offset:52224
	ds_read_b128 v[92:95], v209 offset:53248
	ds_read_b128 v[108:111], v209 offset:54272
	ds_read_b128 v[120:123], v209 offset:55296
	ds_read_b128 v[240:243], v209 offset:56320
	s_nop 0
	global_load_lds_dwordx4 v203, s[56:57]
	s_mov_b32 m0, s41
	s_nop 0
	global_load_lds_dwordx4 v205, s[56:57]
	s_add_u32 s56, s50, 0x80180
	s_addc_u32 s57, s51, 0
	s_add_i32 s43, s73, s26
	s_mov_b32 m0, s43
	s_add_i32 s76, s43, 0x2000
	s_nop 0
	global_load_lds_dwordx4 v203, s[56:57]
	s_mov_b32 m0, s76
	s_nop 0
	global_load_lds_dwordx4 v205, s[56:57]
	s_mov_b32 m0, s65
	s_nop 0
	global_load_lds_dwordx4 v202, s[54:55]
	s_mov_b32 m0, s66
	s_nop 0
	global_load_lds_dwordx4 v204, s[54:55]
	s_waitcnt vmcnt(8)
	s_waitcnt lgkmcnt(0)
	s_barrier
	s_waitcnt lgkmcnt(0)
	v_mfma_f32_16x16x32_bf16 v[12:15], v[4:7], v[32:35], v[134:137]
	v_mfma_f32_16x16x32_bf16 v[60:63], v[8:11], v[36:39], v[12:15]
	v_mfma_f32_16x16x32_bf16 v[12:15], v[216:219], v[32:35], v[156:159]
	v_mfma_f32_16x16x32_bf16 v[56:59], v[220:223], v[36:39], v[12:15]
	v_mfma_f32_16x16x32_bf16 v[12:15], v[4:7], v[68:71], v[160:163]
	v_mfma_f32_16x16x32_bf16 v[44:47], v[8:11], v[84:87], v[12:15]
	v_mfma_f32_16x16x32_bf16 v[12:15], v[216:219], v[68:71], v[164:167]
	v_mfma_f32_16x16x32_bf16 v[40:43], v[220:223], v[84:87], v[12:15]
	v_mfma_f32_16x16x32_bf16 v[12:15], v[4:7], v[92:95], v[168:171]
	v_mfma_f32_16x16x32_bf16 v[28:31], v[8:11], v[108:111], v[12:15]
	v_mfma_f32_16x16x32_bf16 v[12:15], v[216:219], v[92:95], v[172:175]
	v_mfma_f32_16x16x32_bf16 v[4:7], v[4:7], v[120:123], v[16:19]
	v_mfma_f32_16x16x32_bf16 v[24:27], v[220:223], v[108:111], v[12:15]
	v_mfma_f32_16x16x32_bf16 v[12:15], v[8:11], v[240:243], v[4:7]
	v_mfma_f32_16x16x32_bf16 v[4:7], v[216:219], v[120:123], v[20:23]
	v_mfma_f32_16x16x32_bf16 v[8:11], v[220:223], v[240:243], v[4:7]
	v_mfma_f32_16x16x32_bf16 v[4:7], v[224:227], v[32:35], v[176:179]
	v_mfma_f32_16x16x32_bf16 v[52:55], v[228:231], v[36:39], v[4:7]
	v_mfma_f32_16x16x32_bf16 v[4:7], v[232:235], v[32:35], v[180:183]
	v_mfma_f32_16x16x32_bf16 v[48:51], v[236:239], v[36:39], v[4:7]
	v_mfma_f32_16x16x32_bf16 v[4:7], v[224:227], v[68:71], v[186:189]
	v_mfma_f32_16x16x32_bf16 v[36:39], v[228:231], v[84:87], v[4:7]
	v_mfma_f32_16x16x32_bf16 v[4:7], v[232:235], v[68:71], v[190:193]
	v_mfma_f32_16x16x32_bf16 v[32:35], v[236:239], v[84:87], v[4:7]
	v_mfma_f32_16x16x32_bf16 v[4:7], v[224:227], v[92:95], v[194:197]
	v_mfma_f32_16x16x32_bf16 v[20:23], v[228:231], v[108:111], v[4:7]
	v_mfma_f32_16x16x32_bf16 v[4:7], v[232:235], v[92:95], v[198:201]
	v_mfma_f32_16x16x32_bf16 v[0:3], v[224:227], v[120:123], v[0:3]
	v_mfma_f32_16x16x32_bf16 v[16:19], v[236:239], v[108:111], v[4:7]
	v_mfma_f32_16x16x32_bf16 v[4:7], v[228:231], v[240:243], v[0:3]
	v_mfma_f32_16x16x32_bf16 v[0:3], v[232:235], v[120:123], v[212:215]
	v_mfma_f32_16x16x32_bf16 v[0:3], v[236:239], v[240:243], v[0:3]
	s_barrier
	s_add_u32 s77, s52, 0x200
	s_addc_u32 s78, s53, 0
	s_add_u32 s79, s50, 0x200
	s_addc_u32 s80, s51, 0
	s_add_u32 s50, s52, 0x80180
	s_addc_u32 s51, s53, 0
	s_mov_b32 s83, 0
	.p2align	6

.LBB0_801:
	s_ashr_i32 s7, s6, 31
	s_lshl_b64 s[20:21], s[6:7], 20
	s_add_u32 s36, s14, s20
	s_addc_u32 s37, s15, s21
	s_ashr_i32 s9, s8, 31
	s_lshl_b64 s[20:21], s[8:9], 20
	s_add_u32 s38, s24, s20
	s_addc_u32 s39, s25, s21
	s_add_u32 s48, s46, 0x180
	s_addc_u32 s49, s47, 0
	s_waitcnt lgkmcnt(0)
	s_and_b64 s[20:21], s[34:35], exec
	s_cselect_b32 s9, s39, s45
	s_cselect_b32 s12, s38, s44
	s_cselect_b32 s20, s37, s47
	s_cselect_b32 s21, s36, s46
	s_add_u32 s50, s44, 0x180
	s_addc_u32 s51, s45, 0
	s_barrier
	s_waitcnt lgkmcnt(0)
	v_mfma_f32_16x16x32_bf16 v[116:119], v[16:19], v[108:111], 0
	v_mfma_f32_16x16x32_bf16 v[154:157], v[20:23], v[112:115], v[116:119]
	v_mfma_f32_16x16x32_bf16 v[116:119], v[24:27], v[108:111], 0
	v_mfma_f32_16x16x32_bf16 v[158:161], v[28:31], v[112:115], v[116:119]
	v_mfma_f32_16x16x32_bf16 v[116:119], v[16:19], v[100:103], 0
	v_mfma_f32_16x16x32_bf16 v[162:165], v[20:23], v[104:107], v[116:119]
	v_mfma_f32_16x16x32_bf16 v[116:119], v[24:27], v[100:103], 0
	v_mfma_f32_16x16x32_bf16 v[166:169], v[28:31], v[104:107], v[116:119]
	v_mfma_f32_16x16x32_bf16 v[116:119], v[16:19], v[88:91], 0
	v_mfma_f32_16x16x32_bf16 v[16:19], v[16:19], v[68:71], 0
	v_mfma_f32_16x16x32_bf16 v[170:173], v[20:23], v[96:99], v[116:119]
	v_mfma_f32_16x16x32_bf16 v[116:119], v[24:27], v[88:91], 0
	v_mfma_f32_16x16x32_bf16 v[20:23], v[20:23], v[80:83], v[16:19]
	v_mfma_f32_16x16x32_bf16 v[16:19], v[24:27], v[68:71], 0
	v_mfma_f32_16x16x32_bf16 v[174:177], v[28:31], v[96:99], v[116:119]
	v_mfma_f32_16x16x32_bf16 v[28:31], v[28:31], v[80:83], v[16:19]
	v_mfma_f32_16x16x32_bf16 v[16:19], v[0:3], v[108:111], 0
	v_mfma_f32_16x16x32_bf16 v[178:181], v[4:7], v[112:115], v[16:19]
	v_mfma_f32_16x16x32_bf16 v[16:19], v[8:11], v[108:111], 0
	v_mfma_f32_16x16x32_bf16 v[182:185], v[12:15], v[112:115], v[16:19]
	v_mfma_f32_16x16x32_bf16 v[16:19], v[0:3], v[100:103], 0
	v_mfma_f32_16x16x32_bf16 v[186:189], v[4:7], v[104:107], v[16:19]
	v_mfma_f32_16x16x32_bf16 v[16:19], v[8:11], v[100:103], 0
	v_mfma_f32_16x16x32_bf16 v[190:193], v[12:15], v[104:107], v[16:19]
	v_mfma_f32_16x16x32_bf16 v[16:19], v[0:3], v[88:91], 0
	v_mfma_f32_16x16x32_bf16 v[0:3], v[0:3], v[68:71], 0
	v_mfma_f32_16x16x32_bf16 v[194:197], v[4:7], v[96:99], v[16:19]
	v_mfma_f32_16x16x32_bf16 v[16:19], v[8:11], v[88:91], 0
	v_mfma_f32_16x16x32_bf16 v[4:7], v[4:7], v[80:83], v[0:3]
	v_mfma_f32_16x16x32_bf16 v[0:3], v[8:11], v[68:71], 0
	v_mfma_f32_16x16x32_bf16 v[198:201], v[12:15], v[96:99], v[16:19]
	v_mfma_f32_16x16x32_bf16 v[202:205], v[12:15], v[80:83], v[0:3]
	s_barrier
	v_add_u32_e32 v152, s67, v147
	v_add_u32_e32 v153, s68, v147
	s_nop 1
	ds_read_b128 v[0:3], v152
	ds_read_b128 v[8:11], v152 offset:1024
	ds_read_b128 v[12:15], v152 offset:2048
	ds_read_b128 v[206:209], v152 offset:3072
	ds_read_b128 v[210:213], v153
	ds_read_b128 v[214:217], v153 offset:1024
	ds_read_b128 v[218:221], v153 offset:2048
	ds_read_b128 v[222:225], v153 offset:3072
	s_add_u32 s52, s46, 0x80100
	s_addc_u32 s53, s47, 0
	s_mov_b32 m0, s58
	ds_read_b128 v[16:19], v150 offset:32768
	ds_read_b128 v[24:27], v150 offset:33792
	ds_read_b128 v[100:103], v150 offset:34816
	ds_read_b128 v[226:229], v150 offset:35840
	ds_read_b128 v[230:233], v150 offset:36864
	ds_read_b128 v[234:237], v150 offset:37888
	ds_read_b128 v[238:241], v150 offset:38912
	ds_read_b128 v[242:245], v150 offset:39936
	s_nop 0
	global_load_lds_dwordx4 v143, s[52:53]
	s_mov_b32 m0, s59
	s_nop 0
	global_load_lds_dwordx4 v145, s[52:53]
	s_waitcnt vmcnt(8)
	s_waitcnt lgkmcnt(0)
	s_barrier
	s_waitcnt lgkmcnt(0)
	v_mfma_f32_16x16x32_bf16 v[32:35], v[0:3], v[16:19], v[32:35]
	v_mfma_f32_16x16x32_bf16 v[120:123], v[8:11], v[24:27], v[32:35]
	v_mfma_f32_16x16x32_bf16 v[32:35], v[12:15], v[16:19], v[36:39]
	v_mfma_f32_16x16x32_bf16 v[112:115], v[206:209], v[24:27], v[32:35]
	v_mfma_f32_16x16x32_bf16 v[32:35], v[0:3], v[100:103], v[40:43]
	v_mfma_f32_16x16x32_bf16 v[104:107], v[8:11], v[226:229], v[32:35]
	v_mfma_f32_16x16x32_bf16 v[32:35], v[12:15], v[100:103], v[44:47]
	v_mfma_f32_16x16x32_bf16 v[96:99], v[206:209], v[226:229], v[32:35]
	v_mfma_f32_16x16x32_bf16 v[32:35], v[0:3], v[230:233], v[48:51]
	v_mfma_f32_16x16x32_bf16 v[88:91], v[8:11], v[234:237], v[32:35]
	v_mfma_f32_16x16x32_bf16 v[32:35], v[12:15], v[230:233], v[52:55]
	v_mfma_f32_16x16x32_bf16 v[80:83], v[206:209], v[234:237], v[32:35]
	v_mfma_f32_16x16x32_bf16 v[32:35], v[0:3], v[238:241], v[56:59]
	v_mfma_f32_16x16x32_bf16 v[68:71], v[8:11], v[242:245], v[32:35]
	v_mfma_f32_16x16x32_bf16 v[32:35], v[12:15], v[238:241], v[60:63]
	v_mfma_f32_16x16x32_bf16 v[52:55], v[206:209], v[242:245], v[32:35]
	v_mfma_f32_16x16x32_bf16 v[32:35], v[210:213], v[16:19], v[64:67]
	v_mfma_f32_16x16x32_bf16 v[16:19], v[218:221], v[16:19], v[72:75]
	v_mfma_f32_16x16x32_bf16 v[116:119], v[222:225], v[24:27], v[16:19]
	v_mfma_f32_16x16x32_bf16 v[16:19], v[210:213], v[100:103], v[76:79]
	v_mfma_f32_16x16x32_bf16 v[108:111], v[214:217], v[226:229], v[16:19]
	v_mfma_f32_16x16x32_bf16 v[16:19], v[218:221], v[100:103], v[84:87]
	v_mfma_f32_16x16x32_bf16 v[100:103], v[222:225], v[226:229], v[16:19]
	v_mfma_f32_16x16x32_bf16 v[16:19], v[210:213], v[230:233], v[92:95]
	v_mfma_f32_16x16x32_bf16 v[92:95], v[214:217], v[234:237], v[16:19]
	v_mfma_f32_16x16x32_bf16 v[16:19], v[218:221], v[230:233], v[128:131]
	v_mfma_f32_16x16x32_bf16 v[84:87], v[222:225], v[234:237], v[16:19]
	v_mfma_f32_16x16x32_bf16 v[16:19], v[210:213], v[238:241], v[132:135]
	v_mfma_f32_16x16x32_bf16 v[76:79], v[214:217], v[242:245], v[16:19]
	v_mfma_f32_16x16x32_bf16 v[16:19], v[218:221], v[238:241], v[136:139]
	v_mfma_f32_16x16x32_bf16 v[124:127], v[214:217], v[24:27], v[32:35]
	v_mfma_f32_16x16x32_bf16 v[60:63], v[222:225], v[242:245], v[16:19]
	s_barrier
	s_add_i32 s72, s67, s26
	s_mov_b32 m0, s72
	s_add_i32 s73, s72, 0x2000
	ds_read_b128 v[36:39], v150 offset:49152
	ds_read_b128 v[44:47], v150 offset:50176
	ds_read_b128 v[128:131], v150 offset:51200
	ds_read_b128 v[132:135], v150 offset:52224
	ds_read_b128 v[136:139], v150 offset:53248
	ds_read_b128 v[226:229], v150 offset:54272
	ds_read_b128 v[230:233], v150 offset:55296
	ds_read_b128 v[234:237], v150 offset:56320
	s_nop 0
	global_load_lds_dwordx4 v144, s[50:51]
	s_mov_b32 m0, s73
	s_nop 0
	global_load_lds_dwordx4 v146, s[50:51]
	s_add_u32 s50, s44, 0x80180
	s_addc_u32 s51, s45, 0
	s_add_i32 s74, s68, s26
	s_mov_b32 m0, s74
	s_add_i32 s75, s74, 0x2000
	s_nop 0
	global_load_lds_dwordx4 v144, s[50:51]
	s_mov_b32 m0, s75
	s_nop 0
	global_load_lds_dwordx4 v146, s[50:51]
	s_mov_b32 m0, s60
	s_nop 0
	global_load_lds_dwordx4 v143, s[48:49]
	s_mov_b32 m0, s61
	s_nop 0
	global_load_lds_dwordx4 v145, s[48:49]
	s_waitcnt vmcnt(8)
	s_waitcnt lgkmcnt(0)
	s_barrier
	s_waitcnt lgkmcnt(0)
	v_mfma_f32_16x16x32_bf16 v[16:19], v[0:3], v[36:39], v[154:157]
	v_mfma_f32_16x16x32_bf16 v[64:67], v[8:11], v[44:47], v[16:19]
	v_mfma_f32_16x16x32_bf16 v[16:19], v[12:15], v[36:39], v[158:161]
	v_mfma_f32_16x16x32_bf16 v[48:51], v[206:209], v[44:47], v[16:19]
	v_mfma_f32_16x16x32_bf16 v[16:19], v[0:3], v[128:131], v[162:165]
	v_mfma_f32_16x16x32_bf16 v[40:43], v[8:11], v[132:135], v[16:19]
	v_mfma_f32_16x16x32_bf16 v[16:19], v[12:15], v[128:131], v[166:169]
	v_mfma_f32_16x16x32_bf16 v[32:35], v[206:209], v[132:135], v[16:19]
	v_mfma_f32_16x16x32_bf16 v[16:19], v[0:3], v[136:139], v[170:173]
	v_mfma_f32_16x16x32_bf16 v[0:3], v[0:3], v[230:233], v[20:23]
	v_mfma_f32_16x16x32_bf16 v[24:27], v[8:11], v[226:229], v[16:19]
	v_mfma_f32_16x16x32_bf16 v[16:19], v[12:15], v[136:139], v[174:177]
	v_mfma_f32_16x16x32_bf16 v[8:11], v[8:11], v[234:237], v[0:3]
	v_mfma_f32_16x16x32_bf16 v[0:3], v[12:15], v[230:233], v[28:31]
	v_mfma_f32_16x16x32_bf16 v[16:19], v[206:209], v[226:229], v[16:19]
	v_mfma_f32_16x16x32_bf16 v[0:3], v[206:209], v[234:237], v[0:3]
	v_mfma_f32_16x16x32_bf16 v[12:15], v[210:213], v[36:39], v[178:181]
	v_mfma_f32_16x16x32_bf16 v[72:75], v[214:217], v[44:47], v[12:15]
	v_mfma_f32_16x16x32_bf16 v[12:15], v[218:221], v[36:39], v[182:185]
	v_mfma_f32_16x16x32_bf16 v[56:59], v[222:225], v[44:47], v[12:15]
	v_mfma_f32_16x16x32_bf16 v[12:15], v[210:213], v[128:131], v[186:189]
	v_mfma_f32_16x16x32_bf16 v[44:47], v[214:217], v[132:135], v[12:15]
	v_mfma_f32_16x16x32_bf16 v[12:15], v[218:221], v[128:131], v[190:193]
	v_mfma_f32_16x16x32_bf16 v[36:39], v[222:225], v[132:135], v[12:15]
	v_mfma_f32_16x16x32_bf16 v[12:15], v[210:213], v[136:139], v[194:197]
	v_mfma_f32_16x16x32_bf16 v[28:31], v[214:217], v[226:229], v[12:15]
	v_mfma_f32_16x16x32_bf16 v[12:15], v[218:221], v[136:139], v[198:201]
	v_mfma_f32_16x16x32_bf16 v[4:7], v[210:213], v[230:233], v[4:7]
	v_mfma_f32_16x16x32_bf16 v[20:23], v[222:225], v[226:229], v[12:15]
	v_mfma_f32_16x16x32_bf16 v[12:15], v[214:217], v[234:237], v[4:7]
	v_mfma_f32_16x16x32_bf16 v[4:7], v[218:221], v[230:233], v[202:205]
	v_mfma_f32_16x16x32_bf16 v[4:7], v[222:225], v[234:237], v[4:7]
	s_barrier
	s_add_u32 s52, s46, 0x100
	s_addc_u32 s53, s47, 0
	s_add_u32 s76, s44, 0x200
	s_addc_u32 s77, s45, 0
	s_mov_b32 s78, 0
	.p2align	6

.LBB0_899:
	s_add_u32 s50, s48, 0x180
	s_waitcnt lgkmcnt(0)
	s_addc_u32 s51, s49, 0
	s_add_u32 s52, s4, 0x180
	s_addc_u32 s53, s5, 0
	s_barrier
	s_waitcnt lgkmcnt(0)
	v_mfma_f32_16x16x32_bf16 v[128:131], v[16:19], v[120:123], 0
	v_mfma_f32_16x16x32_bf16 v[134:137], v[20:23], v[124:127], v[128:131]
	v_mfma_f32_16x16x32_bf16 v[128:131], v[24:27], v[120:123], 0
	v_mfma_f32_16x16x32_bf16 v[156:159], v[28:31], v[124:127], v[128:131]
	v_mfma_f32_16x16x32_bf16 v[128:131], v[16:19], v[104:107], 0
	v_mfma_f32_16x16x32_bf16 v[160:163], v[20:23], v[116:119], v[128:131]
	v_mfma_f32_16x16x32_bf16 v[128:131], v[24:27], v[104:107], 0
	v_mfma_f32_16x16x32_bf16 v[164:167], v[28:31], v[116:119], v[128:131]
	v_mfma_f32_16x16x32_bf16 v[128:131], v[16:19], v[96:99], 0
	v_mfma_f32_16x16x32_bf16 v[16:19], v[16:19], v[76:79], 0
	v_mfma_f32_16x16x32_bf16 v[168:171], v[20:23], v[100:103], v[128:131]
	v_mfma_f32_16x16x32_bf16 v[16:19], v[20:23], v[80:83], v[16:19]
	v_mfma_f32_16x16x32_bf16 v[20:23], v[24:27], v[76:79], 0
	v_mfma_f32_16x16x32_bf16 v[128:131], v[24:27], v[96:99], 0
	v_mfma_f32_16x16x32_bf16 v[20:23], v[28:31], v[80:83], v[20:23]
	v_mfma_f32_16x16x32_bf16 v[172:175], v[28:31], v[100:103], v[128:131]
	v_mfma_f32_16x16x32_bf16 v[24:27], v[0:3], v[120:123], 0
	v_mfma_f32_16x16x32_bf16 v[176:179], v[4:7], v[124:127], v[24:27]
	v_mfma_f32_16x16x32_bf16 v[24:27], v[8:11], v[120:123], 0
	v_mfma_f32_16x16x32_bf16 v[180:183], v[12:15], v[124:127], v[24:27]
	v_mfma_f32_16x16x32_bf16 v[24:27], v[0:3], v[104:107], 0
	v_mfma_f32_16x16x32_bf16 v[186:189], v[4:7], v[116:119], v[24:27]
	v_mfma_f32_16x16x32_bf16 v[24:27], v[8:11], v[104:107], 0
	v_mfma_f32_16x16x32_bf16 v[190:193], v[12:15], v[116:119], v[24:27]
	v_mfma_f32_16x16x32_bf16 v[24:27], v[0:3], v[96:99], 0
	v_mfma_f32_16x16x32_bf16 v[0:3], v[0:3], v[76:79], 0
	v_mfma_f32_16x16x32_bf16 v[194:197], v[4:7], v[100:103], v[24:27]
	v_mfma_f32_16x16x32_bf16 v[24:27], v[8:11], v[96:99], 0
	v_mfma_f32_16x16x32_bf16 v[0:3], v[4:7], v[80:83], v[0:3]
	v_mfma_f32_16x16x32_bf16 v[4:7], v[8:11], v[76:79], 0
	v_mfma_f32_16x16x32_bf16 v[198:201], v[12:15], v[100:103], v[24:27]
	v_mfma_f32_16x16x32_bf16 v[212:215], v[12:15], v[80:83], v[4:7]
	s_barrier
	v_add_u32_e32 v132, s68, v206
	v_add_u32_e32 v133, s69, v206
	s_nop 1
	ds_read_b128 v[4:7], v132
	ds_read_b128 v[8:11], v132 offset:1024
	ds_read_b128 v[216:219], v132 offset:2048
	ds_read_b128 v[220:223], v132 offset:3072
	ds_read_b128 v[224:227], v133
	ds_read_b128 v[228:231], v133 offset:1024
	ds_read_b128 v[232:235], v133 offset:2048
	ds_read_b128 v[236:239], v133 offset:3072
	s_add_u32 s20, s48, 0x160100
	s_addc_u32 s21, s49, 0
	s_mov_b32 m0, s59
	ds_read_b128 v[12:15], v209 offset:32768
	ds_read_b128 v[24:27], v209 offset:33792
	ds_read_b128 v[28:31], v209 offset:34816
	ds_read_b128 v[96:99], v209 offset:35840
	ds_read_b128 v[240:243], v209 offset:36864
	ds_read_b128 v[244:247], v209 offset:37888
	ds_read_b128 v[248:251], v209 offset:38912
	ds_read_b128 v[32:35], v209 offset:39936
	s_nop 0
	global_load_lds_dwordx4 v202, s[20:21]
	s_mov_b32 m0, s60
	s_nop 0
	global_load_lds_dwordx4 v204, s[20:21]
	s_waitcnt vmcnt(8)
	s_waitcnt lgkmcnt(0)
	s_barrier
	s_waitcnt lgkmcnt(0)
	v_mfma_f32_16x16x32_bf16 v[36:39], v[216:219], v[12:15], v[36:39]
	v_mfma_f32_16x16x32_bf16 v[148:151], v[220:223], v[24:27], v[36:39]
	v_mfma_f32_16x16x32_bf16 v[36:39], v[4:7], v[28:31], v[40:43]
	v_mfma_f32_16x16x32_bf16 v[128:131], v[8:11], v[96:99], v[36:39]
	v_mfma_f32_16x16x32_bf16 v[36:39], v[216:219], v[28:31], v[44:47]
	v_mfma_f32_16x16x32_bf16 v[124:127], v[220:223], v[96:99], v[36:39]
	v_mfma_f32_16x16x32_bf16 v[36:39], v[4:7], v[240:243], v[48:51]
	v_mfma_f32_16x16x32_bf16 v[104:107], v[8:11], v[244:247], v[36:39]
	v_mfma_f32_16x16x32_bf16 v[36:39], v[216:219], v[240:243], v[52:55]
	v_mfma_f32_16x16x32_bf16 v[100:103], v[220:223], v[244:247], v[36:39]
	v_mfma_f32_16x16x32_bf16 v[36:39], v[4:7], v[248:251], v[56:59]
	v_mfma_f32_16x16x32_bf16 v[76:79], v[4:7], v[12:15], v[138:141]
	v_mfma_f32_16x16x32_bf16 v[80:83], v[8:11], v[32:35], v[36:39]
	v_mfma_f32_16x16x32_bf16 v[36:39], v[216:219], v[248:251], v[60:63]
	v_mfma_f32_16x16x32_bf16 v[152:155], v[8:11], v[24:27], v[76:79]
	v_mfma_f32_16x16x32_bf16 v[76:79], v[220:223], v[32:35], v[36:39]
	v_mfma_f32_16x16x32_bf16 v[36:39], v[224:227], v[12:15], v[64:67]
	v_mfma_f32_16x16x32_bf16 v[12:15], v[232:235], v[12:15], v[68:71]
	v_mfma_f32_16x16x32_bf16 v[140:143], v[236:239], v[24:27], v[12:15]
	v_mfma_f32_16x16x32_bf16 v[12:15], v[224:227], v[28:31], v[72:75]
	v_mfma_f32_16x16x32_bf16 v[120:123], v[228:231], v[96:99], v[12:15]
	v_mfma_f32_16x16x32_bf16 v[12:15], v[232:235], v[28:31], v[84:87]
	v_mfma_f32_16x16x32_bf16 v[116:119], v[236:239], v[96:99], v[12:15]
	v_mfma_f32_16x16x32_bf16 v[12:15], v[224:227], v[240:243], v[88:91]
	v_mfma_f32_16x16x32_bf16 v[96:99], v[228:231], v[244:247], v[12:15]
	v_mfma_f32_16x16x32_bf16 v[12:15], v[232:235], v[240:243], v[92:95]
	v_mfma_f32_16x16x32_bf16 v[92:95], v[236:239], v[244:247], v[12:15]
	v_mfma_f32_16x16x32_bf16 v[12:15], v[224:227], v[248:251], v[108:111]
	v_mfma_f32_16x16x32_bf16 v[72:75], v[228:231], v[32:35], v[12:15]
	v_mfma_f32_16x16x32_bf16 v[12:15], v[232:235], v[248:251], v[112:115]
	v_mfma_f32_16x16x32_bf16 v[144:147], v[228:231], v[24:27], v[36:39]
	v_mfma_f32_16x16x32_bf16 v[68:71], v[236:239], v[32:35], v[12:15]
	s_barrier
	s_add_i32 s12, s68, s26
	s_mov_b32 m0, s12
	s_add_i32 s20, s12, 0x2000
	ds_read_b128 v[32:35], v209 offset:49152
	ds_read_b128 v[36:39], v209 offset:50176
	ds_read_b128 v[60:63], v209 offset:51200
	ds_read_b128 v[84:87], v209 offset:52224
	ds_read_b128 v[88:91], v209 offset:53248
	ds_read_b128 v[108:111], v209 offset:54272
	ds_read_b128 v[112:115], v209 offset:55296
	ds_read_b128 v[240:243], v209 offset:56320
	s_nop 0
	global_load_lds_dwordx4 v203, s[52:53]
	s_mov_b32 m0, s20
	s_nop 0
	global_load_lds_dwordx4 v205, s[52:53]
	s_add_u32 s52, s4, 0x160180
	s_addc_u32 s53, s5, 0
	s_add_i32 s21, s69, s26
	s_mov_b32 m0, s21
	s_add_i32 s74, s21, 0x2000
	s_nop 0
	global_load_lds_dwordx4 v203, s[52:53]
	s_mov_b32 m0, s74
	s_nop 0
	global_load_lds_dwordx4 v205, s[52:53]
	s_mov_b32 m0, s61
	s_nop 0
	global_load_lds_dwordx4 v202, s[50:51]
	s_mov_b32 m0, s62
	s_nop 0
	global_load_lds_dwordx4 v204, s[50:51]
	s_waitcnt vmcnt(8)
	s_waitcnt lgkmcnt(0)
	s_barrier
	s_waitcnt lgkmcnt(0)
	v_mfma_f32_16x16x32_bf16 v[12:15], v[4:7], v[32:35], v[134:137]
	v_mfma_f32_16x16x32_bf16 v[64:67], v[8:11], v[36:39], v[12:15]
	v_mfma_f32_16x16x32_bf16 v[12:15], v[216:219], v[32:35], v[156:159]
	v_mfma_f32_16x16x32_bf16 v[56:59], v[220:223], v[36:39], v[12:15]
	v_mfma_f32_16x16x32_bf16 v[12:15], v[4:7], v[60:63], v[160:163]
	v_mfma_f32_16x16x32_bf16 v[44:47], v[8:11], v[84:87], v[12:15]
	v_mfma_f32_16x16x32_bf16 v[12:15], v[216:219], v[60:63], v[164:167]
	v_mfma_f32_16x16x32_bf16 v[40:43], v[220:223], v[84:87], v[12:15]
	v_mfma_f32_16x16x32_bf16 v[12:15], v[4:7], v[88:91], v[168:171]
	v_mfma_f32_16x16x32_bf16 v[28:31], v[8:11], v[108:111], v[12:15]
	v_mfma_f32_16x16x32_bf16 v[12:15], v[216:219], v[88:91], v[172:175]
	v_mfma_f32_16x16x32_bf16 v[4:7], v[4:7], v[112:115], v[16:19]
	v_mfma_f32_16x16x32_bf16 v[24:27], v[220:223], v[108:111], v[12:15]
	v_mfma_f32_16x16x32_bf16 v[12:15], v[8:11], v[240:243], v[4:7]
	v_mfma_f32_16x16x32_bf16 v[4:7], v[216:219], v[112:115], v[20:23]
	v_mfma_f32_16x16x32_bf16 v[8:11], v[220:223], v[240:243], v[4:7]
	v_mfma_f32_16x16x32_bf16 v[4:7], v[224:227], v[32:35], v[176:179]
	v_mfma_f32_16x16x32_bf16 v[52:55], v[228:231], v[36:39], v[4:7]
	v_mfma_f32_16x16x32_bf16 v[4:7], v[232:235], v[32:35], v[180:183]
	v_mfma_f32_16x16x32_bf16 v[48:51], v[236:239], v[36:39], v[4:7]
	v_mfma_f32_16x16x32_bf16 v[4:7], v[224:227], v[60:63], v[186:189]
	v_mfma_f32_16x16x32_bf16 v[36:39], v[228:231], v[84:87], v[4:7]
	v_mfma_f32_16x16x32_bf16 v[4:7], v[232:235], v[60:63], v[190:193]
	v_mfma_f32_16x16x32_bf16 v[32:35], v[236:239], v[84:87], v[4:7]
	v_mfma_f32_16x16x32_bf16 v[4:7], v[224:227], v[88:91], v[194:197]
	v_mfma_f32_16x16x32_bf16 v[20:23], v[228:231], v[108:111], v[4:7]
	v_mfma_f32_16x16x32_bf16 v[4:7], v[232:235], v[88:91], v[198:201]
	v_mfma_f32_16x16x32_bf16 v[0:3], v[224:227], v[112:115], v[0:3]
	v_mfma_f32_16x16x32_bf16 v[16:19], v[236:239], v[108:111], v[4:7]
	v_mfma_f32_16x16x32_bf16 v[4:7], v[228:231], v[240:243], v[0:3]
	v_mfma_f32_16x16x32_bf16 v[0:3], v[232:235], v[112:115], v[212:215]
	v_mfma_f32_16x16x32_bf16 v[0:3], v[236:239], v[240:243], v[0:3]
	s_barrier
	s_add_u32 s75, s48, 0x200
	s_addc_u32 s76, s49, 0
	s_add_u32 s77, s4, 0x200
	s_addc_u32 s78, s5, 0
	s_add_u32 s4, s48, 0x160180
	s_addc_u32 s5, s49, 0
	s_mov_b32 s79, 0
	.p2align	6

.LBB0_1009:
	s_ashr_i32 s7, s6, 31
	s_lshl_b64 s[20:21], s[6:7], 20
	s_add_u32 s40, s14, s20
	s_addc_u32 s41, s15, s21
	s_ashr_i32 s9, s8, 31
	s_lshl_b64 s[20:21], s[8:9], 20
	s_add_u32 s42, s24, s20
	s_addc_u32 s43, s25, s21
	s_add_u32 s48, s46, 0x180
	s_addc_u32 s49, s47, 0
	s_waitcnt lgkmcnt(0)
	s_and_b64 s[20:21], s[38:39], exec
	s_cselect_b32 s9, s43, s45
	s_cselect_b32 s12, s42, s44
	s_cselect_b32 s20, s41, s47
	s_cselect_b32 s21, s40, s46
	s_add_u32 s50, s44, 0x180
	s_addc_u32 s51, s45, 0
	s_barrier
	s_waitcnt lgkmcnt(0)
	v_mfma_f32_16x16x32_bf16 v[116:119], v[16:19], v[108:111], 0
	v_mfma_f32_16x16x32_bf16 v[156:159], v[20:23], v[112:115], v[116:119]
	v_mfma_f32_16x16x32_bf16 v[116:119], v[24:27], v[108:111], 0
	v_mfma_f32_16x16x32_bf16 v[160:163], v[28:31], v[112:115], v[116:119]
	v_mfma_f32_16x16x32_bf16 v[116:119], v[16:19], v[100:103], 0
	v_mfma_f32_16x16x32_bf16 v[164:167], v[20:23], v[104:107], v[116:119]
	v_mfma_f32_16x16x32_bf16 v[116:119], v[24:27], v[100:103], 0
	v_mfma_f32_16x16x32_bf16 v[168:171], v[28:31], v[104:107], v[116:119]
	v_mfma_f32_16x16x32_bf16 v[116:119], v[16:19], v[92:95], 0
	v_mfma_f32_16x16x32_bf16 v[16:19], v[16:19], v[60:63], 0
	v_mfma_f32_16x16x32_bf16 v[172:175], v[20:23], v[96:99], v[116:119]
	v_mfma_f32_16x16x32_bf16 v[16:19], v[20:23], v[88:91], v[16:19]
	v_mfma_f32_16x16x32_bf16 v[20:23], v[24:27], v[60:63], 0
	v_mfma_f32_16x16x32_bf16 v[116:119], v[24:27], v[92:95], 0
	v_mfma_f32_16x16x32_bf16 v[20:23], v[28:31], v[88:91], v[20:23]
	v_mfma_f32_16x16x32_bf16 v[176:179], v[28:31], v[96:99], v[116:119]
	v_mfma_f32_16x16x32_bf16 v[24:27], v[0:3], v[108:111], 0
	v_mfma_f32_16x16x32_bf16 v[180:183], v[4:7], v[112:115], v[24:27]
	v_mfma_f32_16x16x32_bf16 v[24:27], v[8:11], v[108:111], 0
	v_mfma_f32_16x16x32_bf16 v[184:187], v[12:15], v[112:115], v[24:27]
	v_mfma_f32_16x16x32_bf16 v[24:27], v[0:3], v[100:103], 0
	v_mfma_f32_16x16x32_bf16 v[188:191], v[4:7], v[104:107], v[24:27]
	v_mfma_f32_16x16x32_bf16 v[24:27], v[8:11], v[100:103], 0
	v_mfma_f32_16x16x32_bf16 v[192:195], v[12:15], v[104:107], v[24:27]
	v_mfma_f32_16x16x32_bf16 v[24:27], v[0:3], v[92:95], 0
	v_mfma_f32_16x16x32_bf16 v[0:3], v[0:3], v[60:63], 0
	v_mfma_f32_16x16x32_bf16 v[196:199], v[4:7], v[96:99], v[24:27]
	v_mfma_f32_16x16x32_bf16 v[24:27], v[8:11], v[92:95], 0
	v_mfma_f32_16x16x32_bf16 v[0:3], v[4:7], v[88:91], v[0:3]
	v_mfma_f32_16x16x32_bf16 v[4:7], v[8:11], v[60:63], 0
	v_mfma_f32_16x16x32_bf16 v[200:203], v[12:15], v[96:99], v[24:27]
	v_mfma_f32_16x16x32_bf16 v[204:207], v[12:15], v[88:91], v[4:7]
	s_barrier
	v_add_u32_e32 v153, s68, v147
	v_add_u32_e32 v154, s69, v147
	s_nop 1
	ds_read_b128 v[4:7], v153
	ds_read_b128 v[8:11], v153 offset:1024
	ds_read_b128 v[208:211], v153 offset:2048
	ds_read_b128 v[212:215], v153 offset:3072
	ds_read_b128 v[216:219], v154
	ds_read_b128 v[220:223], v154 offset:1024
	ds_read_b128 v[224:227], v154 offset:2048
	ds_read_b128 v[228:231], v154 offset:3072
	s_add_u32 s52, s46, 0x80100
	s_addc_u32 s53, s47, 0
	s_mov_b32 m0, s59
	ds_read_b128 v[12:15], v150 offset:32768
	ds_read_b128 v[24:27], v150 offset:33792
	ds_read_b128 v[28:31], v150 offset:34816
	ds_read_b128 v[96:99], v150 offset:35840
	ds_read_b128 v[232:235], v150 offset:36864
	ds_read_b128 v[236:239], v150 offset:37888
	ds_read_b128 v[240:243], v150 offset:38912
	ds_read_b128 v[244:247], v150 offset:39936
	s_nop 0
	global_load_lds_dwordx4 v143, s[52:53]
	s_mov_b32 m0, s60
	s_nop 0
	global_load_lds_dwordx4 v145, s[52:53]
	s_waitcnt vmcnt(8)
	s_waitcnt lgkmcnt(0)
	s_barrier
	s_waitcnt lgkmcnt(0)
	v_mfma_f32_16x16x32_bf16 v[32:35], v[4:7], v[12:15], v[32:35]
	v_mfma_f32_16x16x32_bf16 v[124:127], v[8:11], v[24:27], v[32:35]
	v_mfma_f32_16x16x32_bf16 v[32:35], v[208:211], v[12:15], v[36:39]
	v_mfma_f32_16x16x32_bf16 v[120:123], v[212:215], v[24:27], v[32:35]
	v_mfma_f32_16x16x32_bf16 v[32:35], v[4:7], v[28:31], v[40:43]
	v_mfma_f32_16x16x32_bf16 v[108:111], v[8:11], v[96:99], v[32:35]
	v_mfma_f32_16x16x32_bf16 v[32:35], v[208:211], v[28:31], v[44:47]
	v_mfma_f32_16x16x32_bf16 v[104:107], v[212:215], v[96:99], v[32:35]
	v_mfma_f32_16x16x32_bf16 v[32:35], v[4:7], v[232:235], v[48:51]
	v_mfma_f32_16x16x32_bf16 v[92:95], v[8:11], v[236:239], v[32:35]
	v_mfma_f32_16x16x32_bf16 v[32:35], v[208:211], v[232:235], v[52:55]
	v_mfma_f32_16x16x32_bf16 v[88:91], v[212:215], v[236:239], v[32:35]
	v_mfma_f32_16x16x32_bf16 v[32:35], v[4:7], v[240:243], v[56:59]
	v_mfma_f32_16x16x32_bf16 v[60:63], v[8:11], v[244:247], v[32:35]
	v_mfma_f32_16x16x32_bf16 v[32:35], v[208:211], v[240:243], v[64:67]
	v_mfma_f32_16x16x32_bf16 v[56:59], v[212:215], v[244:247], v[32:35]
	v_mfma_f32_16x16x32_bf16 v[32:35], v[216:219], v[12:15], v[68:71]
	v_mfma_f32_16x16x32_bf16 v[12:15], v[224:227], v[12:15], v[72:75]
	v_mfma_f32_16x16x32_bf16 v[112:115], v[228:231], v[24:27], v[12:15]
	v_mfma_f32_16x16x32_bf16 v[12:15], v[216:219], v[28:31], v[76:79]
	v_mfma_f32_16x16x32_bf16 v[100:103], v[220:223], v[96:99], v[12:15]
	v_mfma_f32_16x16x32_bf16 v[12:15], v[224:227], v[28:31], v[80:83]
	v_mfma_f32_16x16x32_bf16 v[96:99], v[228:231], v[96:99], v[12:15]
	v_mfma_f32_16x16x32_bf16 v[12:15], v[216:219], v[232:235], v[84:87]
	v_mfma_f32_16x16x32_bf16 v[84:87], v[220:223], v[236:239], v[12:15]
	v_mfma_f32_16x16x32_bf16 v[12:15], v[224:227], v[232:235], v[128:131]
	v_mfma_f32_16x16x32_bf16 v[80:83], v[228:231], v[236:239], v[12:15]
	v_mfma_f32_16x16x32_bf16 v[12:15], v[216:219], v[240:243], v[132:135]
	v_mfma_f32_16x16x32_bf16 v[52:55], v[220:223], v[244:247], v[12:15]
	v_mfma_f32_16x16x32_bf16 v[12:15], v[224:227], v[240:243], v[136:139]
	v_mfma_f32_16x16x32_bf16 v[116:119], v[220:223], v[24:27], v[32:35]
	v_mfma_f32_16x16x32_bf16 v[48:51], v[228:231], v[244:247], v[12:15]
	s_barrier
	s_add_i32 s35, s68, s26
	s_mov_b32 m0, s35
	s_add_i32 s73, s35, 0x2000
	ds_read_b128 v[32:35], v150 offset:49152
	ds_read_b128 v[36:39], v150 offset:50176
	ds_read_b128 v[128:131], v150 offset:51200
	ds_read_b128 v[132:135], v150 offset:52224
	ds_read_b128 v[136:139], v150 offset:53248
	ds_read_b128 v[232:235], v150 offset:54272
	ds_read_b128 v[236:239], v150 offset:55296
	ds_read_b128 v[240:243], v150 offset:56320
	s_nop 0
	global_load_lds_dwordx4 v144, s[50:51]
	s_mov_b32 m0, s73
	s_nop 0
	global_load_lds_dwordx4 v146, s[50:51]
	s_add_u32 s50, s44, 0x80180
	s_addc_u32 s51, s45, 0
	s_add_i32 s74, s69, s26
	s_mov_b32 m0, s74
	s_add_i32 s75, s74, 0x2000
	s_nop 0
	global_load_lds_dwordx4 v144, s[50:51]
	s_mov_b32 m0, s75
	s_nop 0
	global_load_lds_dwordx4 v146, s[50:51]
	s_mov_b32 m0, s61
	s_nop 0
	global_load_lds_dwordx4 v143, s[48:49]
	s_mov_b32 m0, s62
	s_nop 0
	global_load_lds_dwordx4 v145, s[48:49]
	s_waitcnt vmcnt(8)
	s_waitcnt lgkmcnt(0)
	s_barrier
	s_waitcnt lgkmcnt(0)
	v_mfma_f32_16x16x32_bf16 v[12:15], v[4:7], v[32:35], v[156:159]
	v_mfma_f32_16x16x32_bf16 v[76:79], v[8:11], v[36:39], v[12:15]
	v_mfma_f32_16x16x32_bf16 v[12:15], v[208:211], v[32:35], v[160:163]
	v_mfma_f32_16x16x32_bf16 v[72:75], v[212:215], v[36:39], v[12:15]
	v_mfma_f32_16x16x32_bf16 v[12:15], v[4:7], v[128:131], v[164:167]
	v_mfma_f32_16x16x32_bf16 v[44:47], v[8:11], v[132:135], v[12:15]
	v_mfma_f32_16x16x32_bf16 v[12:15], v[208:211], v[128:131], v[168:171]
	v_mfma_f32_16x16x32_bf16 v[40:43], v[212:215], v[132:135], v[12:15]
	v_mfma_f32_16x16x32_bf16 v[12:15], v[4:7], v[136:139], v[172:175]
	v_mfma_f32_16x16x32_bf16 v[28:31], v[8:11], v[232:235], v[12:15]
	v_mfma_f32_16x16x32_bf16 v[12:15], v[208:211], v[136:139], v[176:179]
	v_mfma_f32_16x16x32_bf16 v[4:7], v[4:7], v[236:239], v[16:19]
	v_mfma_f32_16x16x32_bf16 v[24:27], v[212:215], v[232:235], v[12:15]
	v_mfma_f32_16x16x32_bf16 v[12:15], v[8:11], v[240:243], v[4:7]
	v_mfma_f32_16x16x32_bf16 v[4:7], v[208:211], v[236:239], v[20:23]
	v_mfma_f32_16x16x32_bf16 v[8:11], v[212:215], v[240:243], v[4:7]
	v_mfma_f32_16x16x32_bf16 v[4:7], v[216:219], v[32:35], v[180:183]
	v_mfma_f32_16x16x32_bf16 v[68:71], v[220:223], v[36:39], v[4:7]
	v_mfma_f32_16x16x32_bf16 v[4:7], v[224:227], v[32:35], v[184:187]
	v_mfma_f32_16x16x32_bf16 v[64:67], v[228:231], v[36:39], v[4:7]
	v_mfma_f32_16x16x32_bf16 v[4:7], v[216:219], v[128:131], v[188:191]
	v_mfma_f32_16x16x32_bf16 v[36:39], v[220:223], v[132:135], v[4:7]
	v_mfma_f32_16x16x32_bf16 v[4:7], v[224:227], v[128:131], v[192:195]
	v_mfma_f32_16x16x32_bf16 v[32:35], v[228:231], v[132:135], v[4:7]
	v_mfma_f32_16x16x32_bf16 v[4:7], v[216:219], v[136:139], v[196:199]
	v_mfma_f32_16x16x32_bf16 v[20:23], v[220:223], v[232:235], v[4:7]
	v_mfma_f32_16x16x32_bf16 v[4:7], v[224:227], v[136:139], v[200:203]
	v_mfma_f32_16x16x32_bf16 v[0:3], v[216:219], v[236:239], v[0:3]
	v_mfma_f32_16x16x32_bf16 v[16:19], v[228:231], v[232:235], v[4:7]
	v_mfma_f32_16x16x32_bf16 v[4:7], v[220:223], v[240:243], v[0:3]
	v_mfma_f32_16x16x32_bf16 v[0:3], v[224:227], v[236:239], v[204:207]
	v_mfma_f32_16x16x32_bf16 v[0:3], v[228:231], v[240:243], v[0:3]
	s_barrier
	s_add_u32 s52, s46, 0x100
	s_addc_u32 s53, s47, 0
	s_add_u32 s76, s44, 0x200
	s_addc_u32 s77, s45, 0
	s_mov_b32 s78, 0
	.p2align	6

.LBB0_1589:
	s_ashr_i32 s7, s6, 31
	s_lshl_b64 s[20:21], s[6:7], 20
	s_add_u32 s42, s14, s20
	s_addc_u32 s43, s15, s21
	s_ashr_i32 s35, s34, 31
	s_lshl_b64 s[20:21], s[34:35], 20
	s_add_u32 s44, s24, s20
	s_addc_u32 s45, s25, s21
	s_add_u32 s54, s52, 0x180
	s_addc_u32 s55, s53, 0
	s_waitcnt lgkmcnt(0)
	s_and_b64 s[20:21], s[36:37], exec
	s_cselect_b32 s20, s45, s51
	s_cselect_b32 s21, s44, s50
	s_cselect_b32 s35, s43, s53
	s_cselect_b32 s47, s42, s52
	s_add_u32 s56, s50, 0x180
	s_addc_u32 s57, s51, 0
	s_barrier
	s_waitcnt lgkmcnt(0)
	v_mfma_f32_16x16x32_bf16 v[112:115], v[16:19], v[104:107], 0
	v_mfma_f32_16x16x32_bf16 v[166:169], v[20:23], v[108:111], v[112:115]
	v_mfma_f32_16x16x32_bf16 v[112:115], v[24:27], v[104:107], 0
	v_mfma_f32_16x16x32_bf16 v[170:173], v[28:31], v[108:111], v[112:115]
	v_mfma_f32_16x16x32_bf16 v[112:115], v[16:19], v[96:99], 0
	v_mfma_f32_16x16x32_bf16 v[174:177], v[20:23], v[100:103], v[112:115]
	v_mfma_f32_16x16x32_bf16 v[112:115], v[24:27], v[96:99], 0
	v_mfma_f32_16x16x32_bf16 v[178:181], v[28:31], v[100:103], v[112:115]
	v_mfma_f32_16x16x32_bf16 v[112:115], v[16:19], v[88:91], 0
	v_mfma_f32_16x16x32_bf16 v[16:19], v[16:19], v[72:75], 0
	v_mfma_f32_16x16x32_bf16 v[182:185], v[20:23], v[92:95], v[112:115]
	v_mfma_f32_16x16x32_bf16 v[16:19], v[20:23], v[76:79], v[16:19]
	v_mfma_f32_16x16x32_bf16 v[20:23], v[24:27], v[72:75], 0
	v_mfma_f32_16x16x32_bf16 v[112:115], v[24:27], v[88:91], 0
	v_mfma_f32_16x16x32_bf16 v[20:23], v[28:31], v[76:79], v[20:23]
	v_mfma_f32_16x16x32_bf16 v[186:189], v[28:31], v[92:95], v[112:115]
	v_mfma_f32_16x16x32_bf16 v[24:27], v[0:3], v[104:107], 0
	v_mfma_f32_16x16x32_bf16 v[190:193], v[4:7], v[108:111], v[24:27]
	v_mfma_f32_16x16x32_bf16 v[24:27], v[8:11], v[104:107], 0
	v_mfma_f32_16x16x32_bf16 v[194:197], v[12:15], v[108:111], v[24:27]
	v_mfma_f32_16x16x32_bf16 v[24:27], v[0:3], v[96:99], 0
	v_mfma_f32_16x16x32_bf16 v[198:201], v[4:7], v[100:103], v[24:27]
	v_mfma_f32_16x16x32_bf16 v[24:27], v[8:11], v[96:99], 0
	v_mfma_f32_16x16x32_bf16 v[202:205], v[12:15], v[100:103], v[24:27]
	v_mfma_f32_16x16x32_bf16 v[24:27], v[0:3], v[88:91], 0
	v_mfma_f32_16x16x32_bf16 v[0:3], v[0:3], v[72:75], 0
	v_mfma_f32_16x16x32_bf16 v[206:209], v[4:7], v[92:95], v[24:27]
	v_mfma_f32_16x16x32_bf16 v[24:27], v[8:11], v[88:91], 0
	v_mfma_f32_16x16x32_bf16 v[0:3], v[4:7], v[76:79], v[0:3]
	v_mfma_f32_16x16x32_bf16 v[4:7], v[8:11], v[72:75], 0
	v_mfma_f32_16x16x32_bf16 v[210:213], v[12:15], v[92:95], v[24:27]
	v_mfma_f32_16x16x32_bf16 v[214:217], v[12:15], v[76:79], v[4:7]
	s_barrier
	v_add_u32_e32 v144, s74, v159
	v_add_u32_e32 v148, s75, v159
	s_nop 1
	ds_read_b128 v[4:7], v144
	ds_read_b128 v[8:11], v144 offset:1024
	ds_read_b128 v[218:221], v144 offset:2048
	ds_read_b128 v[222:225], v144 offset:3072
	ds_read_b128 v[226:229], v148
	ds_read_b128 v[230:233], v148 offset:1024
	ds_read_b128 v[234:237], v148 offset:2048
	ds_read_b128 v[238:241], v148 offset:3072
	s_add_u32 s58, s52, 0x80100
	s_addc_u32 s59, s53, 0
	s_mov_b32 m0, s66
	ds_read_b128 v[12:15], v162 offset:32768
	ds_read_b128 v[24:27], v162 offset:33792
	ds_read_b128 v[28:31], v162 offset:34816
	ds_read_b128 v[96:99], v162 offset:35840
	ds_read_b128 v[242:245], v162 offset:36864
	ds_read_b128 v[246:249], v162 offset:37888
	ds_read_b128 v[250:253], v162 offset:38912
	ds_read_b128 v[32:35], v162 offset:39936
	s_nop 0
	global_load_lds_dwordx4 v153, s[58:59]
	s_mov_b32 m0, s67
	s_nop 0
	global_load_lds_dwordx4 v157, s[58:59]
	s_waitcnt vmcnt(8)
	s_waitcnt lgkmcnt(0)
	s_barrier
	s_waitcnt lgkmcnt(0)
	v_mfma_f32_16x16x32_bf16 v[36:39], v[218:221], v[12:15], v[36:39]
	v_mfma_f32_16x16x32_bf16 v[120:123], v[222:225], v[24:27], v[36:39]
	v_mfma_f32_16x16x32_bf16 v[36:39], v[4:7], v[28:31], v[40:43]
	v_mfma_f32_16x16x32_bf16 v[108:111], v[8:11], v[96:99], v[36:39]
	v_mfma_f32_16x16x32_bf16 v[36:39], v[218:221], v[28:31], v[44:47]
	v_mfma_f32_16x16x32_bf16 v[104:107], v[222:225], v[96:99], v[36:39]
	v_mfma_f32_16x16x32_bf16 v[36:39], v[4:7], v[242:245], v[48:51]
	v_mfma_f32_16x16x32_bf16 v[92:95], v[8:11], v[246:249], v[36:39]
	v_mfma_f32_16x16x32_bf16 v[36:39], v[218:221], v[242:245], v[52:55]
	v_mfma_f32_16x16x32_bf16 v[88:91], v[222:225], v[246:249], v[36:39]
	v_mfma_f32_16x16x32_bf16 v[36:39], v[4:7], v[250:253], v[56:59]
	v_mfma_f32_16x16x32_bf16 v[72:75], v[4:7], v[12:15], v[116:119]
	v_mfma_f32_16x16x32_bf16 v[76:79], v[8:11], v[32:35], v[36:39]
	v_mfma_f32_16x16x32_bf16 v[36:39], v[218:221], v[250:253], v[60:63]
	v_mfma_f32_16x16x32_bf16 v[124:127], v[8:11], v[24:27], v[72:75]
	v_mfma_f32_16x16x32_bf16 v[72:75], v[222:225], v[32:35], v[36:39]
	v_mfma_f32_16x16x32_bf16 v[36:39], v[226:229], v[12:15], v[64:67]
	v_mfma_f32_16x16x32_bf16 v[12:15], v[234:237], v[12:15], v[68:71]
	v_mfma_f32_16x16x32_bf16 v[112:115], v[238:241], v[24:27], v[12:15]
	v_mfma_f32_16x16x32_bf16 v[12:15], v[226:229], v[28:31], v[80:83]
	v_mfma_f32_16x16x32_bf16 v[100:103], v[230:233], v[96:99], v[12:15]
	v_mfma_f32_16x16x32_bf16 v[12:15], v[234:237], v[28:31], v[84:87]
	v_mfma_f32_16x16x32_bf16 v[96:99], v[238:241], v[96:99], v[12:15]
	v_mfma_f32_16x16x32_bf16 v[12:15], v[226:229], v[242:245], v[128:131]
	v_mfma_f32_16x16x32_bf16 v[84:87], v[230:233], v[246:249], v[12:15]
	v_mfma_f32_16x16x32_bf16 v[12:15], v[234:237], v[242:245], v[132:135]
	v_mfma_f32_16x16x32_bf16 v[80:83], v[238:241], v[246:249], v[12:15]
	v_mfma_f32_16x16x32_bf16 v[12:15], v[226:229], v[250:253], v[136:139]
	v_mfma_f32_16x16x32_bf16 v[68:71], v[230:233], v[32:35], v[12:15]
	v_mfma_f32_16x16x32_bf16 v[12:15], v[234:237], v[250:253], v[140:143]
	v_mfma_f32_16x16x32_bf16 v[116:119], v[230:233], v[24:27], v[36:39]
	v_mfma_f32_16x16x32_bf16 v[60:63], v[238:241], v[32:35], v[12:15]
	s_barrier
	s_add_i32 s49, s74, s26
	s_mov_b32 m0, s49
	s_add_i32 s79, s49, 0x2000
	ds_read_b128 v[32:35], v162 offset:49152
	ds_read_b128 v[36:39], v162 offset:50176
	ds_read_b128 v[128:131], v162 offset:51200
	ds_read_b128 v[132:135], v162 offset:52224
	ds_read_b128 v[136:139], v162 offset:53248
	ds_read_b128 v[140:143], v162 offset:54272
	ds_read_b128 v[242:245], v162 offset:55296
	ds_read_b128 v[246:249], v162 offset:56320
	s_nop 0
	global_load_lds_dwordx4 v156, s[56:57]
	s_mov_b32 m0, s79
	s_nop 0
	global_load_lds_dwordx4 v158, s[56:57]
	s_add_u32 s56, s50, 0x80180
	s_addc_u32 s57, s51, 0
	s_add_i32 s80, s75, s26
	s_mov_b32 m0, s80
	s_add_i32 s83, s80, 0x2000
	s_nop 0
	global_load_lds_dwordx4 v156, s[56:57]
	s_mov_b32 m0, s83
	s_nop 0
	global_load_lds_dwordx4 v158, s[56:57]
	s_mov_b32 m0, s68
	s_nop 0
	global_load_lds_dwordx4 v153, s[54:55]
	s_mov_b32 m0, s69
	s_nop 0
	global_load_lds_dwordx4 v157, s[54:55]
	s_waitcnt vmcnt(8)
	s_waitcnt lgkmcnt(0)
	s_barrier
	s_waitcnt lgkmcnt(0)
	v_mfma_f32_16x16x32_bf16 v[12:15], v[4:7], v[32:35], v[166:169]
	v_mfma_f32_16x16x32_bf16 v[64:67], v[8:11], v[36:39], v[12:15]
	v_mfma_f32_16x16x32_bf16 v[12:15], v[218:221], v[32:35], v[170:173]
	v_mfma_f32_16x16x32_bf16 v[56:59], v[222:225], v[36:39], v[12:15]
	v_mfma_f32_16x16x32_bf16 v[12:15], v[4:7], v[128:131], v[174:177]
	v_mfma_f32_16x16x32_bf16 v[44:47], v[8:11], v[132:135], v[12:15]
	v_mfma_f32_16x16x32_bf16 v[12:15], v[218:221], v[128:131], v[178:181]
	v_mfma_f32_16x16x32_bf16 v[40:43], v[222:225], v[132:135], v[12:15]
	v_mfma_f32_16x16x32_bf16 v[12:15], v[4:7], v[136:139], v[182:185]
	v_mfma_f32_16x16x32_bf16 v[28:31], v[8:11], v[140:143], v[12:15]
	v_mfma_f32_16x16x32_bf16 v[12:15], v[218:221], v[136:139], v[186:189]
	v_mfma_f32_16x16x32_bf16 v[4:7], v[4:7], v[242:245], v[16:19]
	v_mfma_f32_16x16x32_bf16 v[24:27], v[222:225], v[140:143], v[12:15]
	v_mfma_f32_16x16x32_bf16 v[12:15], v[8:11], v[246:249], v[4:7]
	v_mfma_f32_16x16x32_bf16 v[4:7], v[218:221], v[242:245], v[20:23]
	v_mfma_f32_16x16x32_bf16 v[8:11], v[222:225], v[246:249], v[4:7]
	v_mfma_f32_16x16x32_bf16 v[4:7], v[226:229], v[32:35], v[190:193]
	v_mfma_f32_16x16x32_bf16 v[52:55], v[230:233], v[36:39], v[4:7]
	v_mfma_f32_16x16x32_bf16 v[4:7], v[234:237], v[32:35], v[194:197]
	v_mfma_f32_16x16x32_bf16 v[48:51], v[238:241], v[36:39], v[4:7]
	v_mfma_f32_16x16x32_bf16 v[4:7], v[226:229], v[128:131], v[198:201]
	v_mfma_f32_16x16x32_bf16 v[36:39], v[230:233], v[132:135], v[4:7]
	v_mfma_f32_16x16x32_bf16 v[4:7], v[234:237], v[128:131], v[202:205]
	v_mfma_f32_16x16x32_bf16 v[32:35], v[238:241], v[132:135], v[4:7]
	v_mfma_f32_16x16x32_bf16 v[4:7], v[226:229], v[136:139], v[206:209]
	v_mfma_f32_16x16x32_bf16 v[20:23], v[230:233], v[140:143], v[4:7]
	v_mfma_f32_16x16x32_bf16 v[4:7], v[234:237], v[136:139], v[210:213]
	v_mfma_f32_16x16x32_bf16 v[0:3], v[226:229], v[242:245], v[0:3]
	v_mfma_f32_16x16x32_bf16 v[16:19], v[238:241], v[140:143], v[4:7]
	v_mfma_f32_16x16x32_bf16 v[4:7], v[230:233], v[246:249], v[0:3]
	v_mfma_f32_16x16x32_bf16 v[0:3], v[234:237], v[242:245], v[214:217]
	v_mfma_f32_16x16x32_bf16 v[0:3], v[238:241], v[246:249], v[0:3]
	s_barrier
	s_add_u32 s58, s52, 0x100
	s_addc_u32 s59, s53, 0
	s_add_u32 s86, s50, 0x200
	s_addc_u32 s88, s51, 0
	s_mov_b32 s89, 0
	.p2align	6

.LBB0_1705:
	s_ashr_i32 s47, s46, 31
	s_lshl_b64 s[20:21], s[46:47], 18
	s_add_u32 s50, s24, s20
	s_addc_u32 s51, s25, s21
	s_add_u32 s60, s56, 0x180
	s_addc_u32 s61, s57, 0
	s_waitcnt lgkmcnt(0)
	s_and_b64 s[20:21], s[58:59], exec
	s_cselect_b32 s12, s51, s55
	s_cselect_b32 s20, s50, s54
	s_add_u32 s58, s54, 0x180
	s_addc_u32 s59, s55, 0
	s_barrier
	s_waitcnt lgkmcnt(0)
	v_mfma_f32_16x16x32_bf16 v[128:131], v[16:19], v[120:123], 0
	v_mfma_f32_16x16x32_bf16 v[132:135], v[20:23], v[124:127], v[128:131]
	v_mfma_f32_16x16x32_bf16 v[128:131], v[24:27], v[120:123], 0
	v_mfma_f32_16x16x32_bf16 v[144:147], v[28:31], v[124:127], v[128:131]
	v_mfma_f32_16x16x32_bf16 v[128:131], v[16:19], v[112:115], 0
	v_mfma_f32_16x16x32_bf16 v[152:155], v[20:23], v[116:119], v[128:131]
	v_mfma_f32_16x16x32_bf16 v[128:131], v[24:27], v[112:115], 0
	v_mfma_f32_16x16x32_bf16 v[168:171], v[28:31], v[116:119], v[128:131]
	v_mfma_f32_16x16x32_bf16 v[128:131], v[16:19], v[96:99], 0
	v_mfma_f32_16x16x32_bf16 v[16:19], v[16:19], v[88:91], 0
	v_mfma_f32_16x16x32_bf16 v[172:175], v[20:23], v[108:111], v[128:131]
	v_mfma_f32_16x16x32_bf16 v[16:19], v[20:23], v[92:95], v[16:19]
	v_mfma_f32_16x16x32_bf16 v[20:23], v[24:27], v[88:91], 0
	v_mfma_f32_16x16x32_bf16 v[128:131], v[24:27], v[96:99], 0
	v_mfma_f32_16x16x32_bf16 v[20:23], v[28:31], v[92:95], v[20:23]
	v_mfma_f32_16x16x32_bf16 v[176:179], v[28:31], v[108:111], v[128:131]
	v_mfma_f32_16x16x32_bf16 v[24:27], v[0:3], v[120:123], 0
	v_mfma_f32_16x16x32_bf16 v[180:183], v[4:7], v[124:127], v[24:27]
	v_mfma_f32_16x16x32_bf16 v[24:27], v[8:11], v[120:123], 0
	v_mfma_f32_16x16x32_bf16 v[188:191], v[12:15], v[124:127], v[24:27]
	v_mfma_f32_16x16x32_bf16 v[24:27], v[0:3], v[112:115], 0
	v_mfma_f32_16x16x32_bf16 v[192:195], v[4:7], v[116:119], v[24:27]
	v_mfma_f32_16x16x32_bf16 v[24:27], v[8:11], v[112:115], 0
	v_mfma_f32_16x16x32_bf16 v[208:211], v[12:15], v[116:119], v[24:27]
	v_mfma_f32_16x16x32_bf16 v[24:27], v[0:3], v[96:99], 0
	v_mfma_f32_16x16x32_bf16 v[0:3], v[0:3], v[88:91], 0
	v_mfma_f32_16x16x32_bf16 v[212:215], v[4:7], v[108:111], v[24:27]
	v_mfma_f32_16x16x32_bf16 v[24:27], v[8:11], v[96:99], 0
	v_mfma_f32_16x16x32_bf16 v[0:3], v[4:7], v[92:95], v[0:3]
	v_mfma_f32_16x16x32_bf16 v[4:7], v[8:11], v[88:91], 0
	v_mfma_f32_16x16x32_bf16 v[216:219], v[12:15], v[108:111], v[24:27]
	v_mfma_f32_16x16x32_bf16 v[220:223], v[12:15], v[92:95], v[4:7]
	s_barrier
	v_add_u32_e32 v124, s78, v203
	v_add_u32_e32 v125, s83, v203
	s_nop 1
	ds_read_b128 v[4:7], v124
	ds_read_b128 v[8:11], v124 offset:1024
	ds_read_b128 v[224:227], v124 offset:2048
	ds_read_b128 v[228:231], v124 offset:3072
	ds_read_b128 v[232:235], v125
	ds_read_b128 v[236:239], v125 offset:1024
	ds_read_b128 v[240:243], v125 offset:2048
	ds_read_b128 v[244:247], v125 offset:3072
	s_add_u32 s62, s56, 0x70100
	s_addc_u32 s63, s57, 0
	s_mov_b32 m0, s70
	ds_read_b128 v[12:15], v206 offset:32768
	ds_read_b128 v[24:27], v206 offset:33792
	ds_read_b128 v[28:31], v206 offset:34816
	ds_read_b128 v[96:99], v206 offset:35840
	ds_read_b128 v[248:251], v206 offset:36864
	ds_read_b128 v[184:187], v206 offset:37888
	ds_read_b128 v[32:35], v206 offset:38912
	ds_read_b128 v[36:39], v206 offset:39936
	s_nop 0
	global_load_lds_dwordx4 v199, s[62:63]
	s_mov_b32 m0, s71
	s_nop 0
	global_load_lds_dwordx4 v201, s[62:63]
	s_waitcnt vmcnt(8)
	s_waitcnt lgkmcnt(0)
	s_barrier
	s_waitcnt lgkmcnt(0)
	v_mfma_f32_16x16x32_bf16 v[88:91], v[4:7], v[12:15], v[136:139]
	v_mfma_f32_16x16x32_bf16 v[40:43], v[4:7], v[28:31], v[40:43]
	v_mfma_f32_16x16x32_bf16 v[164:167], v[8:11], v[24:27], v[88:91]
	v_mfma_f32_16x16x32_bf16 v[88:91], v[224:227], v[12:15], v[140:143]
	v_mfma_f32_16x16x32_bf16 v[140:143], v[8:11], v[96:99], v[40:43]
	v_mfma_f32_16x16x32_bf16 v[40:43], v[224:227], v[28:31], v[44:47]
	v_mfma_f32_16x16x32_bf16 v[136:139], v[228:231], v[96:99], v[40:43]
	v_mfma_f32_16x16x32_bf16 v[40:43], v[4:7], v[248:251], v[48:51]
	v_mfma_f32_16x16x32_bf16 v[116:119], v[8:11], v[184:187], v[40:43]
	v_mfma_f32_16x16x32_bf16 v[40:43], v[224:227], v[248:251], v[52:55]
	v_mfma_f32_16x16x32_bf16 v[112:115], v[228:231], v[184:187], v[40:43]
	v_mfma_f32_16x16x32_bf16 v[40:43], v[4:7], v[32:35], v[56:59]
	v_mfma_f32_16x16x32_bf16 v[92:95], v[8:11], v[36:39], v[40:43]
	v_mfma_f32_16x16x32_bf16 v[40:43], v[224:227], v[32:35], v[60:63]
	v_mfma_f32_16x16x32_bf16 v[160:163], v[228:231], v[24:27], v[88:91]
	v_mfma_f32_16x16x32_bf16 v[88:91], v[228:231], v[36:39], v[40:43]
	v_mfma_f32_16x16x32_bf16 v[40:43], v[232:235], v[12:15], v[64:67]
	v_mfma_f32_16x16x32_bf16 v[12:15], v[240:243], v[12:15], v[68:71]
	v_mfma_f32_16x16x32_bf16 v[148:151], v[244:247], v[24:27], v[12:15]
	v_mfma_f32_16x16x32_bf16 v[12:15], v[232:235], v[28:31], v[72:75]
	v_mfma_f32_16x16x32_bf16 v[128:131], v[236:239], v[96:99], v[12:15]
	v_mfma_f32_16x16x32_bf16 v[12:15], v[240:243], v[28:31], v[76:79]
	v_mfma_f32_16x16x32_bf16 v[120:123], v[244:247], v[96:99], v[12:15]
	v_mfma_f32_16x16x32_bf16 v[12:15], v[232:235], v[248:251], v[80:83]
	v_mfma_f32_16x16x32_bf16 v[108:111], v[236:239], v[184:187], v[12:15]
	v_mfma_f32_16x16x32_bf16 v[12:15], v[240:243], v[248:251], v[84:87]
	v_mfma_f32_16x16x32_bf16 v[96:99], v[244:247], v[184:187], v[12:15]
	v_mfma_f32_16x16x32_bf16 v[12:15], v[232:235], v[32:35], v[100:103]
	v_mfma_f32_16x16x32_bf16 v[84:87], v[236:239], v[36:39], v[12:15]
	v_mfma_f32_16x16x32_bf16 v[12:15], v[240:243], v[32:35], v[104:107]
	v_mfma_f32_16x16x32_bf16 v[156:159], v[236:239], v[24:27], v[40:43]
	v_mfma_f32_16x16x32_bf16 v[72:75], v[244:247], v[36:39], v[12:15]
	s_barrier
	s_add_i32 s21, s78, s26
	s_mov_b32 m0, s21
	s_add_i32 s45, s21, 0x2000
	ds_read_b128 v[32:35], v206 offset:49152
	ds_read_b128 v[36:39], v206 offset:50176
	ds_read_b128 v[48:51], v206 offset:51200
	ds_read_b128 v[52:55], v206 offset:52224
	ds_read_b128 v[76:79], v206 offset:53248
	ds_read_b128 v[80:83], v206 offset:54272
	ds_read_b128 v[100:103], v206 offset:55296
	ds_read_b128 v[104:107], v206 offset:56320
	s_nop 0
	global_load_lds_dwordx4 v200, s[58:59]
	s_mov_b32 m0, s45
	s_nop 0
	global_load_lds_dwordx4 v202, s[58:59]
	s_add_u32 s58, s54, 0x20180
	s_addc_u32 s59, s55, 0
	s_add_i32 s47, s83, s26
	s_mov_b32 m0, s47
	s_add_i32 s53, s47, 0x2000
	s_nop 0
	global_load_lds_dwordx4 v200, s[58:59]
	s_mov_b32 m0, s53
	s_nop 0
	global_load_lds_dwordx4 v202, s[58:59]
	s_mov_b32 m0, s72
	s_nop 0
	global_load_lds_dwordx4 v199, s[60:61]
	s_mov_b32 m0, s73
	s_nop 0
	global_load_lds_dwordx4 v201, s[60:61]
	s_waitcnt vmcnt(8)
	s_waitcnt lgkmcnt(0)
	s_barrier
	s_waitcnt lgkmcnt(0)
	v_mfma_f32_16x16x32_bf16 v[12:15], v[4:7], v[32:35], v[132:135]
	v_mfma_f32_16x16x32_bf16 v[68:71], v[8:11], v[36:39], v[12:15]
	v_mfma_f32_16x16x32_bf16 v[12:15], v[224:227], v[32:35], v[144:147]
	v_mfma_f32_16x16x32_bf16 v[64:67], v[228:231], v[36:39], v[12:15]
	v_mfma_f32_16x16x32_bf16 v[12:15], v[4:7], v[48:51], v[152:155]
	v_mfma_f32_16x16x32_bf16 v[44:47], v[8:11], v[52:55], v[12:15]
	v_mfma_f32_16x16x32_bf16 v[12:15], v[224:227], v[48:51], v[168:171]
	v_mfma_f32_16x16x32_bf16 v[40:43], v[228:231], v[52:55], v[12:15]
	v_mfma_f32_16x16x32_bf16 v[12:15], v[4:7], v[76:79], v[172:175]
	v_mfma_f32_16x16x32_bf16 v[28:31], v[8:11], v[80:83], v[12:15]
	v_mfma_f32_16x16x32_bf16 v[12:15], v[224:227], v[76:79], v[176:179]
	v_mfma_f32_16x16x32_bf16 v[4:7], v[4:7], v[100:103], v[16:19]
	v_mfma_f32_16x16x32_bf16 v[24:27], v[228:231], v[80:83], v[12:15]
	v_mfma_f32_16x16x32_bf16 v[12:15], v[8:11], v[104:107], v[4:7]
	v_mfma_f32_16x16x32_bf16 v[4:7], v[224:227], v[100:103], v[20:23]
	v_mfma_f32_16x16x32_bf16 v[8:11], v[228:231], v[104:107], v[4:7]
	v_mfma_f32_16x16x32_bf16 v[4:7], v[232:235], v[32:35], v[180:183]
	v_mfma_f32_16x16x32_bf16 v[60:63], v[236:239], v[36:39], v[4:7]
	v_mfma_f32_16x16x32_bf16 v[4:7], v[240:243], v[32:35], v[188:191]
	v_mfma_f32_16x16x32_bf16 v[56:59], v[244:247], v[36:39], v[4:7]
	v_mfma_f32_16x16x32_bf16 v[4:7], v[232:235], v[48:51], v[192:195]
	v_mfma_f32_16x16x32_bf16 v[36:39], v[236:239], v[52:55], v[4:7]
	v_mfma_f32_16x16x32_bf16 v[4:7], v[240:243], v[48:51], v[208:211]
	v_mfma_f32_16x16x32_bf16 v[32:35], v[244:247], v[52:55], v[4:7]
	v_mfma_f32_16x16x32_bf16 v[4:7], v[232:235], v[76:79], v[212:215]
	v_mfma_f32_16x16x32_bf16 v[20:23], v[236:239], v[80:83], v[4:7]
	v_mfma_f32_16x16x32_bf16 v[4:7], v[240:243], v[76:79], v[216:219]
	v_mfma_f32_16x16x32_bf16 v[0:3], v[232:235], v[100:103], v[0:3]
	v_mfma_f32_16x16x32_bf16 v[16:19], v[244:247], v[80:83], v[4:7]
	v_mfma_f32_16x16x32_bf16 v[4:7], v[236:239], v[104:107], v[0:3]
	v_mfma_f32_16x16x32_bf16 v[0:3], v[240:243], v[100:103], v[220:223]
	v_mfma_f32_16x16x32_bf16 v[0:3], v[244:247], v[104:107], v[0:3]
	s_barrier
	s_add_u32 s62, s56, 0x100
	s_addc_u32 s63, s57, 0
	s_add_u32 s79, s54, 0x200
	s_addc_u32 s80, s55, 0
	s_mov_b32 s86, 0
	.p2align	6

.LBB0_1776:
	s_ashr_i32 s51, s50, 31
	s_lshl_b64 s[20:21], s[50:51], 18
	s_add_u32 s58, s26, s20
	s_addc_u32 s59, s27, s21
	s_add_u32 s60, s42, 0x180
	s_addc_u32 s61, s43, 0
	s_waitcnt lgkmcnt(0)
	s_and_b64 s[20:21], s[52:53], exec
	s_cselect_b32 s20, s59, s7
	s_cselect_b32 s21, s58, s6
	s_add_u32 s62, s6, 0x180
	s_addc_u32 s63, s7, 0
	s_barrier
	s_waitcnt lgkmcnt(0)
	v_mfma_f32_16x16x32_bf16 v[116:119], v[16:19], v[108:111], 0
	v_mfma_f32_16x16x32_bf16 v[154:157], v[20:23], v[112:115], v[116:119]
	v_mfma_f32_16x16x32_bf16 v[116:119], v[24:27], v[108:111], 0
	v_mfma_f32_16x16x32_bf16 v[158:161], v[28:31], v[112:115], v[116:119]
	v_mfma_f32_16x16x32_bf16 v[116:119], v[16:19], v[100:103], 0
	v_mfma_f32_16x16x32_bf16 v[162:165], v[20:23], v[104:107], v[116:119]
	v_mfma_f32_16x16x32_bf16 v[116:119], v[24:27], v[100:103], 0
	v_mfma_f32_16x16x32_bf16 v[166:169], v[28:31], v[104:107], v[116:119]
	v_mfma_f32_16x16x32_bf16 v[116:119], v[16:19], v[92:95], 0
	v_mfma_f32_16x16x32_bf16 v[16:19], v[16:19], v[60:63], 0
	v_mfma_f32_16x16x32_bf16 v[170:173], v[20:23], v[96:99], v[116:119]
	v_mfma_f32_16x16x32_bf16 v[16:19], v[20:23], v[88:91], v[16:19]
	v_mfma_f32_16x16x32_bf16 v[20:23], v[24:27], v[60:63], 0
	v_mfma_f32_16x16x32_bf16 v[116:119], v[24:27], v[92:95], 0
	v_mfma_f32_16x16x32_bf16 v[20:23], v[28:31], v[88:91], v[20:23]
	v_mfma_f32_16x16x32_bf16 v[174:177], v[28:31], v[96:99], v[116:119]
	v_mfma_f32_16x16x32_bf16 v[24:27], v[0:3], v[108:111], 0
	v_mfma_f32_16x16x32_bf16 v[178:181], v[4:7], v[112:115], v[24:27]
	v_mfma_f32_16x16x32_bf16 v[24:27], v[8:11], v[108:111], 0
	v_mfma_f32_16x16x32_bf16 v[182:185], v[12:15], v[112:115], v[24:27]
	v_mfma_f32_16x16x32_bf16 v[24:27], v[0:3], v[100:103], 0
	v_mfma_f32_16x16x32_bf16 v[186:189], v[4:7], v[104:107], v[24:27]
	v_mfma_f32_16x16x32_bf16 v[24:27], v[8:11], v[100:103], 0
	v_mfma_f32_16x16x32_bf16 v[190:193], v[12:15], v[104:107], v[24:27]
	v_mfma_f32_16x16x32_bf16 v[24:27], v[0:3], v[92:95], 0
	v_mfma_f32_16x16x32_bf16 v[0:3], v[0:3], v[60:63], 0
	v_mfma_f32_16x16x32_bf16 v[194:197], v[4:7], v[96:99], v[24:27]
	v_mfma_f32_16x16x32_bf16 v[24:27], v[8:11], v[92:95], 0
	v_mfma_f32_16x16x32_bf16 v[0:3], v[4:7], v[88:91], v[0:3]
	v_mfma_f32_16x16x32_bf16 v[4:7], v[8:11], v[60:63], 0
	v_mfma_f32_16x16x32_bf16 v[198:201], v[12:15], v[96:99], v[24:27]
	v_mfma_f32_16x16x32_bf16 v[202:205], v[12:15], v[88:91], v[4:7]
	s_barrier
	v_add_u32_e32 v142, s88, v148
	v_add_u32_e32 v153, s89, v148
	s_nop 1
	ds_read_b128 v[4:7], v142
	ds_read_b128 v[8:11], v142 offset:1024
	ds_read_b128 v[206:209], v142 offset:2048
	ds_read_b128 v[210:213], v142 offset:3072
	ds_read_b128 v[214:217], v153
	ds_read_b128 v[218:221], v153 offset:1024
	ds_read_b128 v[222:225], v153 offset:2048
	ds_read_b128 v[226:229], v153 offset:3072
	s_add_u32 s64, s42, 0x70100
	s_addc_u32 s65, s43, 0
	s_mov_b32 m0, s74
	ds_read_b128 v[12:15], v151 offset:32768
	ds_read_b128 v[24:27], v151 offset:33792
	ds_read_b128 v[28:31], v151 offset:34816
	ds_read_b128 v[96:99], v151 offset:35840
	ds_read_b128 v[230:233], v151 offset:36864
	ds_read_b128 v[234:237], v151 offset:37888
	ds_read_b128 v[238:241], v151 offset:38912
	ds_read_b128 v[242:245], v151 offset:39936
	s_nop 0
	global_load_lds_dwordx4 v144, s[64:65]
	s_mov_b32 m0, s75
	s_nop 0
	global_load_lds_dwordx4 v146, s[64:65]
	s_waitcnt vmcnt(8)
	s_waitcnt lgkmcnt(0)
	s_barrier
	s_waitcnt lgkmcnt(0)
	v_mfma_f32_16x16x32_bf16 v[32:35], v[4:7], v[12:15], v[32:35]
	v_mfma_f32_16x16x32_bf16 v[124:127], v[8:11], v[24:27], v[32:35]
	v_mfma_f32_16x16x32_bf16 v[32:35], v[206:209], v[12:15], v[36:39]
	v_mfma_f32_16x16x32_bf16 v[120:123], v[210:213], v[24:27], v[32:35]
	v_mfma_f32_16x16x32_bf16 v[32:35], v[4:7], v[28:31], v[40:43]
	v_mfma_f32_16x16x32_bf16 v[108:111], v[8:11], v[96:99], v[32:35]
	v_mfma_f32_16x16x32_bf16 v[32:35], v[206:209], v[28:31], v[44:47]
	v_mfma_f32_16x16x32_bf16 v[104:107], v[210:213], v[96:99], v[32:35]
	v_mfma_f32_16x16x32_bf16 v[32:35], v[4:7], v[230:233], v[48:51]
	v_mfma_f32_16x16x32_bf16 v[92:95], v[8:11], v[234:237], v[32:35]
	v_mfma_f32_16x16x32_bf16 v[32:35], v[206:209], v[230:233], v[52:55]
	v_mfma_f32_16x16x32_bf16 v[88:91], v[210:213], v[234:237], v[32:35]
	v_mfma_f32_16x16x32_bf16 v[32:35], v[4:7], v[238:241], v[56:59]
	v_mfma_f32_16x16x32_bf16 v[60:63], v[8:11], v[242:245], v[32:35]
	v_mfma_f32_16x16x32_bf16 v[32:35], v[206:209], v[238:241], v[64:67]
	v_mfma_f32_16x16x32_bf16 v[56:59], v[210:213], v[242:245], v[32:35]
	v_mfma_f32_16x16x32_bf16 v[32:35], v[214:217], v[12:15], v[68:71]
	v_mfma_f32_16x16x32_bf16 v[12:15], v[222:225], v[12:15], v[72:75]
	v_mfma_f32_16x16x32_bf16 v[112:115], v[226:229], v[24:27], v[12:15]
	v_mfma_f32_16x16x32_bf16 v[12:15], v[214:217], v[28:31], v[76:79]
	v_mfma_f32_16x16x32_bf16 v[100:103], v[218:221], v[96:99], v[12:15]
	v_mfma_f32_16x16x32_bf16 v[12:15], v[222:225], v[28:31], v[80:83]
	v_mfma_f32_16x16x32_bf16 v[96:99], v[226:229], v[96:99], v[12:15]
	v_mfma_f32_16x16x32_bf16 v[12:15], v[214:217], v[230:233], v[84:87]
	v_mfma_f32_16x16x32_bf16 v[84:87], v[218:221], v[234:237], v[12:15]
	v_mfma_f32_16x16x32_bf16 v[12:15], v[222:225], v[230:233], v[128:131]
	v_mfma_f32_16x16x32_bf16 v[80:83], v[226:229], v[234:237], v[12:15]
	v_mfma_f32_16x16x32_bf16 v[12:15], v[214:217], v[238:241], v[132:135]
	v_mfma_f32_16x16x32_bf16 v[52:55], v[218:221], v[242:245], v[12:15]
	v_mfma_f32_16x16x32_bf16 v[12:15], v[222:225], v[238:241], v[136:139]
	v_mfma_f32_16x16x32_bf16 v[116:119], v[218:221], v[24:27], v[32:35]
	v_mfma_f32_16x16x32_bf16 v[48:51], v[226:229], v[242:245], v[12:15]
	s_barrier
	s_add_i32 s49, s88, s68
	s_mov_b32 m0, s49
	s_add_i32 s51, s49, 0x2000
	ds_read_b128 v[32:35], v151 offset:49152
	ds_read_b128 v[36:39], v151 offset:50176
	ds_read_b128 v[128:131], v151 offset:51200
	ds_read_b128 v[132:135], v151 offset:52224
	ds_read_b128 v[136:139], v151 offset:53248
	ds_read_b128 v[230:233], v151 offset:54272
	ds_read_b128 v[234:237], v151 offset:55296
	ds_read_b128 v[238:241], v151 offset:56320
	s_nop 0
	global_load_lds_dwordx4 v145, s[62:63]
	s_mov_b32 m0, s51
	s_nop 0
	global_load_lds_dwordx4 v147, s[62:63]
	s_add_u32 s62, s6, 0x20180
	s_addc_u32 s63, s7, 0
	s_add_i32 s79, s89, s68
	s_mov_b32 m0, s79
	s_add_i32 s86, s79, 0x2000
	s_nop 0
	global_load_lds_dwordx4 v145, s[62:63]
	s_mov_b32 m0, s86
	s_nop 0
	global_load_lds_dwordx4 v147, s[62:63]
	s_mov_b32 m0, s76
	s_nop 0
	global_load_lds_dwordx4 v144, s[60:61]
	s_mov_b32 m0, s77
	s_nop 0
	global_load_lds_dwordx4 v146, s[60:61]
	s_waitcnt vmcnt(8)
	s_waitcnt lgkmcnt(0)
	s_barrier
	s_waitcnt lgkmcnt(0)
	v_mfma_f32_16x16x32_bf16 v[12:15], v[4:7], v[32:35], v[154:157]
	v_mfma_f32_16x16x32_bf16 v[76:79], v[8:11], v[36:39], v[12:15]
	v_mfma_f32_16x16x32_bf16 v[12:15], v[206:209], v[32:35], v[158:161]
	v_mfma_f32_16x16x32_bf16 v[72:75], v[210:213], v[36:39], v[12:15]
	v_mfma_f32_16x16x32_bf16 v[12:15], v[4:7], v[128:131], v[162:165]
	v_mfma_f32_16x16x32_bf16 v[44:47], v[8:11], v[132:135], v[12:15]
	v_mfma_f32_16x16x32_bf16 v[12:15], v[206:209], v[128:131], v[166:169]
	v_mfma_f32_16x16x32_bf16 v[40:43], v[210:213], v[132:135], v[12:15]
	v_mfma_f32_16x16x32_bf16 v[12:15], v[4:7], v[136:139], v[170:173]
	v_mfma_f32_16x16x32_bf16 v[28:31], v[8:11], v[230:233], v[12:15]
	v_mfma_f32_16x16x32_bf16 v[12:15], v[206:209], v[136:139], v[174:177]
	v_mfma_f32_16x16x32_bf16 v[4:7], v[4:7], v[234:237], v[16:19]
	v_mfma_f32_16x16x32_bf16 v[24:27], v[210:213], v[230:233], v[12:15]
	v_mfma_f32_16x16x32_bf16 v[12:15], v[8:11], v[238:241], v[4:7]
	v_mfma_f32_16x16x32_bf16 v[4:7], v[206:209], v[234:237], v[20:23]
	v_mfma_f32_16x16x32_bf16 v[8:11], v[210:213], v[238:241], v[4:7]
	v_mfma_f32_16x16x32_bf16 v[4:7], v[214:217], v[32:35], v[178:181]
	v_mfma_f32_16x16x32_bf16 v[68:71], v[218:221], v[36:39], v[4:7]
	v_mfma_f32_16x16x32_bf16 v[4:7], v[222:225], v[32:35], v[182:185]
	v_mfma_f32_16x16x32_bf16 v[64:67], v[226:229], v[36:39], v[4:7]
	v_mfma_f32_16x16x32_bf16 v[4:7], v[214:217], v[128:131], v[186:189]
	v_mfma_f32_16x16x32_bf16 v[36:39], v[218:221], v[132:135], v[4:7]
	v_mfma_f32_16x16x32_bf16 v[4:7], v[222:225], v[128:131], v[190:193]
	v_mfma_f32_16x16x32_bf16 v[32:35], v[226:229], v[132:135], v[4:7]
	v_mfma_f32_16x16x32_bf16 v[4:7], v[214:217], v[136:139], v[194:197]
	v_mfma_f32_16x16x32_bf16 v[20:23], v[218:221], v[230:233], v[4:7]
	v_mfma_f32_16x16x32_bf16 v[4:7], v[222:225], v[136:139], v[198:201]
	v_mfma_f32_16x16x32_bf16 v[0:3], v[214:217], v[234:237], v[0:3]
	v_mfma_f32_16x16x32_bf16 v[16:19], v[226:229], v[230:233], v[4:7]
	v_mfma_f32_16x16x32_bf16 v[4:7], v[218:221], v[238:241], v[0:3]
	v_mfma_f32_16x16x32_bf16 v[0:3], v[222:225], v[234:237], v[202:205]
	v_mfma_f32_16x16x32_bf16 v[0:3], v[226:229], v[238:241], v[0:3]
	s_barrier
	s_mov_b32 s93, 0
	s_mov_b64 s[60:61], 0
	.p2align	6

.LBB0_2042:
	s_ashr_i32 s45, s44, 31
	s_lshl_b64 s[20:21], s[44:45], 20
	s_add_u32 s50, s13, s20
	s_addc_u32 s51, s82, s21
	s_and_b64 s[20:21], s[48:49], exec
	s_cselect_b32 s5, s51, s57
	s_cselect_b32 s12, s50, s56
	s_ashr_i32 s47, s46, 31
	s_lshl_b64 s[20:21], s[46:47], 20
	s_add_u32 s52, s24, s20
	s_addc_u32 s53, s25, s21
	s_and_b64 s[20:21], s[48:49], exec
	s_cselect_b32 s20, s53, s55
	s_cselect_b32 s21, s52, s54
	s_add_u32 s58, s56, 0x180
	s_waitcnt lgkmcnt(0)
	s_addc_u32 s59, s57, 0
	s_add_u32 s60, s54, 0x180
	s_addc_u32 s61, s55, 0
	s_barrier
	s_waitcnt lgkmcnt(0)
	v_mfma_f32_16x16x32_bf16 v[128:131], v[16:19], v[116:119], 0
	v_mfma_f32_16x16x32_bf16 v[140:143], v[20:23], v[124:127], v[128:131]
	v_mfma_f32_16x16x32_bf16 v[128:131], v[24:27], v[116:119], 0
	v_mfma_f32_16x16x32_bf16 v[156:159], v[28:31], v[124:127], v[128:131]
	v_mfma_f32_16x16x32_bf16 v[128:131], v[16:19], v[104:107], 0
	v_mfma_f32_16x16x32_bf16 v[160:163], v[20:23], v[112:115], v[128:131]
	v_mfma_f32_16x16x32_bf16 v[128:131], v[24:27], v[104:107], 0
	v_mfma_f32_16x16x32_bf16 v[164:167], v[28:31], v[112:115], v[128:131]
	v_mfma_f32_16x16x32_bf16 v[128:131], v[16:19], v[92:95], 0
	v_mfma_f32_16x16x32_bf16 v[16:19], v[16:19], v[76:79], 0
	v_mfma_f32_16x16x32_bf16 v[168:171], v[20:23], v[100:103], v[128:131]
	v_mfma_f32_16x16x32_bf16 v[16:19], v[20:23], v[80:83], v[16:19]
	v_mfma_f32_16x16x32_bf16 v[20:23], v[24:27], v[76:79], 0
	v_mfma_f32_16x16x32_bf16 v[128:131], v[24:27], v[92:95], 0
	v_mfma_f32_16x16x32_bf16 v[20:23], v[28:31], v[80:83], v[20:23]
	v_mfma_f32_16x16x32_bf16 v[172:175], v[28:31], v[100:103], v[128:131]
	v_mfma_f32_16x16x32_bf16 v[24:27], v[0:3], v[116:119], 0
	v_mfma_f32_16x16x32_bf16 v[176:179], v[4:7], v[124:127], v[24:27]
	v_mfma_f32_16x16x32_bf16 v[24:27], v[8:11], v[116:119], 0
	v_mfma_f32_16x16x32_bf16 v[180:183], v[12:15], v[124:127], v[24:27]
	v_mfma_f32_16x16x32_bf16 v[24:27], v[0:3], v[104:107], 0
	v_mfma_f32_16x16x32_bf16 v[186:189], v[4:7], v[112:115], v[24:27]
	v_mfma_f32_16x16x32_bf16 v[24:27], v[8:11], v[104:107], 0
	v_mfma_f32_16x16x32_bf16 v[190:193], v[12:15], v[112:115], v[24:27]
	v_mfma_f32_16x16x32_bf16 v[24:27], v[0:3], v[92:95], 0
	v_mfma_f32_16x16x32_bf16 v[0:3], v[0:3], v[76:79], 0
	v_mfma_f32_16x16x32_bf16 v[194:197], v[4:7], v[100:103], v[24:27]
	v_mfma_f32_16x16x32_bf16 v[24:27], v[8:11], v[92:95], 0
	v_mfma_f32_16x16x32_bf16 v[0:3], v[4:7], v[80:83], v[0:3]
	v_mfma_f32_16x16x32_bf16 v[4:7], v[8:11], v[76:79], 0
	v_mfma_f32_16x16x32_bf16 v[198:201], v[12:15], v[100:103], v[24:27]
	v_mfma_f32_16x16x32_bf16 v[212:215], v[12:15], v[80:83], v[4:7]
	s_barrier
	v_add_u32_e32 v132, s75, v206
	v_add_u32_e32 v133, s76, v206
	s_nop 1
	ds_read_b128 v[4:7], v132
	ds_read_b128 v[8:11], v132 offset:1024
	ds_read_b128 v[216:219], v132 offset:2048
	ds_read_b128 v[220:223], v132 offset:3072
	ds_read_b128 v[224:227], v133
	ds_read_b128 v[228:231], v133 offset:1024
	ds_read_b128 v[232:235], v133 offset:2048
	ds_read_b128 v[236:239], v133 offset:3072
	s_add_u32 s88, s56, 0x80100
	s_addc_u32 s89, s57, 0
	s_mov_b32 m0, s67
	ds_read_b128 v[12:15], v209 offset:32768
	ds_read_b128 v[24:27], v209 offset:33792
	ds_read_b128 v[28:31], v209 offset:34816
	ds_read_b128 v[92:95], v209 offset:35840
	ds_read_b128 v[240:243], v209 offset:36864
	ds_read_b128 v[244:247], v209 offset:37888
	ds_read_b128 v[248:251], v209 offset:38912
	ds_read_b128 v[32:35], v209 offset:39936
	s_nop 0
	global_load_lds_dwordx4 v202, s[88:89]
	s_mov_b32 m0, s68
	s_nop 0
	global_load_lds_dwordx4 v204, s[88:89]
	s_waitcnt vmcnt(8)
	s_waitcnt lgkmcnt(0)
	s_barrier
	s_waitcnt lgkmcnt(0)
	v_mfma_f32_16x16x32_bf16 v[36:39], v[216:219], v[12:15], v[36:39]
	v_mfma_f32_16x16x32_bf16 v[148:151], v[220:223], v[24:27], v[36:39]
	v_mfma_f32_16x16x32_bf16 v[36:39], v[4:7], v[28:31], v[40:43]
	v_mfma_f32_16x16x32_bf16 v[128:131], v[8:11], v[92:95], v[36:39]
	v_mfma_f32_16x16x32_bf16 v[36:39], v[216:219], v[28:31], v[44:47]
	v_mfma_f32_16x16x32_bf16 v[124:127], v[220:223], v[92:95], v[36:39]
	v_mfma_f32_16x16x32_bf16 v[36:39], v[4:7], v[240:243], v[48:51]
	v_mfma_f32_16x16x32_bf16 v[104:107], v[8:11], v[244:247], v[36:39]
	v_mfma_f32_16x16x32_bf16 v[36:39], v[216:219], v[240:243], v[52:55]
	v_mfma_f32_16x16x32_bf16 v[100:103], v[220:223], v[244:247], v[36:39]
	v_mfma_f32_16x16x32_bf16 v[36:39], v[4:7], v[248:251], v[56:59]
	v_mfma_f32_16x16x32_bf16 v[76:79], v[4:7], v[12:15], v[134:137]
	v_mfma_f32_16x16x32_bf16 v[80:83], v[8:11], v[32:35], v[36:39]
	v_mfma_f32_16x16x32_bf16 v[36:39], v[216:219], v[248:251], v[60:63]
	v_mfma_f32_16x16x32_bf16 v[152:155], v[8:11], v[24:27], v[76:79]
	v_mfma_f32_16x16x32_bf16 v[76:79], v[220:223], v[32:35], v[36:39]
	v_mfma_f32_16x16x32_bf16 v[36:39], v[224:227], v[12:15], v[64:67]
	v_mfma_f32_16x16x32_bf16 v[12:15], v[232:235], v[12:15], v[68:71]
	v_mfma_f32_16x16x32_bf16 v[136:139], v[236:239], v[24:27], v[12:15]
	v_mfma_f32_16x16x32_bf16 v[12:15], v[224:227], v[28:31], v[72:75]
	v_mfma_f32_16x16x32_bf16 v[116:119], v[228:231], v[92:95], v[12:15]
	v_mfma_f32_16x16x32_bf16 v[12:15], v[232:235], v[28:31], v[84:87]
	v_mfma_f32_16x16x32_bf16 v[112:115], v[236:239], v[92:95], v[12:15]
	v_mfma_f32_16x16x32_bf16 v[12:15], v[224:227], v[240:243], v[88:91]
	v_mfma_f32_16x16x32_bf16 v[92:95], v[228:231], v[244:247], v[12:15]
	v_mfma_f32_16x16x32_bf16 v[12:15], v[232:235], v[240:243], v[96:99]
	v_mfma_f32_16x16x32_bf16 v[88:91], v[236:239], v[244:247], v[12:15]
	v_mfma_f32_16x16x32_bf16 v[12:15], v[224:227], v[248:251], v[108:111]
	v_mfma_f32_16x16x32_bf16 v[68:71], v[228:231], v[32:35], v[12:15]
	v_mfma_f32_16x16x32_bf16 v[12:15], v[232:235], v[248:251], v[120:123]
	v_mfma_f32_16x16x32_bf16 v[144:147], v[228:231], v[24:27], v[36:39]
	v_mfma_f32_16x16x32_bf16 v[64:67], v[236:239], v[32:35], v[12:15]
	s_barrier
	s_add_i32 s45, s75, s26
	s_mov_b32 m0, s45
	s_add_i32 s47, s45, 0x2000
	ds_read_b128 v[32:35], v209 offset:49152
	ds_read_b128 v[36:39], v209 offset:50176
	ds_read_b128 v[72:75], v209 offset:51200
	ds_read_b128 v[84:87], v209 offset:52224
	ds_read_b128 v[96:99], v209 offset:53248
	ds_read_b128 v[108:111], v209 offset:54272
	ds_read_b128 v[120:123], v209 offset:55296
	ds_read_b128 v[240:243], v209 offset:56320
	s_nop 0
	global_load_lds_dwordx4 v203, s[60:61]
	s_mov_b32 m0, s47
	s_nop 0
	global_load_lds_dwordx4 v205, s[60:61]
	s_add_u32 s60, s54, 0x80180
	s_addc_u32 s61, s55, 0
	s_add_i32 s79, s76, s26
	s_mov_b32 m0, s79
	s_add_i32 s80, s79, 0x2000
	s_nop 0
	global_load_lds_dwordx4 v203, s[60:61]
	s_mov_b32 m0, s80
	s_nop 0
	global_load_lds_dwordx4 v205, s[60:61]
	s_mov_b32 m0, s69
	s_nop 0
	global_load_lds_dwordx4 v202, s[58:59]
	s_mov_b32 m0, s70
	s_nop 0
	global_load_lds_dwordx4 v204, s[58:59]
	s_waitcnt vmcnt(8)
	s_waitcnt lgkmcnt(0)
	s_barrier
	s_waitcnt lgkmcnt(0)
	v_mfma_f32_16x16x32_bf16 v[12:15], v[4:7], v[32:35], v[140:143]
	v_mfma_f32_16x16x32_bf16 v[60:63], v[8:11], v[36:39], v[12:15]
	v_mfma_f32_16x16x32_bf16 v[12:15], v[216:219], v[32:35], v[156:159]
	v_mfma_f32_16x16x32_bf16 v[56:59], v[220:223], v[36:39], v[12:15]
	v_mfma_f32_16x16x32_bf16 v[12:15], v[4:7], v[72:75], v[160:163]
	v_mfma_f32_16x16x32_bf16 v[44:47], v[8:11], v[84:87], v[12:15]
	v_mfma_f32_16x16x32_bf16 v[12:15], v[216:219], v[72:75], v[164:167]
	v_mfma_f32_16x16x32_bf16 v[40:43], v[220:223], v[84:87], v[12:15]
	v_mfma_f32_16x16x32_bf16 v[12:15], v[4:7], v[96:99], v[168:171]
	v_mfma_f32_16x16x32_bf16 v[28:31], v[8:11], v[108:111], v[12:15]
	v_mfma_f32_16x16x32_bf16 v[12:15], v[216:219], v[96:99], v[172:175]
	v_mfma_f32_16x16x32_bf16 v[4:7], v[4:7], v[120:123], v[16:19]
	v_mfma_f32_16x16x32_bf16 v[24:27], v[220:223], v[108:111], v[12:15]
	v_mfma_f32_16x16x32_bf16 v[12:15], v[8:11], v[240:243], v[4:7]
	v_mfma_f32_16x16x32_bf16 v[4:7], v[216:219], v[120:123], v[20:23]
	v_mfma_f32_16x16x32_bf16 v[8:11], v[220:223], v[240:243], v[4:7]
	v_mfma_f32_16x16x32_bf16 v[4:7], v[224:227], v[32:35], v[176:179]
	v_mfma_f32_16x16x32_bf16 v[52:55], v[228:231], v[36:39], v[4:7]
	v_mfma_f32_16x16x32_bf16 v[4:7], v[232:235], v[32:35], v[180:183]
	v_mfma_f32_16x16x32_bf16 v[48:51], v[236:239], v[36:39], v[4:7]
	v_mfma_f32_16x16x32_bf16 v[4:7], v[224:227], v[72:75], v[186:189]
	v_mfma_f32_16x16x32_bf16 v[36:39], v[228:231], v[84:87], v[4:7]
	v_mfma_f32_16x16x32_bf16 v[4:7], v[232:235], v[72:75], v[190:193]
	v_mfma_f32_16x16x32_bf16 v[32:35], v[236:239], v[84:87], v[4:7]
	v_mfma_f32_16x16x32_bf16 v[4:7], v[224:227], v[96:99], v[194:197]
	v_mfma_f32_16x16x32_bf16 v[20:23], v[228:231], v[108:111], v[4:7]
	v_mfma_f32_16x16x32_bf16 v[4:7], v[232:235], v[96:99], v[198:201]
	v_mfma_f32_16x16x32_bf16 v[0:3], v[224:227], v[120:123], v[0:3]
	v_mfma_f32_16x16x32_bf16 v[16:19], v[236:239], v[108:111], v[4:7]
	v_mfma_f32_16x16x32_bf16 v[4:7], v[228:231], v[240:243], v[0:3]
	v_mfma_f32_16x16x32_bf16 v[0:3], v[232:235], v[120:123], v[212:215]
	v_mfma_f32_16x16x32_bf16 v[0:3], v[236:239], v[240:243], v[0:3]
	s_barrier
	s_add_u32 s83, s56, 0x200
	s_addc_u32 s86, s57, 0
	s_add_u32 s88, s54, 0x200
	s_addc_u32 s89, s55, 0
	s_add_u32 s54, s56, 0x80180
	s_addc_u32 s55, s57, 0
	s_mov_b32 s90, 0
	.p2align	6

.LBB0_2152:
	s_ashr_i32 s7, s6, 31
	s_lshl_b64 s[20:21], s[6:7], 20
	s_add_u32 s46, s14, s20
	s_addc_u32 s47, s15, s21
	s_ashr_i32 s43, s42, 31
	s_lshl_b64 s[20:21], s[42:43], 20
	s_add_u32 s48, s24, s20
	s_addc_u32 s49, s25, s21
	s_add_u32 s58, s56, 0x180
	s_addc_u32 s59, s57, 0
	s_waitcnt lgkmcnt(0)
	s_and_b64 s[20:21], s[44:45], exec
	s_cselect_b32 s20, s49, s55
	s_cselect_b32 s21, s48, s54
	s_cselect_b32 s43, s47, s57
	s_cselect_b32 s79, s46, s56
	s_add_u32 s60, s54, 0x180
	s_addc_u32 s61, s55, 0
	s_barrier
	s_waitcnt lgkmcnt(0)
	v_mfma_f32_16x16x32_bf16 v[116:119], v[16:19], v[108:111], 0
	v_mfma_f32_16x16x32_bf16 v[154:157], v[20:23], v[112:115], v[116:119]
	v_mfma_f32_16x16x32_bf16 v[116:119], v[24:27], v[108:111], 0
	v_mfma_f32_16x16x32_bf16 v[158:161], v[28:31], v[112:115], v[116:119]
	v_mfma_f32_16x16x32_bf16 v[116:119], v[16:19], v[100:103], 0
	v_mfma_f32_16x16x32_bf16 v[162:165], v[20:23], v[104:107], v[116:119]
	v_mfma_f32_16x16x32_bf16 v[116:119], v[24:27], v[100:103], 0
	v_mfma_f32_16x16x32_bf16 v[166:169], v[28:31], v[104:107], v[116:119]
	v_mfma_f32_16x16x32_bf16 v[116:119], v[16:19], v[88:91], 0
	v_mfma_f32_16x16x32_bf16 v[16:19], v[16:19], v[68:71], 0
	v_mfma_f32_16x16x32_bf16 v[170:173], v[20:23], v[96:99], v[116:119]
	v_mfma_f32_16x16x32_bf16 v[116:119], v[24:27], v[88:91], 0
	v_mfma_f32_16x16x32_bf16 v[20:23], v[20:23], v[80:83], v[16:19]
	v_mfma_f32_16x16x32_bf16 v[16:19], v[24:27], v[68:71], 0
	v_mfma_f32_16x16x32_bf16 v[174:177], v[28:31], v[96:99], v[116:119]
	v_mfma_f32_16x16x32_bf16 v[28:31], v[28:31], v[80:83], v[16:19]
	v_mfma_f32_16x16x32_bf16 v[16:19], v[0:3], v[108:111], 0
	v_mfma_f32_16x16x32_bf16 v[178:181], v[4:7], v[112:115], v[16:19]
	v_mfma_f32_16x16x32_bf16 v[16:19], v[8:11], v[108:111], 0
	v_mfma_f32_16x16x32_bf16 v[182:185], v[12:15], v[112:115], v[16:19]
	v_mfma_f32_16x16x32_bf16 v[16:19], v[0:3], v[100:103], 0
	v_mfma_f32_16x16x32_bf16 v[186:189], v[4:7], v[104:107], v[16:19]
	v_mfma_f32_16x16x32_bf16 v[16:19], v[8:11], v[100:103], 0
	v_mfma_f32_16x16x32_bf16 v[190:193], v[12:15], v[104:107], v[16:19]
	v_mfma_f32_16x16x32_bf16 v[16:19], v[0:3], v[88:91], 0
	v_mfma_f32_16x16x32_bf16 v[0:3], v[0:3], v[68:71], 0
	v_mfma_f32_16x16x32_bf16 v[194:197], v[4:7], v[96:99], v[16:19]
	v_mfma_f32_16x16x32_bf16 v[16:19], v[8:11], v[88:91], 0
	v_mfma_f32_16x16x32_bf16 v[4:7], v[4:7], v[80:83], v[0:3]
	v_mfma_f32_16x16x32_bf16 v[0:3], v[8:11], v[68:71], 0
	v_mfma_f32_16x16x32_bf16 v[198:201], v[12:15], v[96:99], v[16:19]
	v_mfma_f32_16x16x32_bf16 v[202:205], v[12:15], v[80:83], v[0:3]
	s_barrier
	v_add_u32_e32 v152, s76, v147
	v_add_u32_e32 v153, s77, v147
	s_nop 1
	ds_read_b128 v[0:3], v152
	ds_read_b128 v[8:11], v152 offset:1024
	ds_read_b128 v[12:15], v152 offset:2048
	ds_read_b128 v[206:209], v152 offset:3072
	ds_read_b128 v[210:213], v153
	ds_read_b128 v[214:217], v153 offset:1024
	ds_read_b128 v[218:221], v153 offset:2048
	ds_read_b128 v[222:225], v153 offset:3072
	s_add_u32 s62, s56, 0x80100
	s_addc_u32 s63, s57, 0
	s_mov_b32 m0, s68
	ds_read_b128 v[16:19], v150 offset:32768
	ds_read_b128 v[24:27], v150 offset:33792
	ds_read_b128 v[100:103], v150 offset:34816
	ds_read_b128 v[226:229], v150 offset:35840
	ds_read_b128 v[230:233], v150 offset:36864
	ds_read_b128 v[234:237], v150 offset:37888
	ds_read_b128 v[238:241], v150 offset:38912
	ds_read_b128 v[242:245], v150 offset:39936
	s_nop 0
	global_load_lds_dwordx4 v143, s[62:63]
	s_mov_b32 m0, s69
	s_nop 0
	global_load_lds_dwordx4 v145, s[62:63]
	s_waitcnt vmcnt(8)
	s_waitcnt lgkmcnt(0)
	s_barrier
	s_waitcnt lgkmcnt(0)
	v_mfma_f32_16x16x32_bf16 v[32:35], v[0:3], v[16:19], v[32:35]
	v_mfma_f32_16x16x32_bf16 v[120:123], v[8:11], v[24:27], v[32:35]
	v_mfma_f32_16x16x32_bf16 v[32:35], v[12:15], v[16:19], v[36:39]
	v_mfma_f32_16x16x32_bf16 v[112:115], v[206:209], v[24:27], v[32:35]
	v_mfma_f32_16x16x32_bf16 v[32:35], v[0:3], v[100:103], v[40:43]
	v_mfma_f32_16x16x32_bf16 v[104:107], v[8:11], v[226:229], v[32:35]
	v_mfma_f32_16x16x32_bf16 v[32:35], v[12:15], v[100:103], v[44:47]
	v_mfma_f32_16x16x32_bf16 v[96:99], v[206:209], v[226:229], v[32:35]
	v_mfma_f32_16x16x32_bf16 v[32:35], v[0:3], v[230:233], v[48:51]
	v_mfma_f32_16x16x32_bf16 v[88:91], v[8:11], v[234:237], v[32:35]
	v_mfma_f32_16x16x32_bf16 v[32:35], v[12:15], v[230:233], v[52:55]
	v_mfma_f32_16x16x32_bf16 v[80:83], v[206:209], v[234:237], v[32:35]
	v_mfma_f32_16x16x32_bf16 v[32:35], v[0:3], v[238:241], v[56:59]
	v_mfma_f32_16x16x32_bf16 v[68:71], v[8:11], v[242:245], v[32:35]
	v_mfma_f32_16x16x32_bf16 v[32:35], v[12:15], v[238:241], v[60:63]
	v_mfma_f32_16x16x32_bf16 v[52:55], v[206:209], v[242:245], v[32:35]
	v_mfma_f32_16x16x32_bf16 v[32:35], v[210:213], v[16:19], v[64:67]
	v_mfma_f32_16x16x32_bf16 v[16:19], v[218:221], v[16:19], v[72:75]
	v_mfma_f32_16x16x32_bf16 v[116:119], v[222:225], v[24:27], v[16:19]
	v_mfma_f32_16x16x32_bf16 v[16:19], v[210:213], v[100:103], v[76:79]
	v_mfma_f32_16x16x32_bf16 v[108:111], v[214:217], v[226:229], v[16:19]
	v_mfma_f32_16x16x32_bf16 v[16:19], v[218:221], v[100:103], v[84:87]
	v_mfma_f32_16x16x32_bf16 v[100:103], v[222:225], v[226:229], v[16:19]
	v_mfma_f32_16x16x32_bf16 v[16:19], v[210:213], v[230:233], v[92:95]
	v_mfma_f32_16x16x32_bf16 v[92:95], v[214:217], v[234:237], v[16:19]
	v_mfma_f32_16x16x32_bf16 v[16:19], v[218:221], v[230:233], v[128:131]
	v_mfma_f32_16x16x32_bf16 v[84:87], v[222:225], v[234:237], v[16:19]
	v_mfma_f32_16x16x32_bf16 v[16:19], v[210:213], v[238:241], v[132:135]
	v_mfma_f32_16x16x32_bf16 v[76:79], v[214:217], v[242:245], v[16:19]
	v_mfma_f32_16x16x32_bf16 v[16:19], v[218:221], v[238:241], v[136:139]
	v_mfma_f32_16x16x32_bf16 v[124:127], v[214:217], v[24:27], v[32:35]
	v_mfma_f32_16x16x32_bf16 v[60:63], v[222:225], v[242:245], v[16:19]
	s_barrier
	s_add_i32 s80, s76, s26
	s_mov_b32 m0, s80
	s_add_i32 s86, s80, 0x2000
	ds_read_b128 v[36:39], v150 offset:49152
	ds_read_b128 v[44:47], v150 offset:50176
	ds_read_b128 v[128:131], v150 offset:51200
	ds_read_b128 v[132:135], v150 offset:52224
	ds_read_b128 v[136:139], v150 offset:53248
	ds_read_b128 v[226:229], v150 offset:54272
	ds_read_b128 v[230:233], v150 offset:55296
	ds_read_b128 v[234:237], v150 offset:56320
	s_nop 0
	global_load_lds_dwordx4 v144, s[60:61]
	s_mov_b32 m0, s86
	s_nop 0
	global_load_lds_dwordx4 v146, s[60:61]
	s_add_u32 s60, s54, 0x80180
	s_addc_u32 s61, s55, 0
	s_add_i32 s89, s77, s26
	s_mov_b32 m0, s89
	s_add_i32 s90, s89, 0x2000
	s_nop 0
	global_load_lds_dwordx4 v144, s[60:61]
	s_mov_b32 m0, s90
	s_nop 0
	global_load_lds_dwordx4 v146, s[60:61]
	s_mov_b32 m0, s70
	s_nop 0
	global_load_lds_dwordx4 v143, s[58:59]
	s_mov_b32 m0, s71
	s_nop 0
	global_load_lds_dwordx4 v145, s[58:59]
	s_waitcnt vmcnt(8)
	s_waitcnt lgkmcnt(0)
	s_barrier
	s_waitcnt lgkmcnt(0)
	v_mfma_f32_16x16x32_bf16 v[16:19], v[0:3], v[36:39], v[154:157]
	v_mfma_f32_16x16x32_bf16 v[64:67], v[8:11], v[44:47], v[16:19]
	v_mfma_f32_16x16x32_bf16 v[16:19], v[12:15], v[36:39], v[158:161]
	v_mfma_f32_16x16x32_bf16 v[48:51], v[206:209], v[44:47], v[16:19]
	v_mfma_f32_16x16x32_bf16 v[16:19], v[0:3], v[128:131], v[162:165]
	v_mfma_f32_16x16x32_bf16 v[40:43], v[8:11], v[132:135], v[16:19]
	v_mfma_f32_16x16x32_bf16 v[16:19], v[12:15], v[128:131], v[166:169]
	v_mfma_f32_16x16x32_bf16 v[32:35], v[206:209], v[132:135], v[16:19]
	v_mfma_f32_16x16x32_bf16 v[16:19], v[0:3], v[136:139], v[170:173]
	v_mfma_f32_16x16x32_bf16 v[0:3], v[0:3], v[230:233], v[20:23]
	v_mfma_f32_16x16x32_bf16 v[24:27], v[8:11], v[226:229], v[16:19]
	v_mfma_f32_16x16x32_bf16 v[16:19], v[12:15], v[136:139], v[174:177]
	v_mfma_f32_16x16x32_bf16 v[8:11], v[8:11], v[234:237], v[0:3]
	v_mfma_f32_16x16x32_bf16 v[0:3], v[12:15], v[230:233], v[28:31]
	v_mfma_f32_16x16x32_bf16 v[16:19], v[206:209], v[226:229], v[16:19]
	v_mfma_f32_16x16x32_bf16 v[0:3], v[206:209], v[234:237], v[0:3]
	v_mfma_f32_16x16x32_bf16 v[12:15], v[210:213], v[36:39], v[178:181]
	v_mfma_f32_16x16x32_bf16 v[72:75], v[214:217], v[44:47], v[12:15]
	v_mfma_f32_16x16x32_bf16 v[12:15], v[218:221], v[36:39], v[182:185]
	v_mfma_f32_16x16x32_bf16 v[56:59], v[222:225], v[44:47], v[12:15]
	v_mfma_f32_16x16x32_bf16 v[12:15], v[210:213], v[128:131], v[186:189]
	v_mfma_f32_16x16x32_bf16 v[44:47], v[214:217], v[132:135], v[12:15]
	v_mfma_f32_16x16x32_bf16 v[12:15], v[218:221], v[128:131], v[190:193]
	v_mfma_f32_16x16x32_bf16 v[36:39], v[222:225], v[132:135], v[12:15]
	v_mfma_f32_16x16x32_bf16 v[12:15], v[210:213], v[136:139], v[194:197]
	v_mfma_f32_16x16x32_bf16 v[28:31], v[214:217], v[226:229], v[12:15]
	v_mfma_f32_16x16x32_bf16 v[12:15], v[218:221], v[136:139], v[198:201]
	v_mfma_f32_16x16x32_bf16 v[4:7], v[210:213], v[230:233], v[4:7]
	v_mfma_f32_16x16x32_bf16 v[20:23], v[222:225], v[226:229], v[12:15]
	v_mfma_f32_16x16x32_bf16 v[12:15], v[214:217], v[234:237], v[4:7]
	v_mfma_f32_16x16x32_bf16 v[4:7], v[218:221], v[230:233], v[202:205]
	v_mfma_f32_16x16x32_bf16 v[4:7], v[222:225], v[234:237], v[4:7]
	s_barrier
	s_add_u32 s62, s56, 0x100
	s_addc_u32 s63, s57, 0
	s_add_u32 s91, s54, 0x200
	s_addc_u32 s92, s55, 0
	s_mov_b32 s93, 0
	.p2align	6

.LBB0_2250:
	s_add_u32 s52, s50, 0x180
	s_waitcnt lgkmcnt(0)
	s_addc_u32 s53, s51, 0
	s_add_u32 s54, s4, 0x180
	s_addc_u32 s55, s5, 0
	s_barrier
	s_waitcnt lgkmcnt(0)
	v_mfma_f32_16x16x32_bf16 v[128:131], v[16:19], v[116:119], 0
	v_mfma_f32_16x16x32_bf16 v[140:143], v[20:23], v[124:127], v[128:131]
	v_mfma_f32_16x16x32_bf16 v[128:131], v[24:27], v[116:119], 0
	v_mfma_f32_16x16x32_bf16 v[156:159], v[28:31], v[124:127], v[128:131]
	v_mfma_f32_16x16x32_bf16 v[128:131], v[16:19], v[104:107], 0
	v_mfma_f32_16x16x32_bf16 v[160:163], v[20:23], v[112:115], v[128:131]
	v_mfma_f32_16x16x32_bf16 v[128:131], v[24:27], v[104:107], 0
	v_mfma_f32_16x16x32_bf16 v[164:167], v[28:31], v[112:115], v[128:131]
	v_mfma_f32_16x16x32_bf16 v[128:131], v[16:19], v[92:95], 0
	v_mfma_f32_16x16x32_bf16 v[16:19], v[16:19], v[76:79], 0
	v_mfma_f32_16x16x32_bf16 v[168:171], v[20:23], v[100:103], v[128:131]
	v_mfma_f32_16x16x32_bf16 v[16:19], v[20:23], v[80:83], v[16:19]
	v_mfma_f32_16x16x32_bf16 v[20:23], v[24:27], v[76:79], 0
	v_mfma_f32_16x16x32_bf16 v[128:131], v[24:27], v[92:95], 0
	v_mfma_f32_16x16x32_bf16 v[20:23], v[28:31], v[80:83], v[20:23]
	v_mfma_f32_16x16x32_bf16 v[172:175], v[28:31], v[100:103], v[128:131]
	v_mfma_f32_16x16x32_bf16 v[24:27], v[0:3], v[116:119], 0
	v_mfma_f32_16x16x32_bf16 v[176:179], v[4:7], v[124:127], v[24:27]
	v_mfma_f32_16x16x32_bf16 v[24:27], v[8:11], v[116:119], 0
	v_mfma_f32_16x16x32_bf16 v[180:183], v[12:15], v[124:127], v[24:27]
	v_mfma_f32_16x16x32_bf16 v[24:27], v[0:3], v[104:107], 0
	v_mfma_f32_16x16x32_bf16 v[186:189], v[4:7], v[112:115], v[24:27]
	v_mfma_f32_16x16x32_bf16 v[24:27], v[8:11], v[104:107], 0
	v_mfma_f32_16x16x32_bf16 v[190:193], v[12:15], v[112:115], v[24:27]
	v_mfma_f32_16x16x32_bf16 v[24:27], v[0:3], v[92:95], 0
	v_mfma_f32_16x16x32_bf16 v[0:3], v[0:3], v[76:79], 0
	v_mfma_f32_16x16x32_bf16 v[194:197], v[4:7], v[100:103], v[24:27]
	v_mfma_f32_16x16x32_bf16 v[24:27], v[8:11], v[92:95], 0
	v_mfma_f32_16x16x32_bf16 v[0:3], v[4:7], v[80:83], v[0:3]
	v_mfma_f32_16x16x32_bf16 v[4:7], v[8:11], v[76:79], 0
	v_mfma_f32_16x16x32_bf16 v[198:201], v[12:15], v[100:103], v[24:27]
	v_mfma_f32_16x16x32_bf16 v[212:215], v[12:15], v[80:83], v[4:7]
	s_barrier
	v_add_u32_e32 v132, s69, v206
	v_add_u32_e32 v133, s70, v206
	s_nop 1
	ds_read_b128 v[4:7], v132
	ds_read_b128 v[8:11], v132 offset:1024
	ds_read_b128 v[216:219], v132 offset:2048
	ds_read_b128 v[220:223], v132 offset:3072
	ds_read_b128 v[224:227], v133
	ds_read_b128 v[228:231], v133 offset:1024
	ds_read_b128 v[232:235], v133 offset:2048
	ds_read_b128 v[236:239], v133 offset:3072
	s_add_u32 s20, s50, 0x160100
	s_addc_u32 s21, s51, 0
	s_mov_b32 m0, s61
	ds_read_b128 v[12:15], v209 offset:32768
	ds_read_b128 v[24:27], v209 offset:33792
	ds_read_b128 v[28:31], v209 offset:34816
	ds_read_b128 v[92:95], v209 offset:35840
	ds_read_b128 v[240:243], v209 offset:36864
	ds_read_b128 v[244:247], v209 offset:37888
	ds_read_b128 v[248:251], v209 offset:38912
	ds_read_b128 v[32:35], v209 offset:39936
	s_nop 0
	global_load_lds_dwordx4 v202, s[20:21]
	s_mov_b32 m0, s62
	s_nop 0
	global_load_lds_dwordx4 v204, s[20:21]
	s_waitcnt vmcnt(8)
	s_waitcnt lgkmcnt(0)
	s_barrier
	s_waitcnt lgkmcnt(0)
	v_mfma_f32_16x16x32_bf16 v[36:39], v[216:219], v[12:15], v[36:39]
	v_mfma_f32_16x16x32_bf16 v[148:151], v[220:223], v[24:27], v[36:39]
	v_mfma_f32_16x16x32_bf16 v[36:39], v[4:7], v[28:31], v[40:43]
	v_mfma_f32_16x16x32_bf16 v[128:131], v[8:11], v[92:95], v[36:39]
	v_mfma_f32_16x16x32_bf16 v[36:39], v[216:219], v[28:31], v[44:47]
	v_mfma_f32_16x16x32_bf16 v[124:127], v[220:223], v[92:95], v[36:39]
	v_mfma_f32_16x16x32_bf16 v[36:39], v[4:7], v[240:243], v[48:51]
	v_mfma_f32_16x16x32_bf16 v[104:107], v[8:11], v[244:247], v[36:39]
	v_mfma_f32_16x16x32_bf16 v[36:39], v[216:219], v[240:243], v[52:55]
	v_mfma_f32_16x16x32_bf16 v[100:103], v[220:223], v[244:247], v[36:39]
	v_mfma_f32_16x16x32_bf16 v[36:39], v[4:7], v[248:251], v[56:59]
	v_mfma_f32_16x16x32_bf16 v[76:79], v[4:7], v[12:15], v[134:137]
	v_mfma_f32_16x16x32_bf16 v[80:83], v[8:11], v[32:35], v[36:39]
	v_mfma_f32_16x16x32_bf16 v[36:39], v[216:219], v[248:251], v[60:63]
	v_mfma_f32_16x16x32_bf16 v[152:155], v[8:11], v[24:27], v[76:79]
	v_mfma_f32_16x16x32_bf16 v[76:79], v[220:223], v[32:35], v[36:39]
	v_mfma_f32_16x16x32_bf16 v[36:39], v[224:227], v[12:15], v[64:67]
	v_mfma_f32_16x16x32_bf16 v[12:15], v[232:235], v[12:15], v[68:71]
	v_mfma_f32_16x16x32_bf16 v[136:139], v[236:239], v[24:27], v[12:15]
	v_mfma_f32_16x16x32_bf16 v[12:15], v[224:227], v[28:31], v[72:75]
	v_mfma_f32_16x16x32_bf16 v[116:119], v[228:231], v[92:95], v[12:15]
	v_mfma_f32_16x16x32_bf16 v[12:15], v[232:235], v[28:31], v[84:87]
	v_mfma_f32_16x16x32_bf16 v[112:115], v[236:239], v[92:95], v[12:15]
	v_mfma_f32_16x16x32_bf16 v[12:15], v[224:227], v[240:243], v[88:91]
	v_mfma_f32_16x16x32_bf16 v[92:95], v[228:231], v[244:247], v[12:15]
	v_mfma_f32_16x16x32_bf16 v[12:15], v[232:235], v[240:243], v[96:99]
	v_mfma_f32_16x16x32_bf16 v[88:91], v[236:239], v[244:247], v[12:15]
	v_mfma_f32_16x16x32_bf16 v[12:15], v[224:227], v[248:251], v[108:111]
	v_mfma_f32_16x16x32_bf16 v[68:71], v[228:231], v[32:35], v[12:15]
	v_mfma_f32_16x16x32_bf16 v[12:15], v[232:235], v[248:251], v[120:123]
	v_mfma_f32_16x16x32_bf16 v[144:147], v[228:231], v[24:27], v[36:39]
	v_mfma_f32_16x16x32_bf16 v[64:67], v[236:239], v[32:35], v[12:15]
	s_barrier
	s_add_i32 s20, s69, s26
	s_mov_b32 m0, s20
	s_add_i32 s21, s20, 0x2000
	ds_read_b128 v[32:35], v209 offset:49152
	ds_read_b128 v[36:39], v209 offset:50176
	ds_read_b128 v[72:75], v209 offset:51200
	ds_read_b128 v[84:87], v209 offset:52224
	ds_read_b128 v[96:99], v209 offset:53248
	ds_read_b128 v[108:111], v209 offset:54272
	ds_read_b128 v[120:123], v209 offset:55296
	ds_read_b128 v[240:243], v209 offset:56320
	s_nop 0
	global_load_lds_dwordx4 v203, s[54:55]
	s_mov_b32 m0, s21
	s_nop 0
	global_load_lds_dwordx4 v205, s[54:55]
	s_add_u32 s54, s4, 0x160180
	s_addc_u32 s55, s5, 0
	s_add_i32 s75, s70, s26
	s_mov_b32 m0, s75
	s_add_i32 s76, s75, 0x2000
	s_nop 0
	global_load_lds_dwordx4 v203, s[54:55]
	s_mov_b32 m0, s76
	s_nop 0
	global_load_lds_dwordx4 v205, s[54:55]
	s_mov_b32 m0, s63
	s_nop 0
	global_load_lds_dwordx4 v202, s[52:53]
	s_mov_b32 m0, s64
	s_nop 0
	global_load_lds_dwordx4 v204, s[52:53]
	s_waitcnt vmcnt(8)
	s_waitcnt lgkmcnt(0)
	s_barrier
	s_waitcnt lgkmcnt(0)
	v_mfma_f32_16x16x32_bf16 v[12:15], v[4:7], v[32:35], v[140:143]
	v_mfma_f32_16x16x32_bf16 v[60:63], v[8:11], v[36:39], v[12:15]
	v_mfma_f32_16x16x32_bf16 v[12:15], v[216:219], v[32:35], v[156:159]
	v_mfma_f32_16x16x32_bf16 v[56:59], v[220:223], v[36:39], v[12:15]
	v_mfma_f32_16x16x32_bf16 v[12:15], v[4:7], v[72:75], v[160:163]
	v_mfma_f32_16x16x32_bf16 v[44:47], v[8:11], v[84:87], v[12:15]
	v_mfma_f32_16x16x32_bf16 v[12:15], v[216:219], v[72:75], v[164:167]
	v_mfma_f32_16x16x32_bf16 v[40:43], v[220:223], v[84:87], v[12:15]
	v_mfma_f32_16x16x32_bf16 v[12:15], v[4:7], v[96:99], v[168:171]
	v_mfma_f32_16x16x32_bf16 v[28:31], v[8:11], v[108:111], v[12:15]
	v_mfma_f32_16x16x32_bf16 v[12:15], v[216:219], v[96:99], v[172:175]
	v_mfma_f32_16x16x32_bf16 v[4:7], v[4:7], v[120:123], v[16:19]
	v_mfma_f32_16x16x32_bf16 v[24:27], v[220:223], v[108:111], v[12:15]
	v_mfma_f32_16x16x32_bf16 v[12:15], v[8:11], v[240:243], v[4:7]
	v_mfma_f32_16x16x32_bf16 v[4:7], v[216:219], v[120:123], v[20:23]
	v_mfma_f32_16x16x32_bf16 v[8:11], v[220:223], v[240:243], v[4:7]
	v_mfma_f32_16x16x32_bf16 v[4:7], v[224:227], v[32:35], v[176:179]
	v_mfma_f32_16x16x32_bf16 v[52:55], v[228:231], v[36:39], v[4:7]
	v_mfma_f32_16x16x32_bf16 v[4:7], v[232:235], v[32:35], v[180:183]
	v_mfma_f32_16x16x32_bf16 v[48:51], v[236:239], v[36:39], v[4:7]
	v_mfma_f32_16x16x32_bf16 v[4:7], v[224:227], v[72:75], v[186:189]
	v_mfma_f32_16x16x32_bf16 v[36:39], v[228:231], v[84:87], v[4:7]
	v_mfma_f32_16x16x32_bf16 v[4:7], v[232:235], v[72:75], v[190:193]
	v_mfma_f32_16x16x32_bf16 v[32:35], v[236:239], v[84:87], v[4:7]
	v_mfma_f32_16x16x32_bf16 v[4:7], v[224:227], v[96:99], v[194:197]
	v_mfma_f32_16x16x32_bf16 v[20:23], v[228:231], v[108:111], v[4:7]
	v_mfma_f32_16x16x32_bf16 v[4:7], v[232:235], v[96:99], v[198:201]
	v_mfma_f32_16x16x32_bf16 v[0:3], v[224:227], v[120:123], v[0:3]
	v_mfma_f32_16x16x32_bf16 v[16:19], v[236:239], v[108:111], v[4:7]
	v_mfma_f32_16x16x32_bf16 v[4:7], v[228:231], v[240:243], v[0:3]
	v_mfma_f32_16x16x32_bf16 v[0:3], v[232:235], v[120:123], v[212:215]
	v_mfma_f32_16x16x32_bf16 v[0:3], v[236:239], v[240:243], v[0:3]
	s_barrier
	s_add_u32 s77, s50, 0x200
	s_addc_u32 s78, s51, 0
	s_add_u32 s79, s4, 0x200
	s_addc_u32 s80, s5, 0
	s_add_u32 s4, s50, 0x160180
	s_addc_u32 s5, s51, 0
	s_mov_b32 s83, 0
	.p2align	6

.LBB0_2364:
	s_ashr_i32 s7, s6, 31
	s_lshl_b64 s[20:21], s[6:7], 20
	s_add_u32 s46, s14, s20
	s_addc_u32 s47, s15, s21
	s_ashr_i32 s43, s42, 31
	s_lshl_b64 s[20:21], s[42:43], 20
	s_add_u32 s48, s24, s20
	s_addc_u32 s49, s25, s21
	s_add_u32 s58, s56, 0x180
	s_addc_u32 s59, s57, 0
	s_waitcnt lgkmcnt(0)
	s_and_b64 s[20:21], s[44:45], exec
	s_cselect_b32 s20, s49, s55
	s_cselect_b32 s21, s48, s54
	s_cselect_b32 s43, s47, s57
	s_cselect_b32 s51, s46, s56
	s_add_u32 s60, s54, 0x180
	s_addc_u32 s61, s55, 0
	s_barrier
	s_waitcnt lgkmcnt(0)
	v_mfma_f32_16x16x32_bf16 v[112:115], v[16:19], v[104:107], 0
	v_mfma_f32_16x16x32_bf16 v[166:169], v[20:23], v[108:111], v[112:115]
	v_mfma_f32_16x16x32_bf16 v[112:115], v[24:27], v[104:107], 0
	v_mfma_f32_16x16x32_bf16 v[170:173], v[28:31], v[108:111], v[112:115]
	v_mfma_f32_16x16x32_bf16 v[112:115], v[16:19], v[96:99], 0
	v_mfma_f32_16x16x32_bf16 v[174:177], v[20:23], v[100:103], v[112:115]
	v_mfma_f32_16x16x32_bf16 v[112:115], v[24:27], v[96:99], 0
	v_mfma_f32_16x16x32_bf16 v[178:181], v[28:31], v[100:103], v[112:115]
	v_mfma_f32_16x16x32_bf16 v[112:115], v[16:19], v[88:91], 0
	v_mfma_f32_16x16x32_bf16 v[16:19], v[16:19], v[72:75], 0
	v_mfma_f32_16x16x32_bf16 v[182:185], v[20:23], v[92:95], v[112:115]
	v_mfma_f32_16x16x32_bf16 v[16:19], v[20:23], v[76:79], v[16:19]
	v_mfma_f32_16x16x32_bf16 v[20:23], v[24:27], v[72:75], 0
	v_mfma_f32_16x16x32_bf16 v[112:115], v[24:27], v[88:91], 0
	v_mfma_f32_16x16x32_bf16 v[20:23], v[28:31], v[76:79], v[20:23]
	v_mfma_f32_16x16x32_bf16 v[186:189], v[28:31], v[92:95], v[112:115]
	v_mfma_f32_16x16x32_bf16 v[24:27], v[0:3], v[104:107], 0
	v_mfma_f32_16x16x32_bf16 v[190:193], v[4:7], v[108:111], v[24:27]
	v_mfma_f32_16x16x32_bf16 v[24:27], v[8:11], v[104:107], 0
	v_mfma_f32_16x16x32_bf16 v[194:197], v[12:15], v[108:111], v[24:27]
	v_mfma_f32_16x16x32_bf16 v[24:27], v[0:3], v[96:99], 0
	v_mfma_f32_16x16x32_bf16 v[198:201], v[4:7], v[100:103], v[24:27]
	v_mfma_f32_16x16x32_bf16 v[24:27], v[8:11], v[96:99], 0
	v_mfma_f32_16x16x32_bf16 v[202:205], v[12:15], v[100:103], v[24:27]
	v_mfma_f32_16x16x32_bf16 v[24:27], v[0:3], v[88:91], 0
	v_mfma_f32_16x16x32_bf16 v[0:3], v[0:3], v[72:75], 0
	v_mfma_f32_16x16x32_bf16 v[206:209], v[4:7], v[92:95], v[24:27]
	v_mfma_f32_16x16x32_bf16 v[24:27], v[8:11], v[88:91], 0
	v_mfma_f32_16x16x32_bf16 v[0:3], v[4:7], v[76:79], v[0:3]
	v_mfma_f32_16x16x32_bf16 v[4:7], v[8:11], v[72:75], 0
	v_mfma_f32_16x16x32_bf16 v[210:213], v[12:15], v[92:95], v[24:27]
	v_mfma_f32_16x16x32_bf16 v[214:217], v[12:15], v[76:79], v[4:7]
	s_barrier
	v_add_u32_e32 v144, s78, v159
	v_add_u32_e32 v148, s83, v159
	s_nop 1
	ds_read_b128 v[4:7], v144
	ds_read_b128 v[8:11], v144 offset:1024
	ds_read_b128 v[218:221], v144 offset:2048
	ds_read_b128 v[222:225], v144 offset:3072
	ds_read_b128 v[226:229], v148
	ds_read_b128 v[230:233], v148 offset:1024
	ds_read_b128 v[234:237], v148 offset:2048
	ds_read_b128 v[238:241], v148 offset:3072
	s_add_u32 s62, s56, 0x80100
	s_addc_u32 s63, s57, 0
	s_mov_b32 m0, s70
	ds_read_b128 v[12:15], v162 offset:32768
	ds_read_b128 v[24:27], v162 offset:33792
	ds_read_b128 v[28:31], v162 offset:34816
	ds_read_b128 v[96:99], v162 offset:35840
	ds_read_b128 v[242:245], v162 offset:36864
	ds_read_b128 v[246:249], v162 offset:37888
	ds_read_b128 v[250:253], v162 offset:38912
	ds_read_b128 v[32:35], v162 offset:39936
	s_nop 0
	global_load_lds_dwordx4 v153, s[62:63]
	s_mov_b32 m0, s71
	s_nop 0
	global_load_lds_dwordx4 v157, s[62:63]
	s_waitcnt vmcnt(8)
	s_waitcnt lgkmcnt(0)
	s_barrier
	s_waitcnt lgkmcnt(0)
	v_mfma_f32_16x16x32_bf16 v[36:39], v[218:221], v[12:15], v[36:39]
	v_mfma_f32_16x16x32_bf16 v[120:123], v[222:225], v[24:27], v[36:39]
	v_mfma_f32_16x16x32_bf16 v[36:39], v[4:7], v[28:31], v[40:43]
	v_mfma_f32_16x16x32_bf16 v[108:111], v[8:11], v[96:99], v[36:39]
	v_mfma_f32_16x16x32_bf16 v[36:39], v[218:221], v[28:31], v[44:47]
	v_mfma_f32_16x16x32_bf16 v[104:107], v[222:225], v[96:99], v[36:39]
	v_mfma_f32_16x16x32_bf16 v[36:39], v[4:7], v[242:245], v[48:51]
	v_mfma_f32_16x16x32_bf16 v[92:95], v[8:11], v[246:249], v[36:39]
	v_mfma_f32_16x16x32_bf16 v[36:39], v[218:221], v[242:245], v[52:55]
	v_mfma_f32_16x16x32_bf16 v[88:91], v[222:225], v[246:249], v[36:39]
	v_mfma_f32_16x16x32_bf16 v[36:39], v[4:7], v[250:253], v[56:59]
	v_mfma_f32_16x16x32_bf16 v[72:75], v[4:7], v[12:15], v[116:119]
	v_mfma_f32_16x16x32_bf16 v[76:79], v[8:11], v[32:35], v[36:39]
	v_mfma_f32_16x16x32_bf16 v[36:39], v[218:221], v[250:253], v[60:63]
	v_mfma_f32_16x16x32_bf16 v[124:127], v[8:11], v[24:27], v[72:75]
	v_mfma_f32_16x16x32_bf16 v[72:75], v[222:225], v[32:35], v[36:39]
	v_mfma_f32_16x16x32_bf16 v[36:39], v[226:229], v[12:15], v[64:67]
	v_mfma_f32_16x16x32_bf16 v[12:15], v[234:237], v[12:15], v[68:71]
	v_mfma_f32_16x16x32_bf16 v[112:115], v[238:241], v[24:27], v[12:15]
	v_mfma_f32_16x16x32_bf16 v[12:15], v[226:229], v[28:31], v[80:83]
	v_mfma_f32_16x16x32_bf16 v[100:103], v[230:233], v[96:99], v[12:15]
	v_mfma_f32_16x16x32_bf16 v[12:15], v[234:237], v[28:31], v[84:87]
	v_mfma_f32_16x16x32_bf16 v[96:99], v[238:241], v[96:99], v[12:15]
	v_mfma_f32_16x16x32_bf16 v[12:15], v[226:229], v[242:245], v[128:131]
	v_mfma_f32_16x16x32_bf16 v[84:87], v[230:233], v[246:249], v[12:15]
	v_mfma_f32_16x16x32_bf16 v[12:15], v[234:237], v[242:245], v[132:135]
	v_mfma_f32_16x16x32_bf16 v[80:83], v[238:241], v[246:249], v[12:15]
	v_mfma_f32_16x16x32_bf16 v[12:15], v[226:229], v[250:253], v[136:139]
	v_mfma_f32_16x16x32_bf16 v[68:71], v[230:233], v[32:35], v[12:15]
	v_mfma_f32_16x16x32_bf16 v[12:15], v[234:237], v[250:253], v[140:143]
	v_mfma_f32_16x16x32_bf16 v[116:119], v[230:233], v[24:27], v[36:39]
	v_mfma_f32_16x16x32_bf16 v[60:63], v[238:241], v[32:35], v[12:15]
	s_barrier
	s_add_i32 s53, s78, s26
	s_mov_b32 m0, s53
	s_add_i32 s79, s53, 0x2000
	ds_read_b128 v[32:35], v162 offset:49152
	ds_read_b128 v[36:39], v162 offset:50176
	ds_read_b128 v[128:131], v162 offset:51200
	ds_read_b128 v[132:135], v162 offset:52224
	ds_read_b128 v[136:139], v162 offset:53248
	ds_read_b128 v[140:143], v162 offset:54272
	ds_read_b128 v[242:245], v162 offset:55296
	ds_read_b128 v[246:249], v162 offset:56320
	s_nop 0
	global_load_lds_dwordx4 v156, s[60:61]
	s_mov_b32 m0, s79
	s_nop 0
	global_load_lds_dwordx4 v158, s[60:61]
	s_add_u32 s60, s54, 0x80180
	s_addc_u32 s61, s55, 0
	s_add_i32 s80, s83, s26
	s_mov_b32 m0, s80
	s_add_i32 s86, s80, 0x2000
	s_nop 0
	global_load_lds_dwordx4 v156, s[60:61]
	s_mov_b32 m0, s86
	s_nop 0
	global_load_lds_dwordx4 v158, s[60:61]
	s_mov_b32 m0, s72
	s_nop 0
	global_load_lds_dwordx4 v153, s[58:59]
	s_mov_b32 m0, s73
	s_nop 0
	global_load_lds_dwordx4 v157, s[58:59]
	s_waitcnt vmcnt(8)
	s_waitcnt lgkmcnt(0)
	s_barrier
	s_waitcnt lgkmcnt(0)
	v_mfma_f32_16x16x32_bf16 v[12:15], v[4:7], v[32:35], v[166:169]
	v_mfma_f32_16x16x32_bf16 v[64:67], v[8:11], v[36:39], v[12:15]
	v_mfma_f32_16x16x32_bf16 v[12:15], v[218:221], v[32:35], v[170:173]
	v_mfma_f32_16x16x32_bf16 v[56:59], v[222:225], v[36:39], v[12:15]
	v_mfma_f32_16x16x32_bf16 v[12:15], v[4:7], v[128:131], v[174:177]
	v_mfma_f32_16x16x32_bf16 v[44:47], v[8:11], v[132:135], v[12:15]
	v_mfma_f32_16x16x32_bf16 v[12:15], v[218:221], v[128:131], v[178:181]
	v_mfma_f32_16x16x32_bf16 v[40:43], v[222:225], v[132:135], v[12:15]
	v_mfma_f32_16x16x32_bf16 v[12:15], v[4:7], v[136:139], v[182:185]
	v_mfma_f32_16x16x32_bf16 v[28:31], v[8:11], v[140:143], v[12:15]
	v_mfma_f32_16x16x32_bf16 v[12:15], v[218:221], v[136:139], v[186:189]
	v_mfma_f32_16x16x32_bf16 v[4:7], v[4:7], v[242:245], v[16:19]
	v_mfma_f32_16x16x32_bf16 v[24:27], v[222:225], v[140:143], v[12:15]
	v_mfma_f32_16x16x32_bf16 v[12:15], v[8:11], v[246:249], v[4:7]
	v_mfma_f32_16x16x32_bf16 v[4:7], v[218:221], v[242:245], v[20:23]
	v_mfma_f32_16x16x32_bf16 v[8:11], v[222:225], v[246:249], v[4:7]
	v_mfma_f32_16x16x32_bf16 v[4:7], v[226:229], v[32:35], v[190:193]
	v_mfma_f32_16x16x32_bf16 v[52:55], v[230:233], v[36:39], v[4:7]
	v_mfma_f32_16x16x32_bf16 v[4:7], v[234:237], v[32:35], v[194:197]
	v_mfma_f32_16x16x32_bf16 v[48:51], v[238:241], v[36:39], v[4:7]
	v_mfma_f32_16x16x32_bf16 v[4:7], v[226:229], v[128:131], v[198:201]
	v_mfma_f32_16x16x32_bf16 v[36:39], v[230:233], v[132:135], v[4:7]
	v_mfma_f32_16x16x32_bf16 v[4:7], v[234:237], v[128:131], v[202:205]
	v_mfma_f32_16x16x32_bf16 v[32:35], v[238:241], v[132:135], v[4:7]
	v_mfma_f32_16x16x32_bf16 v[4:7], v[226:229], v[136:139], v[206:209]
	v_mfma_f32_16x16x32_bf16 v[20:23], v[230:233], v[140:143], v[4:7]
	v_mfma_f32_16x16x32_bf16 v[4:7], v[234:237], v[136:139], v[210:213]
	v_mfma_f32_16x16x32_bf16 v[0:3], v[226:229], v[242:245], v[0:3]
	v_mfma_f32_16x16x32_bf16 v[16:19], v[238:241], v[140:143], v[4:7]
	v_mfma_f32_16x16x32_bf16 v[4:7], v[230:233], v[246:249], v[0:3]
	v_mfma_f32_16x16x32_bf16 v[0:3], v[234:237], v[242:245], v[214:217]
	v_mfma_f32_16x16x32_bf16 v[0:3], v[238:241], v[246:249], v[0:3]
	s_barrier
	s_add_u32 s62, s56, 0x100
	s_addc_u32 s63, s57, 0
	s_add_u32 s91, s54, 0x200
	s_addc_u32 s92, s55, 0
	s_mov_b32 s93, 0
	.p2align	6

.LBB0_2480:
	s_ashr_i32 s47, s46, 31
	s_lshl_b64 s[20:21], s[46:47], 18
	s_add_u32 s50, s24, s20
	s_addc_u32 s51, s25, s21
	s_add_u32 s60, s56, 0x180
	s_addc_u32 s61, s57, 0
	s_waitcnt lgkmcnt(0)
	s_and_b64 s[20:21], s[58:59], exec
	s_cselect_b32 s5, s51, s55
	s_cselect_b32 s12, s50, s54
	s_add_u32 s58, s54, 0x180
	s_addc_u32 s59, s55, 0
	s_barrier
	s_waitcnt lgkmcnt(0)
	v_mfma_f32_16x16x32_bf16 v[128:131], v[16:19], v[120:123], 0
	v_mfma_f32_16x16x32_bf16 v[132:135], v[20:23], v[124:127], v[128:131]
	v_mfma_f32_16x16x32_bf16 v[128:131], v[24:27], v[120:123], 0
	v_mfma_f32_16x16x32_bf16 v[144:147], v[28:31], v[124:127], v[128:131]
	v_mfma_f32_16x16x32_bf16 v[128:131], v[16:19], v[112:115], 0
	v_mfma_f32_16x16x32_bf16 v[152:155], v[20:23], v[116:119], v[128:131]
	v_mfma_f32_16x16x32_bf16 v[128:131], v[24:27], v[112:115], 0
	v_mfma_f32_16x16x32_bf16 v[168:171], v[28:31], v[116:119], v[128:131]
	v_mfma_f32_16x16x32_bf16 v[128:131], v[16:19], v[96:99], 0
	v_mfma_f32_16x16x32_bf16 v[16:19], v[16:19], v[88:91], 0
	v_mfma_f32_16x16x32_bf16 v[172:175], v[20:23], v[108:111], v[128:131]
	v_mfma_f32_16x16x32_bf16 v[16:19], v[20:23], v[92:95], v[16:19]
	v_mfma_f32_16x16x32_bf16 v[20:23], v[24:27], v[88:91], 0
	v_mfma_f32_16x16x32_bf16 v[128:131], v[24:27], v[96:99], 0
	v_mfma_f32_16x16x32_bf16 v[20:23], v[28:31], v[92:95], v[20:23]
	v_mfma_f32_16x16x32_bf16 v[176:179], v[28:31], v[108:111], v[128:131]
	v_mfma_f32_16x16x32_bf16 v[24:27], v[0:3], v[120:123], 0
	v_mfma_f32_16x16x32_bf16 v[180:183], v[4:7], v[124:127], v[24:27]
	v_mfma_f32_16x16x32_bf16 v[24:27], v[8:11], v[120:123], 0
	v_mfma_f32_16x16x32_bf16 v[188:191], v[12:15], v[124:127], v[24:27]
	v_mfma_f32_16x16x32_bf16 v[24:27], v[0:3], v[112:115], 0
	v_mfma_f32_16x16x32_bf16 v[192:195], v[4:7], v[116:119], v[24:27]
	v_mfma_f32_16x16x32_bf16 v[24:27], v[8:11], v[112:115], 0
	v_mfma_f32_16x16x32_bf16 v[208:211], v[12:15], v[116:119], v[24:27]
	v_mfma_f32_16x16x32_bf16 v[24:27], v[0:3], v[96:99], 0
	v_mfma_f32_16x16x32_bf16 v[0:3], v[0:3], v[88:91], 0
	v_mfma_f32_16x16x32_bf16 v[212:215], v[4:7], v[108:111], v[24:27]
	v_mfma_f32_16x16x32_bf16 v[24:27], v[8:11], v[96:99], 0
	v_mfma_f32_16x16x32_bf16 v[0:3], v[4:7], v[92:95], v[0:3]
	v_mfma_f32_16x16x32_bf16 v[4:7], v[8:11], v[88:91], 0
	v_mfma_f32_16x16x32_bf16 v[216:219], v[12:15], v[108:111], v[24:27]
	v_mfma_f32_16x16x32_bf16 v[220:223], v[12:15], v[92:95], v[4:7]
	s_barrier
	v_add_u32_e32 v124, s78, v203
	v_add_u32_e32 v125, s83, v203
	s_nop 1
	ds_read_b128 v[4:7], v124
	ds_read_b128 v[8:11], v124 offset:1024
	ds_read_b128 v[224:227], v124 offset:2048
	ds_read_b128 v[228:231], v124 offset:3072
	ds_read_b128 v[232:235], v125
	ds_read_b128 v[236:239], v125 offset:1024
	ds_read_b128 v[240:243], v125 offset:2048
	ds_read_b128 v[244:247], v125 offset:3072
	s_add_u32 s20, s56, 0x70100
	s_addc_u32 s21, s57, 0
	s_mov_b32 m0, s70
	ds_read_b128 v[12:15], v206 offset:32768
	ds_read_b128 v[24:27], v206 offset:33792
	ds_read_b128 v[28:31], v206 offset:34816
	ds_read_b128 v[96:99], v206 offset:35840
	ds_read_b128 v[248:251], v206 offset:36864
	ds_read_b128 v[184:187], v206 offset:37888
	ds_read_b128 v[32:35], v206 offset:38912
	ds_read_b128 v[36:39], v206 offset:39936
	s_nop 0
	global_load_lds_dwordx4 v199, s[20:21]
	s_mov_b32 m0, s71
	s_nop 0
	global_load_lds_dwordx4 v201, s[20:21]
	s_waitcnt vmcnt(8)
	s_waitcnt lgkmcnt(0)
	s_barrier
	s_waitcnt lgkmcnt(0)
	v_mfma_f32_16x16x32_bf16 v[88:91], v[4:7], v[12:15], v[136:139]
	v_mfma_f32_16x16x32_bf16 v[40:43], v[4:7], v[28:31], v[40:43]
	v_mfma_f32_16x16x32_bf16 v[164:167], v[8:11], v[24:27], v[88:91]
	v_mfma_f32_16x16x32_bf16 v[88:91], v[224:227], v[12:15], v[140:143]
	v_mfma_f32_16x16x32_bf16 v[140:143], v[8:11], v[96:99], v[40:43]
	v_mfma_f32_16x16x32_bf16 v[40:43], v[224:227], v[28:31], v[44:47]
	v_mfma_f32_16x16x32_bf16 v[136:139], v[228:231], v[96:99], v[40:43]
	v_mfma_f32_16x16x32_bf16 v[40:43], v[4:7], v[248:251], v[48:51]
	v_mfma_f32_16x16x32_bf16 v[116:119], v[8:11], v[184:187], v[40:43]
	v_mfma_f32_16x16x32_bf16 v[40:43], v[224:227], v[248:251], v[52:55]
	v_mfma_f32_16x16x32_bf16 v[112:115], v[228:231], v[184:187], v[40:43]
	v_mfma_f32_16x16x32_bf16 v[40:43], v[4:7], v[32:35], v[56:59]
	v_mfma_f32_16x16x32_bf16 v[92:95], v[8:11], v[36:39], v[40:43]
	v_mfma_f32_16x16x32_bf16 v[40:43], v[224:227], v[32:35], v[60:63]
	v_mfma_f32_16x16x32_bf16 v[160:163], v[228:231], v[24:27], v[88:91]
	v_mfma_f32_16x16x32_bf16 v[88:91], v[228:231], v[36:39], v[40:43]
	v_mfma_f32_16x16x32_bf16 v[40:43], v[232:235], v[12:15], v[64:67]
	v_mfma_f32_16x16x32_bf16 v[12:15], v[240:243], v[12:15], v[68:71]
	v_mfma_f32_16x16x32_bf16 v[148:151], v[244:247], v[24:27], v[12:15]
	v_mfma_f32_16x16x32_bf16 v[12:15], v[232:235], v[28:31], v[72:75]
	v_mfma_f32_16x16x32_bf16 v[128:131], v[236:239], v[96:99], v[12:15]
	v_mfma_f32_16x16x32_bf16 v[12:15], v[240:243], v[28:31], v[76:79]
	v_mfma_f32_16x16x32_bf16 v[120:123], v[244:247], v[96:99], v[12:15]
	v_mfma_f32_16x16x32_bf16 v[12:15], v[232:235], v[248:251], v[80:83]
	v_mfma_f32_16x16x32_bf16 v[108:111], v[236:239], v[184:187], v[12:15]
	v_mfma_f32_16x16x32_bf16 v[12:15], v[240:243], v[248:251], v[84:87]
	v_mfma_f32_16x16x32_bf16 v[96:99], v[244:247], v[184:187], v[12:15]
	v_mfma_f32_16x16x32_bf16 v[12:15], v[232:235], v[32:35], v[100:103]
	v_mfma_f32_16x16x32_bf16 v[84:87], v[236:239], v[36:39], v[12:15]
	v_mfma_f32_16x16x32_bf16 v[12:15], v[240:243], v[32:35], v[104:107]
	v_mfma_f32_16x16x32_bf16 v[156:159], v[236:239], v[24:27], v[40:43]
	v_mfma_f32_16x16x32_bf16 v[72:75], v[244:247], v[36:39], v[12:15]
	s_barrier
	s_add_i32 s20, s78, s26
	s_mov_b32 m0, s20
	s_add_i32 s21, s20, 0x2000
	ds_read_b128 v[32:35], v206 offset:49152
	ds_read_b128 v[36:39], v206 offset:50176
	ds_read_b128 v[48:51], v206 offset:51200
	ds_read_b128 v[52:55], v206 offset:52224
	ds_read_b128 v[76:79], v206 offset:53248
	ds_read_b128 v[80:83], v206 offset:54272
	ds_read_b128 v[100:103], v206 offset:55296
	ds_read_b128 v[104:107], v206 offset:56320
	s_nop 0
	global_load_lds_dwordx4 v200, s[58:59]
	s_mov_b32 m0, s21
	s_nop 0
	global_load_lds_dwordx4 v202, s[58:59]
	s_add_u32 s58, s54, 0x20180
	s_addc_u32 s59, s55, 0
	s_add_i32 s45, s83, s26
	s_mov_b32 m0, s45
	s_add_i32 s47, s45, 0x2000
	s_nop 0
	global_load_lds_dwordx4 v200, s[58:59]
	s_mov_b32 m0, s47
	s_nop 0
	global_load_lds_dwordx4 v202, s[58:59]
	s_mov_b32 m0, s72
	s_nop 0
	global_load_lds_dwordx4 v199, s[60:61]
	s_mov_b32 m0, s73
	s_nop 0
	global_load_lds_dwordx4 v201, s[60:61]
	s_waitcnt vmcnt(8)
	s_waitcnt lgkmcnt(0)
	s_barrier
	s_waitcnt lgkmcnt(0)
	v_mfma_f32_16x16x32_bf16 v[12:15], v[4:7], v[32:35], v[132:135]
	v_mfma_f32_16x16x32_bf16 v[68:71], v[8:11], v[36:39], v[12:15]
	v_mfma_f32_16x16x32_bf16 v[12:15], v[224:227], v[32:35], v[144:147]
	v_mfma_f32_16x16x32_bf16 v[64:67], v[228:231], v[36:39], v[12:15]
	v_mfma_f32_16x16x32_bf16 v[12:15], v[4:7], v[48:51], v[152:155]
	v_mfma_f32_16x16x32_bf16 v[44:47], v[8:11], v[52:55], v[12:15]
	v_mfma_f32_16x16x32_bf16 v[12:15], v[224:227], v[48:51], v[168:171]
	v_mfma_f32_16x16x32_bf16 v[40:43], v[228:231], v[52:55], v[12:15]
	v_mfma_f32_16x16x32_bf16 v[12:15], v[4:7], v[76:79], v[172:175]
	v_mfma_f32_16x16x32_bf16 v[28:31], v[8:11], v[80:83], v[12:15]
	v_mfma_f32_16x16x32_bf16 v[12:15], v[224:227], v[76:79], v[176:179]
	v_mfma_f32_16x16x32_bf16 v[4:7], v[4:7], v[100:103], v[16:19]
	v_mfma_f32_16x16x32_bf16 v[24:27], v[228:231], v[80:83], v[12:15]
	v_mfma_f32_16x16x32_bf16 v[12:15], v[8:11], v[104:107], v[4:7]
	v_mfma_f32_16x16x32_bf16 v[4:7], v[224:227], v[100:103], v[20:23]
	v_mfma_f32_16x16x32_bf16 v[8:11], v[228:231], v[104:107], v[4:7]
	v_mfma_f32_16x16x32_bf16 v[4:7], v[232:235], v[32:35], v[180:183]
	v_mfma_f32_16x16x32_bf16 v[60:63], v[236:239], v[36:39], v[4:7]
	v_mfma_f32_16x16x32_bf16 v[4:7], v[240:243], v[32:35], v[188:191]
	v_mfma_f32_16x16x32_bf16 v[56:59], v[244:247], v[36:39], v[4:7]
	v_mfma_f32_16x16x32_bf16 v[4:7], v[232:235], v[48:51], v[192:195]
	v_mfma_f32_16x16x32_bf16 v[36:39], v[236:239], v[52:55], v[4:7]
	v_mfma_f32_16x16x32_bf16 v[4:7], v[240:243], v[48:51], v[208:211]
	v_mfma_f32_16x16x32_bf16 v[32:35], v[244:247], v[52:55], v[4:7]
	v_mfma_f32_16x16x32_bf16 v[4:7], v[232:235], v[76:79], v[212:215]
	v_mfma_f32_16x16x32_bf16 v[20:23], v[236:239], v[80:83], v[4:7]
	v_mfma_f32_16x16x32_bf16 v[4:7], v[240:243], v[76:79], v[216:219]
	v_mfma_f32_16x16x32_bf16 v[0:3], v[232:235], v[100:103], v[0:3]
	v_mfma_f32_16x16x32_bf16 v[16:19], v[244:247], v[80:83], v[4:7]
	v_mfma_f32_16x16x32_bf16 v[4:7], v[236:239], v[104:107], v[0:3]
	v_mfma_f32_16x16x32_bf16 v[0:3], v[240:243], v[100:103], v[220:223]
	v_mfma_f32_16x16x32_bf16 v[0:3], v[244:247], v[104:107], v[0:3]
	s_barrier
	s_add_u32 s62, s56, 0x100
	s_addc_u32 s63, s57, 0
	s_add_u32 s53, s54, 0x200
	s_addc_u32 s79, s55, 0
	s_mov_b32 s80, 0
	.p2align	6

.LBB0_2778:
	s_ashr_i32 s43, s42, 31
	s_lshl_b64 s[20:21], s[42:43], 20
	s_add_u32 s48, s13, s20
	s_addc_u32 s49, s82, s21
	s_and_b64 s[20:21], s[46:47], exec
	s_cselect_b32 s3, s49, s55
	s_cselect_b32 s5, s48, s54
	s_ashr_i32 s45, s44, 31
	s_lshl_b64 s[20:21], s[44:45], 20
	s_add_u32 s50, s24, s20
	s_addc_u32 s51, s25, s21
	s_and_b64 s[20:21], s[46:47], exec
	s_cselect_b32 s12, s51, s53
	s_cselect_b32 s20, s50, s52
	s_add_u32 s56, s54, 0x180
	s_waitcnt lgkmcnt(0)
	s_addc_u32 s57, s55, 0
	s_add_u32 s58, s52, 0x180
	s_addc_u32 s59, s53, 0
	s_barrier
	s_waitcnt lgkmcnt(0)
	v_mfma_f32_16x16x32_bf16 v[128:131], v[16:19], v[120:123], 0
	v_mfma_f32_16x16x32_bf16 v[134:137], v[20:23], v[124:127], v[128:131]
	v_mfma_f32_16x16x32_bf16 v[128:131], v[24:27], v[120:123], 0
	v_mfma_f32_16x16x32_bf16 v[156:159], v[28:31], v[124:127], v[128:131]
	v_mfma_f32_16x16x32_bf16 v[128:131], v[16:19], v[104:107], 0
	v_mfma_f32_16x16x32_bf16 v[160:163], v[20:23], v[116:119], v[128:131]
	v_mfma_f32_16x16x32_bf16 v[128:131], v[24:27], v[104:107], 0
	v_mfma_f32_16x16x32_bf16 v[164:167], v[28:31], v[116:119], v[128:131]
	v_mfma_f32_16x16x32_bf16 v[128:131], v[16:19], v[96:99], 0
	v_mfma_f32_16x16x32_bf16 v[16:19], v[16:19], v[76:79], 0
	v_mfma_f32_16x16x32_bf16 v[168:171], v[20:23], v[100:103], v[128:131]
	v_mfma_f32_16x16x32_bf16 v[16:19], v[20:23], v[80:83], v[16:19]
	v_mfma_f32_16x16x32_bf16 v[20:23], v[24:27], v[76:79], 0
	v_mfma_f32_16x16x32_bf16 v[128:131], v[24:27], v[96:99], 0
	v_mfma_f32_16x16x32_bf16 v[20:23], v[28:31], v[80:83], v[20:23]
	v_mfma_f32_16x16x32_bf16 v[172:175], v[28:31], v[100:103], v[128:131]
	v_mfma_f32_16x16x32_bf16 v[24:27], v[0:3], v[120:123], 0
	v_mfma_f32_16x16x32_bf16 v[176:179], v[4:7], v[124:127], v[24:27]
	v_mfma_f32_16x16x32_bf16 v[24:27], v[8:11], v[120:123], 0
	v_mfma_f32_16x16x32_bf16 v[180:183], v[12:15], v[124:127], v[24:27]
	v_mfma_f32_16x16x32_bf16 v[24:27], v[0:3], v[104:107], 0
	v_mfma_f32_16x16x32_bf16 v[186:189], v[4:7], v[116:119], v[24:27]
	v_mfma_f32_16x16x32_bf16 v[24:27], v[8:11], v[104:107], 0
	v_mfma_f32_16x16x32_bf16 v[190:193], v[12:15], v[116:119], v[24:27]
	v_mfma_f32_16x16x32_bf16 v[24:27], v[0:3], v[96:99], 0
	v_mfma_f32_16x16x32_bf16 v[0:3], v[0:3], v[76:79], 0
	v_mfma_f32_16x16x32_bf16 v[194:197], v[4:7], v[100:103], v[24:27]
	v_mfma_f32_16x16x32_bf16 v[24:27], v[8:11], v[96:99], 0
	v_mfma_f32_16x16x32_bf16 v[0:3], v[4:7], v[80:83], v[0:3]
	v_mfma_f32_16x16x32_bf16 v[4:7], v[8:11], v[76:79], 0
	v_mfma_f32_16x16x32_bf16 v[198:201], v[12:15], v[100:103], v[24:27]
	v_mfma_f32_16x16x32_bf16 v[212:215], v[12:15], v[80:83], v[4:7]
	s_barrier
	v_add_u32_e32 v132, s74, v206
	v_add_u32_e32 v133, s75, v206
	s_nop 1
	ds_read_b128 v[4:7], v132
	ds_read_b128 v[8:11], v132 offset:1024
	ds_read_b128 v[216:219], v132 offset:2048
	ds_read_b128 v[220:223], v132 offset:3072
	ds_read_b128 v[224:227], v133
	ds_read_b128 v[228:231], v133 offset:1024
	ds_read_b128 v[232:235], v133 offset:2048
	ds_read_b128 v[236:239], v133 offset:3072
	s_add_u32 s78, s54, 0x80100
	s_addc_u32 s79, s55, 0
	s_mov_b32 m0, s65
	ds_read_b128 v[12:15], v209 offset:32768
	ds_read_b128 v[24:27], v209 offset:33792
	ds_read_b128 v[28:31], v209 offset:34816
	ds_read_b128 v[96:99], v209 offset:35840
	ds_read_b128 v[240:243], v209 offset:36864
	ds_read_b128 v[244:247], v209 offset:37888
	ds_read_b128 v[248:251], v209 offset:38912
	ds_read_b128 v[32:35], v209 offset:39936
	s_nop 0
	global_load_lds_dwordx4 v202, s[78:79]
	s_mov_b32 m0, s66
	s_nop 0
	global_load_lds_dwordx4 v204, s[78:79]
	s_waitcnt vmcnt(8)
	s_waitcnt lgkmcnt(0)
	s_barrier
	s_waitcnt lgkmcnt(0)
	v_mfma_f32_16x16x32_bf16 v[36:39], v[216:219], v[12:15], v[36:39]
	v_mfma_f32_16x16x32_bf16 v[148:151], v[220:223], v[24:27], v[36:39]
	v_mfma_f32_16x16x32_bf16 v[36:39], v[4:7], v[28:31], v[40:43]
	v_mfma_f32_16x16x32_bf16 v[128:131], v[8:11], v[96:99], v[36:39]
	v_mfma_f32_16x16x32_bf16 v[36:39], v[216:219], v[28:31], v[44:47]
	v_mfma_f32_16x16x32_bf16 v[124:127], v[220:223], v[96:99], v[36:39]
	v_mfma_f32_16x16x32_bf16 v[36:39], v[4:7], v[240:243], v[48:51]
	v_mfma_f32_16x16x32_bf16 v[104:107], v[8:11], v[244:247], v[36:39]
	v_mfma_f32_16x16x32_bf16 v[36:39], v[216:219], v[240:243], v[52:55]
	v_mfma_f32_16x16x32_bf16 v[100:103], v[220:223], v[244:247], v[36:39]
	v_mfma_f32_16x16x32_bf16 v[36:39], v[4:7], v[248:251], v[56:59]
	v_mfma_f32_16x16x32_bf16 v[76:79], v[4:7], v[12:15], v[138:141]
	v_mfma_f32_16x16x32_bf16 v[80:83], v[8:11], v[32:35], v[36:39]
	v_mfma_f32_16x16x32_bf16 v[36:39], v[216:219], v[248:251], v[60:63]
	v_mfma_f32_16x16x32_bf16 v[152:155], v[8:11], v[24:27], v[76:79]
	v_mfma_f32_16x16x32_bf16 v[76:79], v[220:223], v[32:35], v[36:39]
	v_mfma_f32_16x16x32_bf16 v[36:39], v[224:227], v[12:15], v[64:67]
	v_mfma_f32_16x16x32_bf16 v[12:15], v[232:235], v[12:15], v[68:71]
	v_mfma_f32_16x16x32_bf16 v[140:143], v[236:239], v[24:27], v[12:15]
	v_mfma_f32_16x16x32_bf16 v[12:15], v[224:227], v[28:31], v[72:75]
	v_mfma_f32_16x16x32_bf16 v[120:123], v[228:231], v[96:99], v[12:15]
	v_mfma_f32_16x16x32_bf16 v[12:15], v[232:235], v[28:31], v[84:87]
	v_mfma_f32_16x16x32_bf16 v[116:119], v[236:239], v[96:99], v[12:15]
	v_mfma_f32_16x16x32_bf16 v[12:15], v[224:227], v[240:243], v[88:91]
	v_mfma_f32_16x16x32_bf16 v[96:99], v[228:231], v[244:247], v[12:15]
	v_mfma_f32_16x16x32_bf16 v[12:15], v[232:235], v[240:243], v[92:95]
	v_mfma_f32_16x16x32_bf16 v[92:95], v[236:239], v[244:247], v[12:15]
	v_mfma_f32_16x16x32_bf16 v[12:15], v[224:227], v[248:251], v[108:111]
	v_mfma_f32_16x16x32_bf16 v[72:75], v[228:231], v[32:35], v[12:15]
	v_mfma_f32_16x16x32_bf16 v[12:15], v[232:235], v[248:251], v[112:115]
	v_mfma_f32_16x16x32_bf16 v[144:147], v[228:231], v[24:27], v[36:39]
	v_mfma_f32_16x16x32_bf16 v[68:71], v[236:239], v[32:35], v[12:15]
	s_barrier
	s_add_i32 s21, s74, s26
	s_mov_b32 m0, s21
	s_add_i32 s43, s21, 0x2000
	ds_read_b128 v[32:35], v209 offset:49152
	ds_read_b128 v[36:39], v209 offset:50176
	ds_read_b128 v[60:63], v209 offset:51200
	ds_read_b128 v[84:87], v209 offset:52224
	ds_read_b128 v[88:91], v209 offset:53248
	ds_read_b128 v[108:111], v209 offset:54272
	ds_read_b128 v[112:115], v209 offset:55296
	ds_read_b128 v[240:243], v209 offset:56320
	s_nop 0
	global_load_lds_dwordx4 v203, s[58:59]
	s_mov_b32 m0, s43
	s_nop 0
	global_load_lds_dwordx4 v205, s[58:59]
	s_add_u32 s58, s52, 0x80180
	s_addc_u32 s59, s53, 0
	s_add_i32 s45, s75, s26
	s_mov_b32 m0, s45
	s_add_i32 s78, s45, 0x2000
	s_nop 0
	global_load_lds_dwordx4 v203, s[58:59]
	s_mov_b32 m0, s78
	s_nop 0
	global_load_lds_dwordx4 v205, s[58:59]
	s_mov_b32 m0, s67
	s_nop 0
	global_load_lds_dwordx4 v202, s[56:57]
	s_mov_b32 m0, s68
	s_nop 0
	global_load_lds_dwordx4 v204, s[56:57]
	s_waitcnt vmcnt(8)
	s_waitcnt lgkmcnt(0)
	s_barrier
	s_waitcnt lgkmcnt(0)
	v_mfma_f32_16x16x32_bf16 v[12:15], v[4:7], v[32:35], v[134:137]
	v_mfma_f32_16x16x32_bf16 v[64:67], v[8:11], v[36:39], v[12:15]
	v_mfma_f32_16x16x32_bf16 v[12:15], v[216:219], v[32:35], v[156:159]
	v_mfma_f32_16x16x32_bf16 v[56:59], v[220:223], v[36:39], v[12:15]
	v_mfma_f32_16x16x32_bf16 v[12:15], v[4:7], v[60:63], v[160:163]
	v_mfma_f32_16x16x32_bf16 v[44:47], v[8:11], v[84:87], v[12:15]
	v_mfma_f32_16x16x32_bf16 v[12:15], v[216:219], v[60:63], v[164:167]
	v_mfma_f32_16x16x32_bf16 v[40:43], v[220:223], v[84:87], v[12:15]
	v_mfma_f32_16x16x32_bf16 v[12:15], v[4:7], v[88:91], v[168:171]
	v_mfma_f32_16x16x32_bf16 v[28:31], v[8:11], v[108:111], v[12:15]
	v_mfma_f32_16x16x32_bf16 v[12:15], v[216:219], v[88:91], v[172:175]
	v_mfma_f32_16x16x32_bf16 v[4:7], v[4:7], v[112:115], v[16:19]
	v_mfma_f32_16x16x32_bf16 v[24:27], v[220:223], v[108:111], v[12:15]
	v_mfma_f32_16x16x32_bf16 v[12:15], v[8:11], v[240:243], v[4:7]
	v_mfma_f32_16x16x32_bf16 v[4:7], v[216:219], v[112:115], v[20:23]
	v_mfma_f32_16x16x32_bf16 v[8:11], v[220:223], v[240:243], v[4:7]
	v_mfma_f32_16x16x32_bf16 v[4:7], v[224:227], v[32:35], v[176:179]
	v_mfma_f32_16x16x32_bf16 v[52:55], v[228:231], v[36:39], v[4:7]
	v_mfma_f32_16x16x32_bf16 v[4:7], v[232:235], v[32:35], v[180:183]
	v_mfma_f32_16x16x32_bf16 v[48:51], v[236:239], v[36:39], v[4:7]
	v_mfma_f32_16x16x32_bf16 v[4:7], v[224:227], v[60:63], v[186:189]
	v_mfma_f32_16x16x32_bf16 v[36:39], v[228:231], v[84:87], v[4:7]
	v_mfma_f32_16x16x32_bf16 v[4:7], v[232:235], v[60:63], v[190:193]
	v_mfma_f32_16x16x32_bf16 v[32:35], v[236:239], v[84:87], v[4:7]
	v_mfma_f32_16x16x32_bf16 v[4:7], v[224:227], v[88:91], v[194:197]
	v_mfma_f32_16x16x32_bf16 v[20:23], v[228:231], v[108:111], v[4:7]
	v_mfma_f32_16x16x32_bf16 v[4:7], v[232:235], v[88:91], v[198:201]
	v_mfma_f32_16x16x32_bf16 v[0:3], v[224:227], v[112:115], v[0:3]
	v_mfma_f32_16x16x32_bf16 v[16:19], v[236:239], v[108:111], v[4:7]
	v_mfma_f32_16x16x32_bf16 v[4:7], v[228:231], v[240:243], v[0:3]
	v_mfma_f32_16x16x32_bf16 v[0:3], v[232:235], v[112:115], v[212:215]
	v_mfma_f32_16x16x32_bf16 v[0:3], v[236:239], v[240:243], v[0:3]
	s_barrier
	s_add_u32 s79, s54, 0x200
	s_addc_u32 s80, s55, 0
	s_add_u32 s81, s52, 0x200
	s_addc_u32 s83, s53, 0
	s_add_u32 s52, s54, 0x80180
	s_addc_u32 s53, s55, 0
	s_mov_b32 s84, 0
	.p2align	6

.LBB0_2888:
	s_ashr_i32 s7, s6, 31
	s_lshl_b64 s[20:21], s[6:7], 20
	s_add_u32 s36, s14, s20
	s_addc_u32 s37, s15, s21
	s_ashr_i32 s9, s8, 31
	s_lshl_b64 s[20:21], s[8:9], 20
	s_add_u32 s38, s17, s20
	s_addc_u32 s39, s24, s21
	s_add_u32 s48, s46, 0x180
	s_addc_u32 s49, s47, 0
	s_waitcnt lgkmcnt(0)
	s_and_b64 s[20:21], s[34:35], exec
	s_cselect_b32 s9, s39, s45
	s_cselect_b32 s12, s38, s44
	s_cselect_b32 s20, s37, s47
	s_cselect_b32 s21, s36, s46
	s_add_u32 s50, s44, 0x180
	s_addc_u32 s51, s45, 0
	s_barrier
	s_waitcnt lgkmcnt(0)
	v_mfma_f32_16x16x32_bf16 v[116:119], v[16:19], v[108:111], 0
	v_mfma_f32_16x16x32_bf16 v[154:157], v[20:23], v[112:115], v[116:119]
	v_mfma_f32_16x16x32_bf16 v[116:119], v[24:27], v[108:111], 0
	v_mfma_f32_16x16x32_bf16 v[158:161], v[28:31], v[112:115], v[116:119]
	v_mfma_f32_16x16x32_bf16 v[116:119], v[16:19], v[100:103], 0
	v_mfma_f32_16x16x32_bf16 v[162:165], v[20:23], v[104:107], v[116:119]
	v_mfma_f32_16x16x32_bf16 v[116:119], v[24:27], v[100:103], 0
	v_mfma_f32_16x16x32_bf16 v[166:169], v[28:31], v[104:107], v[116:119]
	v_mfma_f32_16x16x32_bf16 v[116:119], v[16:19], v[88:91], 0
	v_mfma_f32_16x16x32_bf16 v[16:19], v[16:19], v[68:71], 0
	v_mfma_f32_16x16x32_bf16 v[170:173], v[20:23], v[96:99], v[116:119]
	v_mfma_f32_16x16x32_bf16 v[116:119], v[24:27], v[88:91], 0
	v_mfma_f32_16x16x32_bf16 v[20:23], v[20:23], v[80:83], v[16:19]
	v_mfma_f32_16x16x32_bf16 v[16:19], v[24:27], v[68:71], 0
	v_mfma_f32_16x16x32_bf16 v[174:177], v[28:31], v[96:99], v[116:119]
	v_mfma_f32_16x16x32_bf16 v[28:31], v[28:31], v[80:83], v[16:19]
	v_mfma_f32_16x16x32_bf16 v[16:19], v[0:3], v[108:111], 0
	v_mfma_f32_16x16x32_bf16 v[178:181], v[4:7], v[112:115], v[16:19]
	v_mfma_f32_16x16x32_bf16 v[16:19], v[8:11], v[108:111], 0
	v_mfma_f32_16x16x32_bf16 v[182:185], v[12:15], v[112:115], v[16:19]
	v_mfma_f32_16x16x32_bf16 v[16:19], v[0:3], v[100:103], 0
	v_mfma_f32_16x16x32_bf16 v[186:189], v[4:7], v[104:107], v[16:19]
	v_mfma_f32_16x16x32_bf16 v[16:19], v[8:11], v[100:103], 0
	v_mfma_f32_16x16x32_bf16 v[190:193], v[12:15], v[104:107], v[16:19]
	v_mfma_f32_16x16x32_bf16 v[16:19], v[0:3], v[88:91], 0
	v_mfma_f32_16x16x32_bf16 v[0:3], v[0:3], v[68:71], 0
	v_mfma_f32_16x16x32_bf16 v[194:197], v[4:7], v[96:99], v[16:19]
	v_mfma_f32_16x16x32_bf16 v[16:19], v[8:11], v[88:91], 0
	v_mfma_f32_16x16x32_bf16 v[4:7], v[4:7], v[80:83], v[0:3]
	v_mfma_f32_16x16x32_bf16 v[0:3], v[8:11], v[68:71], 0
	v_mfma_f32_16x16x32_bf16 v[198:201], v[12:15], v[96:99], v[16:19]
	v_mfma_f32_16x16x32_bf16 v[202:205], v[12:15], v[80:83], v[0:3]
	s_barrier
	v_add_u32_e32 v152, s66, v147
	v_add_u32_e32 v153, s67, v147
	s_nop 1
	ds_read_b128 v[0:3], v152
	ds_read_b128 v[8:11], v152 offset:1024
	ds_read_b128 v[12:15], v152 offset:2048
	ds_read_b128 v[206:209], v152 offset:3072
	ds_read_b128 v[210:213], v153
	ds_read_b128 v[214:217], v153 offset:1024
	ds_read_b128 v[218:221], v153 offset:2048
	ds_read_b128 v[222:225], v153 offset:3072
	s_add_u32 s52, s46, 0x80100
	s_addc_u32 s53, s47, 0
	s_mov_b32 m0, s57
	ds_read_b128 v[16:19], v150 offset:32768
	ds_read_b128 v[24:27], v150 offset:33792
	ds_read_b128 v[100:103], v150 offset:34816
	ds_read_b128 v[226:229], v150 offset:35840
	ds_read_b128 v[230:233], v150 offset:36864
	ds_read_b128 v[234:237], v150 offset:37888
	ds_read_b128 v[238:241], v150 offset:38912
	ds_read_b128 v[242:245], v150 offset:39936
	s_nop 0
	global_load_lds_dwordx4 v143, s[52:53]
	s_mov_b32 m0, s58
	s_nop 0
	global_load_lds_dwordx4 v145, s[52:53]
	s_waitcnt vmcnt(8)
	s_waitcnt lgkmcnt(0)
	s_barrier
	s_waitcnt lgkmcnt(0)
	v_mfma_f32_16x16x32_bf16 v[32:35], v[0:3], v[16:19], v[32:35]
	v_mfma_f32_16x16x32_bf16 v[120:123], v[8:11], v[24:27], v[32:35]
	v_mfma_f32_16x16x32_bf16 v[32:35], v[12:15], v[16:19], v[36:39]
	v_mfma_f32_16x16x32_bf16 v[112:115], v[206:209], v[24:27], v[32:35]
	v_mfma_f32_16x16x32_bf16 v[32:35], v[0:3], v[100:103], v[40:43]
	v_mfma_f32_16x16x32_bf16 v[104:107], v[8:11], v[226:229], v[32:35]
	v_mfma_f32_16x16x32_bf16 v[32:35], v[12:15], v[100:103], v[44:47]
	v_mfma_f32_16x16x32_bf16 v[96:99], v[206:209], v[226:229], v[32:35]
	v_mfma_f32_16x16x32_bf16 v[32:35], v[0:3], v[230:233], v[48:51]
	v_mfma_f32_16x16x32_bf16 v[88:91], v[8:11], v[234:237], v[32:35]
	v_mfma_f32_16x16x32_bf16 v[32:35], v[12:15], v[230:233], v[52:55]
	v_mfma_f32_16x16x32_bf16 v[80:83], v[206:209], v[234:237], v[32:35]
	v_mfma_f32_16x16x32_bf16 v[32:35], v[0:3], v[238:241], v[56:59]
	v_mfma_f32_16x16x32_bf16 v[68:71], v[8:11], v[242:245], v[32:35]
	v_mfma_f32_16x16x32_bf16 v[32:35], v[12:15], v[238:241], v[60:63]
	v_mfma_f32_16x16x32_bf16 v[52:55], v[206:209], v[242:245], v[32:35]
	v_mfma_f32_16x16x32_bf16 v[32:35], v[210:213], v[16:19], v[64:67]
	v_mfma_f32_16x16x32_bf16 v[16:19], v[218:221], v[16:19], v[72:75]
	v_mfma_f32_16x16x32_bf16 v[116:119], v[222:225], v[24:27], v[16:19]
	v_mfma_f32_16x16x32_bf16 v[16:19], v[210:213], v[100:103], v[76:79]
	v_mfma_f32_16x16x32_bf16 v[108:111], v[214:217], v[226:229], v[16:19]
	v_mfma_f32_16x16x32_bf16 v[16:19], v[218:221], v[100:103], v[84:87]
	v_mfma_f32_16x16x32_bf16 v[100:103], v[222:225], v[226:229], v[16:19]
	v_mfma_f32_16x16x32_bf16 v[16:19], v[210:213], v[230:233], v[92:95]
	v_mfma_f32_16x16x32_bf16 v[92:95], v[214:217], v[234:237], v[16:19]
	v_mfma_f32_16x16x32_bf16 v[16:19], v[218:221], v[230:233], v[128:131]
	v_mfma_f32_16x16x32_bf16 v[84:87], v[222:225], v[234:237], v[16:19]
	v_mfma_f32_16x16x32_bf16 v[16:19], v[210:213], v[238:241], v[132:135]
	v_mfma_f32_16x16x32_bf16 v[76:79], v[214:217], v[242:245], v[16:19]
	v_mfma_f32_16x16x32_bf16 v[16:19], v[218:221], v[238:241], v[136:139]
	v_mfma_f32_16x16x32_bf16 v[124:127], v[214:217], v[24:27], v[32:35]
	v_mfma_f32_16x16x32_bf16 v[60:63], v[222:225], v[242:245], v[16:19]
	s_barrier
	s_add_i32 s71, s66, s25
	s_mov_b32 m0, s71
	s_add_i32 s72, s71, 0x2000
	ds_read_b128 v[36:39], v150 offset:49152
	ds_read_b128 v[44:47], v150 offset:50176
	ds_read_b128 v[128:131], v150 offset:51200
	ds_read_b128 v[132:135], v150 offset:52224
	ds_read_b128 v[136:139], v150 offset:53248
	ds_read_b128 v[226:229], v150 offset:54272
	ds_read_b128 v[230:233], v150 offset:55296
	ds_read_b128 v[234:237], v150 offset:56320
	s_nop 0
	global_load_lds_dwordx4 v144, s[50:51]
	s_mov_b32 m0, s72
	s_nop 0
	global_load_lds_dwordx4 v146, s[50:51]
	s_add_u32 s50, s44, 0x80180
	s_addc_u32 s51, s45, 0
	s_add_i32 s73, s67, s25
	s_mov_b32 m0, s73
	s_add_i32 s74, s73, 0x2000
	s_nop 0
	global_load_lds_dwordx4 v144, s[50:51]
	s_mov_b32 m0, s74
	s_nop 0
	global_load_lds_dwordx4 v146, s[50:51]
	s_mov_b32 m0, s59
	s_nop 0
	global_load_lds_dwordx4 v143, s[48:49]
	s_mov_b32 m0, s60
	s_nop 0
	global_load_lds_dwordx4 v145, s[48:49]
	s_waitcnt vmcnt(8)
	s_waitcnt lgkmcnt(0)
	s_barrier
	s_waitcnt lgkmcnt(0)
	v_mfma_f32_16x16x32_bf16 v[16:19], v[0:3], v[36:39], v[154:157]
	v_mfma_f32_16x16x32_bf16 v[64:67], v[8:11], v[44:47], v[16:19]
	v_mfma_f32_16x16x32_bf16 v[16:19], v[12:15], v[36:39], v[158:161]
	v_mfma_f32_16x16x32_bf16 v[48:51], v[206:209], v[44:47], v[16:19]
	v_mfma_f32_16x16x32_bf16 v[16:19], v[0:3], v[128:131], v[162:165]
	v_mfma_f32_16x16x32_bf16 v[40:43], v[8:11], v[132:135], v[16:19]
	v_mfma_f32_16x16x32_bf16 v[16:19], v[12:15], v[128:131], v[166:169]
	v_mfma_f32_16x16x32_bf16 v[32:35], v[206:209], v[132:135], v[16:19]
	v_mfma_f32_16x16x32_bf16 v[16:19], v[0:3], v[136:139], v[170:173]
	v_mfma_f32_16x16x32_bf16 v[0:3], v[0:3], v[230:233], v[20:23]
	v_mfma_f32_16x16x32_bf16 v[24:27], v[8:11], v[226:229], v[16:19]
	v_mfma_f32_16x16x32_bf16 v[16:19], v[12:15], v[136:139], v[174:177]
	v_mfma_f32_16x16x32_bf16 v[8:11], v[8:11], v[234:237], v[0:3]
	v_mfma_f32_16x16x32_bf16 v[0:3], v[12:15], v[230:233], v[28:31]
	v_mfma_f32_16x16x32_bf16 v[16:19], v[206:209], v[226:229], v[16:19]
	v_mfma_f32_16x16x32_bf16 v[0:3], v[206:209], v[234:237], v[0:3]
	v_mfma_f32_16x16x32_bf16 v[12:15], v[210:213], v[36:39], v[178:181]
	v_mfma_f32_16x16x32_bf16 v[72:75], v[214:217], v[44:47], v[12:15]
	v_mfma_f32_16x16x32_bf16 v[12:15], v[218:221], v[36:39], v[182:185]
	v_mfma_f32_16x16x32_bf16 v[56:59], v[222:225], v[44:47], v[12:15]
	v_mfma_f32_16x16x32_bf16 v[12:15], v[210:213], v[128:131], v[186:189]
	v_mfma_f32_16x16x32_bf16 v[44:47], v[214:217], v[132:135], v[12:15]
	v_mfma_f32_16x16x32_bf16 v[12:15], v[218:221], v[128:131], v[190:193]
	v_mfma_f32_16x16x32_bf16 v[36:39], v[222:225], v[132:135], v[12:15]
	v_mfma_f32_16x16x32_bf16 v[12:15], v[210:213], v[136:139], v[194:197]
	v_mfma_f32_16x16x32_bf16 v[28:31], v[214:217], v[226:229], v[12:15]
	v_mfma_f32_16x16x32_bf16 v[12:15], v[218:221], v[136:139], v[198:201]
	v_mfma_f32_16x16x32_bf16 v[4:7], v[210:213], v[230:233], v[4:7]
	v_mfma_f32_16x16x32_bf16 v[20:23], v[222:225], v[226:229], v[12:15]
	v_mfma_f32_16x16x32_bf16 v[12:15], v[214:217], v[234:237], v[4:7]
	v_mfma_f32_16x16x32_bf16 v[4:7], v[218:221], v[230:233], v[202:205]
	v_mfma_f32_16x16x32_bf16 v[4:7], v[222:225], v[234:237], v[4:7]
	s_barrier
	s_add_u32 s52, s46, 0x100
	s_addc_u32 s53, s47, 0
	s_add_u32 s75, s44, 0x200
	s_addc_u32 s76, s45, 0
	s_mov_b32 s77, 0
	.p2align	6

.LBB0_2986:
	s_add_u32 s50, s48, 0x180
	s_waitcnt lgkmcnt(0)
	s_addc_u32 s51, s49, 0
	s_add_u32 s52, s4, 0x180
	s_addc_u32 s53, s5, 0
	s_barrier
	s_waitcnt lgkmcnt(0)
	v_mfma_f32_16x16x32_bf16 v[128:131], v[16:19], v[120:123], 0
	v_mfma_f32_16x16x32_bf16 v[134:137], v[20:23], v[124:127], v[128:131]
	v_mfma_f32_16x16x32_bf16 v[128:131], v[24:27], v[120:123], 0
	v_mfma_f32_16x16x32_bf16 v[156:159], v[28:31], v[124:127], v[128:131]
	v_mfma_f32_16x16x32_bf16 v[128:131], v[16:19], v[104:107], 0
	v_mfma_f32_16x16x32_bf16 v[160:163], v[20:23], v[116:119], v[128:131]
	v_mfma_f32_16x16x32_bf16 v[128:131], v[24:27], v[104:107], 0
	v_mfma_f32_16x16x32_bf16 v[164:167], v[28:31], v[116:119], v[128:131]
	v_mfma_f32_16x16x32_bf16 v[128:131], v[16:19], v[96:99], 0
	v_mfma_f32_16x16x32_bf16 v[16:19], v[16:19], v[76:79], 0
	v_mfma_f32_16x16x32_bf16 v[168:171], v[20:23], v[100:103], v[128:131]
	v_mfma_f32_16x16x32_bf16 v[16:19], v[20:23], v[80:83], v[16:19]
	v_mfma_f32_16x16x32_bf16 v[20:23], v[24:27], v[76:79], 0
	v_mfma_f32_16x16x32_bf16 v[128:131], v[24:27], v[96:99], 0
	v_mfma_f32_16x16x32_bf16 v[20:23], v[28:31], v[80:83], v[20:23]
	v_mfma_f32_16x16x32_bf16 v[172:175], v[28:31], v[100:103], v[128:131]
	v_mfma_f32_16x16x32_bf16 v[24:27], v[0:3], v[120:123], 0
	v_mfma_f32_16x16x32_bf16 v[176:179], v[4:7], v[124:127], v[24:27]
	v_mfma_f32_16x16x32_bf16 v[24:27], v[8:11], v[120:123], 0
	v_mfma_f32_16x16x32_bf16 v[180:183], v[12:15], v[124:127], v[24:27]
	v_mfma_f32_16x16x32_bf16 v[24:27], v[0:3], v[104:107], 0
	v_mfma_f32_16x16x32_bf16 v[186:189], v[4:7], v[116:119], v[24:27]
	v_mfma_f32_16x16x32_bf16 v[24:27], v[8:11], v[104:107], 0
	v_mfma_f32_16x16x32_bf16 v[190:193], v[12:15], v[116:119], v[24:27]
	v_mfma_f32_16x16x32_bf16 v[24:27], v[0:3], v[96:99], 0
	v_mfma_f32_16x16x32_bf16 v[0:3], v[0:3], v[76:79], 0
	v_mfma_f32_16x16x32_bf16 v[194:197], v[4:7], v[100:103], v[24:27]
	v_mfma_f32_16x16x32_bf16 v[24:27], v[8:11], v[96:99], 0
	v_mfma_f32_16x16x32_bf16 v[0:3], v[4:7], v[80:83], v[0:3]
	v_mfma_f32_16x16x32_bf16 v[4:7], v[8:11], v[76:79], 0
	v_mfma_f32_16x16x32_bf16 v[198:201], v[12:15], v[100:103], v[24:27]
	v_mfma_f32_16x16x32_bf16 v[212:215], v[12:15], v[80:83], v[4:7]
	s_barrier
	v_add_u32_e32 v132, s67, v206
	v_add_u32_e32 v133, s68, v206
	s_nop 1
	ds_read_b128 v[4:7], v132
	ds_read_b128 v[8:11], v132 offset:1024
	ds_read_b128 v[216:219], v132 offset:2048
	ds_read_b128 v[220:223], v132 offset:3072
	ds_read_b128 v[224:227], v133
	ds_read_b128 v[228:231], v133 offset:1024
	ds_read_b128 v[232:235], v133 offset:2048
	ds_read_b128 v[236:239], v133 offset:3072
	s_add_u32 s20, s48, 0x160100
	s_addc_u32 s21, s49, 0
	s_mov_b32 m0, s58
	ds_read_b128 v[12:15], v209 offset:32768
	ds_read_b128 v[24:27], v209 offset:33792
	ds_read_b128 v[28:31], v209 offset:34816
	ds_read_b128 v[96:99], v209 offset:35840
	ds_read_b128 v[240:243], v209 offset:36864
	ds_read_b128 v[244:247], v209 offset:37888
	ds_read_b128 v[248:251], v209 offset:38912
	ds_read_b128 v[32:35], v209 offset:39936
	s_nop 0
	global_load_lds_dwordx4 v202, s[20:21]
	s_mov_b32 m0, s59
	s_nop 0
	global_load_lds_dwordx4 v204, s[20:21]
	s_waitcnt vmcnt(8)
	s_waitcnt lgkmcnt(0)
	s_barrier
	s_waitcnt lgkmcnt(0)
	v_mfma_f32_16x16x32_bf16 v[36:39], v[216:219], v[12:15], v[36:39]
	v_mfma_f32_16x16x32_bf16 v[148:151], v[220:223], v[24:27], v[36:39]
	v_mfma_f32_16x16x32_bf16 v[36:39], v[4:7], v[28:31], v[40:43]
	v_mfma_f32_16x16x32_bf16 v[128:131], v[8:11], v[96:99], v[36:39]
	v_mfma_f32_16x16x32_bf16 v[36:39], v[216:219], v[28:31], v[44:47]
	v_mfma_f32_16x16x32_bf16 v[124:127], v[220:223], v[96:99], v[36:39]
	v_mfma_f32_16x16x32_bf16 v[36:39], v[4:7], v[240:243], v[48:51]
	v_mfma_f32_16x16x32_bf16 v[104:107], v[8:11], v[244:247], v[36:39]
	v_mfma_f32_16x16x32_bf16 v[36:39], v[216:219], v[240:243], v[52:55]
	v_mfma_f32_16x16x32_bf16 v[100:103], v[220:223], v[244:247], v[36:39]
	v_mfma_f32_16x16x32_bf16 v[36:39], v[4:7], v[248:251], v[56:59]
	v_mfma_f32_16x16x32_bf16 v[76:79], v[4:7], v[12:15], v[138:141]
	v_mfma_f32_16x16x32_bf16 v[80:83], v[8:11], v[32:35], v[36:39]
	v_mfma_f32_16x16x32_bf16 v[36:39], v[216:219], v[248:251], v[60:63]
	v_mfma_f32_16x16x32_bf16 v[152:155], v[8:11], v[24:27], v[76:79]
	v_mfma_f32_16x16x32_bf16 v[76:79], v[220:223], v[32:35], v[36:39]
	v_mfma_f32_16x16x32_bf16 v[36:39], v[224:227], v[12:15], v[64:67]
	v_mfma_f32_16x16x32_bf16 v[12:15], v[232:235], v[12:15], v[68:71]
	v_mfma_f32_16x16x32_bf16 v[140:143], v[236:239], v[24:27], v[12:15]
	v_mfma_f32_16x16x32_bf16 v[12:15], v[224:227], v[28:31], v[72:75]
	v_mfma_f32_16x16x32_bf16 v[120:123], v[228:231], v[96:99], v[12:15]
	v_mfma_f32_16x16x32_bf16 v[12:15], v[232:235], v[28:31], v[84:87]
	v_mfma_f32_16x16x32_bf16 v[116:119], v[236:239], v[96:99], v[12:15]
	v_mfma_f32_16x16x32_bf16 v[12:15], v[224:227], v[240:243], v[88:91]
	v_mfma_f32_16x16x32_bf16 v[96:99], v[228:231], v[244:247], v[12:15]
	v_mfma_f32_16x16x32_bf16 v[12:15], v[232:235], v[240:243], v[92:95]
	v_mfma_f32_16x16x32_bf16 v[92:95], v[236:239], v[244:247], v[12:15]
	v_mfma_f32_16x16x32_bf16 v[12:15], v[224:227], v[248:251], v[108:111]
	v_mfma_f32_16x16x32_bf16 v[72:75], v[228:231], v[32:35], v[12:15]
	v_mfma_f32_16x16x32_bf16 v[12:15], v[232:235], v[248:251], v[112:115]
	v_mfma_f32_16x16x32_bf16 v[144:147], v[228:231], v[24:27], v[36:39]
	v_mfma_f32_16x16x32_bf16 v[68:71], v[236:239], v[32:35], v[12:15]
	s_barrier
	s_add_i32 s12, s67, s25
	s_mov_b32 m0, s12
	s_add_i32 s20, s12, 0x2000
	ds_read_b128 v[32:35], v209 offset:49152
	ds_read_b128 v[36:39], v209 offset:50176
	ds_read_b128 v[60:63], v209 offset:51200
	ds_read_b128 v[84:87], v209 offset:52224
	ds_read_b128 v[88:91], v209 offset:53248
	ds_read_b128 v[108:111], v209 offset:54272
	ds_read_b128 v[112:115], v209 offset:55296
	ds_read_b128 v[240:243], v209 offset:56320
	s_nop 0
	global_load_lds_dwordx4 v203, s[52:53]
	s_mov_b32 m0, s20
	s_nop 0
	global_load_lds_dwordx4 v205, s[52:53]
	s_add_u32 s52, s4, 0x160180
	s_addc_u32 s53, s5, 0
	s_add_i32 s21, s68, s25
	s_mov_b32 m0, s21
	s_add_i32 s72, s21, 0x2000
	s_nop 0
	global_load_lds_dwordx4 v203, s[52:53]
	s_mov_b32 m0, s72
	s_nop 0
	global_load_lds_dwordx4 v205, s[52:53]
	s_mov_b32 m0, s60
	s_nop 0
	global_load_lds_dwordx4 v202, s[50:51]
	s_mov_b32 m0, s61
	s_nop 0
	global_load_lds_dwordx4 v204, s[50:51]
	s_waitcnt vmcnt(8)
	s_waitcnt lgkmcnt(0)
	s_barrier
	s_waitcnt lgkmcnt(0)
	v_mfma_f32_16x16x32_bf16 v[12:15], v[4:7], v[32:35], v[134:137]
	v_mfma_f32_16x16x32_bf16 v[64:67], v[8:11], v[36:39], v[12:15]
	v_mfma_f32_16x16x32_bf16 v[12:15], v[216:219], v[32:35], v[156:159]
	v_mfma_f32_16x16x32_bf16 v[56:59], v[220:223], v[36:39], v[12:15]
	v_mfma_f32_16x16x32_bf16 v[12:15], v[4:7], v[60:63], v[160:163]
	v_mfma_f32_16x16x32_bf16 v[44:47], v[8:11], v[84:87], v[12:15]
	v_mfma_f32_16x16x32_bf16 v[12:15], v[216:219], v[60:63], v[164:167]
	v_mfma_f32_16x16x32_bf16 v[40:43], v[220:223], v[84:87], v[12:15]
	v_mfma_f32_16x16x32_bf16 v[12:15], v[4:7], v[88:91], v[168:171]
	v_mfma_f32_16x16x32_bf16 v[28:31], v[8:11], v[108:111], v[12:15]
	v_mfma_f32_16x16x32_bf16 v[12:15], v[216:219], v[88:91], v[172:175]
	v_mfma_f32_16x16x32_bf16 v[4:7], v[4:7], v[112:115], v[16:19]
	v_mfma_f32_16x16x32_bf16 v[24:27], v[220:223], v[108:111], v[12:15]
	v_mfma_f32_16x16x32_bf16 v[12:15], v[8:11], v[240:243], v[4:7]
	v_mfma_f32_16x16x32_bf16 v[4:7], v[216:219], v[112:115], v[20:23]
	v_mfma_f32_16x16x32_bf16 v[8:11], v[220:223], v[240:243], v[4:7]
	v_mfma_f32_16x16x32_bf16 v[4:7], v[224:227], v[32:35], v[176:179]
	v_mfma_f32_16x16x32_bf16 v[52:55], v[228:231], v[36:39], v[4:7]
	v_mfma_f32_16x16x32_bf16 v[4:7], v[232:235], v[32:35], v[180:183]
	v_mfma_f32_16x16x32_bf16 v[48:51], v[236:239], v[36:39], v[4:7]
	v_mfma_f32_16x16x32_bf16 v[4:7], v[224:227], v[60:63], v[186:189]
	v_mfma_f32_16x16x32_bf16 v[36:39], v[228:231], v[84:87], v[4:7]
	v_mfma_f32_16x16x32_bf16 v[4:7], v[232:235], v[60:63], v[190:193]
	v_mfma_f32_16x16x32_bf16 v[32:35], v[236:239], v[84:87], v[4:7]
	v_mfma_f32_16x16x32_bf16 v[4:7], v[224:227], v[88:91], v[194:197]
	v_mfma_f32_16x16x32_bf16 v[20:23], v[228:231], v[108:111], v[4:7]
	v_mfma_f32_16x16x32_bf16 v[4:7], v[232:235], v[88:91], v[198:201]
	v_mfma_f32_16x16x32_bf16 v[0:3], v[224:227], v[112:115], v[0:3]
	v_mfma_f32_16x16x32_bf16 v[16:19], v[236:239], v[108:111], v[4:7]
	v_mfma_f32_16x16x32_bf16 v[4:7], v[228:231], v[240:243], v[0:3]
	v_mfma_f32_16x16x32_bf16 v[0:3], v[232:235], v[112:115], v[212:215]
	v_mfma_f32_16x16x32_bf16 v[0:3], v[236:239], v[240:243], v[0:3]
	s_barrier
	s_add_u32 s73, s48, 0x200
	s_addc_u32 s74, s49, 0
	s_add_u32 s75, s4, 0x200
	s_addc_u32 s76, s5, 0
	s_add_u32 s4, s48, 0x160180
	s_addc_u32 s5, s49, 0
	s_mov_b32 s77, 0
	.p2align	6
